# GEMM K-loops: 8 of 16 LDS-DMA loads per iteration use the SGPR-base + 32-bit lane-offset form (their 64-bit VALU address adds deleted)
# speedup vs baseline: 1.0045x; 1.0045x over previous
; #define PG8_STAGE(bufoff, gbase, voff) do { _Pragma("unroll") for (int _i = 0; _i < 2; ++_i) \
;         __builtin_amdgcn_global_load_lds((const unsigned*)((const char*)(gbase) + (voff)[_i]), (PG8_LAS unsigned*)(lds + (bufoff) + ldsw + _i * 8192), 16, 0, 0); } while (0)
; #define PG8_LDA(dst, b, h) do { _Pragma("unroll") for (int m = 0; m < 4; ++m) _Pragma("unroll") for (int k = 0; k < 2; ++k) dst[m][k] = *(const PG8_LAS bf16x8*)(lds + PG8_SA(b, h) + aoff + m * 2048 + k * 1024); } while (0)
; #define PG8_LDB(dst, b, h) do { _Pragma("unroll") for (int n = 0; n < 2; ++n) _Pragma("unroll") for (int k = 0; k < 2; ++k) dst[n][k] = *(const PG8_LAS bf16x8*)(lds + PG8_SB(b, h) + boff + n * 2048 + k * 1024); } while (0)
; #define PG8_MMA(ai, bj, At, Bt) do { __builtin_amdgcn_s_setprio(1); _Pragma("unroll") for (int m = 0; m < 4; ++m) _Pragma("unroll") for (int n = 0; n < 2; ++n) _Pragma("unroll") for (int k = 0; k < 2; ++k) \
;         acc[ai][bj][m][n] = __builtin_amdgcn_mfma_f32_16x16x32_bf16(Bt[n][k], At[m][k], acc[ai][bj][m][n], 0, 0, 0); __builtin_amdgcn_s_setprio(0); } while (0)
; #define PG8_WAIT_V(n) asm volatile("s_waitcnt vmcnt(" #n ")" ::: "memory")
; #define PG8_WAIT_L(n) asm volatile("s_waitcnt lgkmcnt(" #n ")" ::: "memory")
; template <class Epi, class Sched, bool ALIGN_EPI = false, bool SP2 = false>
; __device__ __forceinline__ void gemm_phase(PG8_LAS unsigned char* lds, const Gemm g, const Sched& S, const Epi& E, int tid_in) {
;     ...
;             const bool last = (t == nt - 2);
;             const char* a1 = cA + (size_t)(t + 1) * kstep;
;             const char* a2 = last ? nA : cA + (size_t)(t + 2) * kstep; const char* b2 = last ? nB : cB + (size_t)(t + 2) * kstep;
;             const char* a3 = a2 + kstep; const char* b3 = b2 + kstep;
;             if (last && has_next) S.a_ready(nxt);
;             if constexpr (SP2) {
;             PG8_LDB(B0, 0, 0); PG8_LDB(B1, 0, 1); PG8_SCHED; PG8_LDA(At, 0, 0); PG8_STAGE(PG8_SA(1, 1), a1 + hstepA, voffA);
;             PG8_WAIT_V(8); PG8_WAIT_L(0); PG8_BAR; PG8_MMA(0, 0, At, B0); PG8_MMA(0, 1, At, B1); PG8_BAR; PG8_SCHED;
;             PG8_LDA(At, 0, 1); PG8_STAGE(PG8_SB(0, 0), b2, voffB); PG8_STAGE(PG8_SB(0, 1), b2 + hstep, voffB); PG8_STAGE(PG8_SA(0, 0), a2, voffA);
;             PG8_WAIT_V(8); PG8_WAIT_L(0); PG8_BAR; PG8_MMA(1, 0, At, B0); PG8_MMA(1, 1, At, B1); PG8_BAR; PG8_SCHED;
.LBB0_204:
	s_add_u32 s10, s2, 0xfffc0080
	s_addc_u32 s11, s3, -1
	s_add_i32 s28, 0, 0x10000
	s_cmp_eq_u32 s27, 12
	s_cselect_b32 s13, s15, s11
	s_cselect_b32 s12, s20, s10
	v_add_u32_e32 v156, s28, v159
	s_cselect_b32 s11, s21, s26
	s_cselect_b32 s10, s24, s25
	s_add_i32 s52, 0, 0x14000
	ds_read_b128 v[144:147], v156
	ds_read_b128 v[148:151], v156 offset:1024
	ds_read_b128 v[152:155], v156 offset:2048
	ds_read_b128 v[162:165], v156 offset:3072
	v_add_u32_e32 v156, s52, v159
	ds_read_b128 v[166:169], v156
	ds_read_b128 v[170:173], v156 offset:1024
	ds_read_b128 v[174:177], v156 offset:2048
	ds_read_b128 v[178:181], v156 offset:3072
	s_add_i32 m0, s35, 0xc000
	ds_read_b128 v[182:185], v160
	ds_read_b128 v[186:189], v160 offset:1024
	ds_read_b128 v[200:203], v160 offset:2048
	ds_read_b128 v[204:207], v160 offset:3072
	ds_read_b128 v[208:211], v160 offset:4096
	ds_read_b128 v[212:215], v160 offset:5120
	ds_read_b128 v[216:219], v160 offset:6144
	ds_read_b128 v[226:229], v160 offset:7168
	global_load_lds_dwordx4 v142, s[2:3]
	s_add_i32 m0, s35, 0xe000
	s_nop 0
	global_load_lds_dwordx4 v140, s[2:3]
	s_waitcnt vmcnt(8)
	s_waitcnt lgkmcnt(0)
	s_barrier
	s_setprio 1
	s_waitcnt lgkmcnt(0)
	v_mfma_f32_16x16x32_bf16 v[124:127], v[144:147], v[182:185], v[124:127]
	v_mfma_f32_16x16x32_bf16 v[120:123], v[152:155], v[182:185], v[120:123]
	v_mfma_f32_16x16x32_bf16 v[108:111], v[144:147], v[200:203], v[108:111]
	v_mfma_f32_16x16x32_bf16 v[104:107], v[152:155], v[200:203], v[104:107]
	v_mfma_f32_16x16x32_bf16 v[92:95], v[144:147], v[208:211], v[92:95]
	v_mfma_f32_16x16x32_bf16 v[88:91], v[152:155], v[208:211], v[88:91]
	v_mfma_f32_16x16x32_bf16 v[76:79], v[144:147], v[216:219], v[76:79]
	v_mfma_f32_16x16x32_bf16 v[72:75], v[152:155], v[216:219], v[72:75]
	v_mfma_f32_16x16x32_bf16 v[124:127], v[148:151], v[186:189], v[124:127]
	v_mfma_f32_16x16x32_bf16 v[120:123], v[162:165], v[186:189], v[120:123]
	v_mfma_f32_16x16x32_bf16 v[108:111], v[148:151], v[204:207], v[108:111]
	v_mfma_f32_16x16x32_bf16 v[104:107], v[162:165], v[204:207], v[104:107]
	v_mfma_f32_16x16x32_bf16 v[92:95], v[148:151], v[212:215], v[92:95]
	v_mfma_f32_16x16x32_bf16 v[88:91], v[162:165], v[212:215], v[88:91]
	v_mfma_f32_16x16x32_bf16 v[76:79], v[148:151], v[226:229], v[76:79]
	v_mfma_f32_16x16x32_bf16 v[72:75], v[162:165], v[226:229], v[72:75]
	s_setprio 0
	s_setprio 1
	v_mfma_f32_16x16x32_bf16 v[116:119], v[166:169], v[182:185], v[116:119]
	v_mfma_f32_16x16x32_bf16 v[112:115], v[174:177], v[182:185], v[112:115]
	v_mfma_f32_16x16x32_bf16 v[100:103], v[166:169], v[200:203], v[100:103]
	v_mfma_f32_16x16x32_bf16 v[96:99], v[174:177], v[200:203], v[96:99]
	v_mfma_f32_16x16x32_bf16 v[84:87], v[166:169], v[208:211], v[84:87]
	v_mfma_f32_16x16x32_bf16 v[80:83], v[174:177], v[208:211], v[80:83]
	v_mfma_f32_16x16x32_bf16 v[68:71], v[166:169], v[216:219], v[68:71]
	v_mfma_f32_16x16x32_bf16 v[64:67], v[174:177], v[216:219], v[64:67]
	v_mfma_f32_16x16x32_bf16 v[116:119], v[170:173], v[186:189], v[116:119]
	v_mfma_f32_16x16x32_bf16 v[112:115], v[178:181], v[186:189], v[112:115]
	v_mfma_f32_16x16x32_bf16 v[100:103], v[170:173], v[204:207], v[100:103]
	v_mfma_f32_16x16x32_bf16 v[96:99], v[178:181], v[204:207], v[96:99]
	v_mfma_f32_16x16x32_bf16 v[84:87], v[170:173], v[212:215], v[84:87]
	v_mfma_f32_16x16x32_bf16 v[80:83], v[178:181], v[212:215], v[80:83]
	v_mfma_f32_16x16x32_bf16 v[68:71], v[170:173], v[226:229], v[68:71]
	v_mfma_f32_16x16x32_bf16 v[64:67], v[178:181], v[226:229], v[64:67]
	s_setprio 0
	s_barrier
	s_add_i32 s28, s28, s34
	v_lshl_add_u64 v[156:157], s[10:11], 0, v[132:133]
	s_mov_b32 m0, s28
	ds_read_b128 v[182:185], v160 offset:16384
	ds_read_b128 v[186:189], v160 offset:17408
	ds_read_b128 v[200:203], v160 offset:18432
	ds_read_b128 v[204:207], v160 offset:19456
	ds_read_b128 v[208:211], v160 offset:20480
	ds_read_b128 v[212:215], v160 offset:21504
	ds_read_b128 v[216:219], v160 offset:22528
	ds_read_b128 v[226:229], v160 offset:23552
	global_load_lds_dwordx4 v[156:157], off
	s_add_i32 m0, s28, 0x2000
	s_add_u32 s28, s10, 0x40000
	v_lshl_add_u64 v[230:231], s[10:11], 0, v[128:129]
	s_addc_u32 s29, s11, 0
	s_add_i32 s52, s52, s34
	global_load_lds_dwordx4 v[230:231], off
	s_mov_b32 m0, s52
	v_lshl_add_u64 v[234:235], s[12:13], 0, v[130:131]
	global_load_lds_dwordx4 v132, s[28:29]
	s_add_i32 m0, s52, 0x2000
	s_nop 0
	global_load_lds_dwordx4 v128, s[28:29]
	v_lshl_add_u64 v[232:233], s[12:13], 0, v[134:135]
	s_mov_b32 m0, s35
	s_nop 0
	global_load_lds_dwordx4 v[232:233], off
	s_mov_b32 m0, s38
	s_nop 0
	global_load_lds_dwordx4 v[234:235], off
	s_waitcnt vmcnt(8)
	s_waitcnt lgkmcnt(0)
	s_barrier
; #define PG8_STAGE(bufoff, gbase, voff) do { _Pragma("unroll") for (int _i = 0; _i < 2; ++_i) \
;         __builtin_amdgcn_global_load_lds((const unsigned*)((const char*)(gbase) + (voff)[_i]), (PG8_LAS unsigned*)(lds + (bufoff) + ldsw + _i * 8192), 16, 0, 0); } while (0)
; #define PG8_LDA(dst, b, h) do { _Pragma("unroll") for (int m = 0; m < 4; ++m) _Pragma("unroll") for (int k = 0; k < 2; ++k) dst[m][k] = *(const PG8_LAS bf16x8*)(lds + PG8_SA(b, h) + aoff + m * 2048 + k * 1024); } while (0)
; #define PG8_LDB(dst, b, h) do { _Pragma("unroll") for (int n = 0; n < 2; ++n) _Pragma("unroll") for (int k = 0; k < 2; ++k) dst[n][k] = *(const PG8_LAS bf16x8*)(lds + PG8_SB(b, h) + boff + n * 2048 + k * 1024); } while (0)
; #define PG8_MMA(ai, bj, At, Bt) do { __builtin_amdgcn_s_setprio(1); _Pragma("unroll") for (int m = 0; m < 4; ++m) _Pragma("unroll") for (int n = 0; n < 2; ++n) _Pragma("unroll") for (int k = 0; k < 2; ++k) \
;         acc[ai][bj][m][n] = __builtin_amdgcn_mfma_f32_16x16x32_bf16(Bt[n][k], At[m][k], acc[ai][bj][m][n], 0, 0, 0); __builtin_amdgcn_s_setprio(0); } while (0)
; #define PG8_WAIT_V(n) asm volatile("s_waitcnt vmcnt(" #n ")" ::: "memory")
; #define PG8_WAIT_L(n) asm volatile("s_waitcnt lgkmcnt(" #n ")" ::: "memory")
; #define PG8_BAR __builtin_amdgcn_s_barrier()
; #define PG8_SCHED __builtin_amdgcn_sched_barrier(0)
; template <class Epi, class Sched, bool ALIGN_EPI = false, bool SP2 = false>
; __device__ __forceinline__ void gemm_phase(PG8_LAS unsigned char* lds, const Gemm g, const Sched& S, const Epi& E, int tid_in) {
;     ...
;             PG8_WAIT_V(8); PG8_WAIT_L(0); PG8_BAR; PG8_MMA(1, 0, At, B0); PG8_MMA(1, 1, At, B1); PG8_BAR; PG8_SCHED;
;             PG8_LDB(B0, 1, 0); PG8_LDB(B1, 1, 1); PG8_SCHED; PG8_LDA(At, 1, 0); PG8_STAGE(PG8_SA(0, 1), a2 + hstepA, voffA);
;             PG8_WAIT_V(8); PG8_WAIT_L(0); PG8_BAR; PG8_MMA(0, 0, At, B0); PG8_MMA(0, 1, At, B1); PG8_BAR; PG8_SCHED;
	s_setprio 1
	s_waitcnt lgkmcnt(0)
	v_mfma_f32_16x16x32_bf16 v[60:63], v[144:147], v[182:185], v[60:63]
	v_mfma_f32_16x16x32_bf16 v[56:59], v[152:155], v[182:185], v[56:59]
	v_mfma_f32_16x16x32_bf16 v[44:47], v[144:147], v[200:203], v[44:47]
	v_mfma_f32_16x16x32_bf16 v[40:43], v[152:155], v[200:203], v[40:43]
	v_mfma_f32_16x16x32_bf16 v[28:31], v[144:147], v[208:211], v[28:31]
	v_mfma_f32_16x16x32_bf16 v[24:27], v[152:155], v[208:211], v[24:27]
	v_mfma_f32_16x16x32_bf16 v[12:15], v[144:147], v[216:219], v[12:15]
	v_mfma_f32_16x16x32_bf16 v[8:11], v[152:155], v[216:219], v[8:11]
	v_mfma_f32_16x16x32_bf16 v[60:63], v[148:151], v[186:189], v[60:63]
	v_mfma_f32_16x16x32_bf16 v[56:59], v[162:165], v[186:189], v[56:59]
	v_mfma_f32_16x16x32_bf16 v[44:47], v[148:151], v[204:207], v[44:47]
	v_mfma_f32_16x16x32_bf16 v[40:43], v[162:165], v[204:207], v[40:43]
	v_mfma_f32_16x16x32_bf16 v[28:31], v[148:151], v[212:215], v[28:31]
	v_mfma_f32_16x16x32_bf16 v[24:27], v[162:165], v[212:215], v[24:27]
	v_mfma_f32_16x16x32_bf16 v[12:15], v[148:151], v[226:229], v[12:15]
	v_mfma_f32_16x16x32_bf16 v[8:11], v[162:165], v[226:229], v[8:11]
	s_setprio 0
	s_setprio 1
	v_mfma_f32_16x16x32_bf16 v[52:55], v[166:169], v[182:185], v[52:55]
	v_mfma_f32_16x16x32_bf16 v[48:51], v[174:177], v[182:185], v[48:51]
	v_mfma_f32_16x16x32_bf16 v[36:39], v[166:169], v[200:203], v[36:39]
	v_mfma_f32_16x16x32_bf16 v[32:35], v[174:177], v[200:203], v[32:35]
	v_mfma_f32_16x16x32_bf16 v[20:23], v[166:169], v[208:211], v[20:23]
	v_mfma_f32_16x16x32_bf16 v[16:19], v[174:177], v[208:211], v[16:19]
	v_mfma_f32_16x16x32_bf16 v[4:7], v[166:169], v[216:219], v[4:7]
	v_mfma_f32_16x16x32_bf16 v[0:3], v[174:177], v[216:219], v[0:3]
	v_mfma_f32_16x16x32_bf16 v[52:55], v[170:173], v[186:189], v[52:55]
	v_mfma_f32_16x16x32_bf16 v[48:51], v[178:181], v[186:189], v[48:51]
	v_mfma_f32_16x16x32_bf16 v[36:39], v[170:173], v[204:207], v[36:39]
	v_mfma_f32_16x16x32_bf16 v[32:35], v[178:181], v[204:207], v[32:35]
	v_mfma_f32_16x16x32_bf16 v[20:23], v[170:173], v[212:215], v[20:23]
	v_mfma_f32_16x16x32_bf16 v[16:19], v[178:181], v[212:215], v[16:19]
	v_mfma_f32_16x16x32_bf16 v[4:7], v[170:173], v[226:229], v[4:7]
	v_mfma_f32_16x16x32_bf16 v[0:3], v[178:181], v[226:229], v[0:3]
	s_setprio 0
	s_barrier
	s_add_i32 s28, 0, 0x18000
	v_add_u32_e32 v161, s28, v159
	s_add_i32 s29, 0, 0x1c000
	ds_read_b128 v[144:147], v161
	ds_read_b128 v[148:151], v161 offset:1024
	ds_read_b128 v[152:155], v161 offset:2048
	ds_read_b128 v[162:165], v161 offset:3072
	v_add_u32_e32 v161, s29, v159
	ds_read_b128 v[166:169], v161
	ds_read_b128 v[170:173], v161 offset:1024
	ds_read_b128 v[174:177], v161 offset:2048
	ds_read_b128 v[178:181], v161 offset:3072
	s_add_u32 s12, s12, 0x40000
	s_addc_u32 s13, s13, 0
	s_mov_b32 m0, s77
	ds_read_b128 v[182:185], v160 offset:32768
	ds_read_b128 v[186:189], v160 offset:33792
	ds_read_b128 v[200:203], v160 offset:34816
	ds_read_b128 v[204:207], v160 offset:35840
	ds_read_b128 v[208:211], v160 offset:36864
	ds_read_b128 v[212:215], v160 offset:37888
	ds_read_b128 v[216:219], v160 offset:38912
	ds_read_b128 v[226:229], v160 offset:39936
	global_load_lds_dwordx4 v134, s[12:13]
	s_mov_b32 m0, s78
	s_nop 0
	global_load_lds_dwordx4 v130, s[12:13]
	s_waitcnt vmcnt(8)
	s_waitcnt lgkmcnt(0)
	s_barrier
	s_setprio 1
	s_waitcnt lgkmcnt(0)
	v_mfma_f32_16x16x32_bf16 v[124:127], v[144:147], v[182:185], v[124:127]
	v_mfma_f32_16x16x32_bf16 v[120:123], v[152:155], v[182:185], v[120:123]
	v_mfma_f32_16x16x32_bf16 v[108:111], v[144:147], v[200:203], v[108:111]
	v_mfma_f32_16x16x32_bf16 v[104:107], v[152:155], v[200:203], v[104:107]
	v_mfma_f32_16x16x32_bf16 v[92:95], v[144:147], v[208:211], v[92:95]
	v_mfma_f32_16x16x32_bf16 v[88:91], v[152:155], v[208:211], v[88:91]
	v_mfma_f32_16x16x32_bf16 v[76:79], v[144:147], v[216:219], v[76:79]
	v_mfma_f32_16x16x32_bf16 v[72:75], v[152:155], v[216:219], v[72:75]
	v_mfma_f32_16x16x32_bf16 v[124:127], v[148:151], v[186:189], v[124:127]
	v_mfma_f32_16x16x32_bf16 v[120:123], v[162:165], v[186:189], v[120:123]
	v_mfma_f32_16x16x32_bf16 v[108:111], v[148:151], v[204:207], v[108:111]
	v_mfma_f32_16x16x32_bf16 v[104:107], v[162:165], v[204:207], v[104:107]
	v_mfma_f32_16x16x32_bf16 v[92:95], v[148:151], v[212:215], v[92:95]
	v_mfma_f32_16x16x32_bf16 v[88:91], v[162:165], v[212:215], v[88:91]
	v_mfma_f32_16x16x32_bf16 v[76:79], v[148:151], v[226:229], v[76:79]
	v_mfma_f32_16x16x32_bf16 v[72:75], v[162:165], v[226:229], v[72:75]
	s_setprio 0
	s_setprio 1
	v_mfma_f32_16x16x32_bf16 v[116:119], v[166:169], v[182:185], v[116:119]
	v_mfma_f32_16x16x32_bf16 v[112:115], v[174:177], v[182:185], v[112:115]
	v_mfma_f32_16x16x32_bf16 v[100:103], v[166:169], v[200:203], v[100:103]
	v_mfma_f32_16x16x32_bf16 v[96:99], v[174:177], v[200:203], v[96:99]
	v_mfma_f32_16x16x32_bf16 v[84:87], v[166:169], v[208:211], v[84:87]
	v_mfma_f32_16x16x32_bf16 v[80:83], v[174:177], v[208:211], v[80:83]
	v_mfma_f32_16x16x32_bf16 v[68:71], v[166:169], v[216:219], v[68:71]
	v_mfma_f32_16x16x32_bf16 v[64:67], v[174:177], v[216:219], v[64:67]
	v_mfma_f32_16x16x32_bf16 v[116:119], v[170:173], v[186:189], v[116:119]
	v_mfma_f32_16x16x32_bf16 v[112:115], v[178:181], v[186:189], v[112:115]
	v_mfma_f32_16x16x32_bf16 v[100:103], v[170:173], v[204:207], v[100:103]
	v_mfma_f32_16x16x32_bf16 v[96:99], v[178:181], v[204:207], v[96:99]
	v_mfma_f32_16x16x32_bf16 v[84:87], v[170:173], v[212:215], v[84:87]
	v_mfma_f32_16x16x32_bf16 v[80:83], v[178:181], v[212:215], v[80:83]
	v_mfma_f32_16x16x32_bf16 v[68:71], v[170:173], v[226:229], v[68:71]
	v_mfma_f32_16x16x32_bf16 v[64:67], v[178:181], v[226:229], v[64:67]
	s_setprio 0
	s_barrier
; #define PG8_STAGE(bufoff, gbase, voff) do { _Pragma("unroll") for (int _i = 0; _i < 2; ++_i) \
;         __builtin_amdgcn_global_load_lds((const unsigned*)((const char*)(gbase) + (voff)[_i]), (PG8_LAS unsigned*)(lds + (bufoff) + ldsw + _i * 8192), 16, 0, 0); } while (0)
; #define PG8_LDA(dst, b, h) do { _Pragma("unroll") for (int m = 0; m < 4; ++m) _Pragma("unroll") for (int k = 0; k < 2; ++k) dst[m][k] = *(const PG8_LAS bf16x8*)(lds + PG8_SA(b, h) + aoff + m * 2048 + k * 1024); } while (0)
; #define PG8_MMA(ai, bj, At, Bt) do { __builtin_amdgcn_s_setprio(1); _Pragma("unroll") for (int m = 0; m < 4; ++m) _Pragma("unroll") for (int n = 0; n < 2; ++n) _Pragma("unroll") for (int k = 0; k < 2; ++k) \
;         acc[ai][bj][m][n] = __builtin_amdgcn_mfma_f32_16x16x32_bf16(Bt[n][k], At[m][k], acc[ai][bj][m][n], 0, 0, 0); __builtin_amdgcn_s_setprio(0); } while (0)
; #define PG8_WAIT_V(n) asm volatile("s_waitcnt vmcnt(" #n ")" ::: "memory")
; #define PG8_WAIT_L(n) asm volatile("s_waitcnt lgkmcnt(" #n ")" ::: "memory")
; #define PG8_BAR __builtin_amdgcn_s_barrier()
; #define PG8_SCHED __builtin_amdgcn_sched_barrier(0)
; template <class Epi, class Sched, bool ALIGN_EPI = false, bool SP2 = false>
; __device__ __forceinline__ void gemm_phase(PG8_LAS unsigned char* lds, const Gemm g, const Sched& S, const Epi& E, int tid_in) {
;     ...
;             PG8_LDA(At, 1, 1); PG8_STAGE(PG8_SB(1, 0), b3, voffB); PG8_STAGE(PG8_SB(1, 1), b3 + hstep, voffB); PG8_STAGE(PG8_SA(1, 0), a3, voffA);
;             PG8_WAIT_V(8); PG8_WAIT_L(0); PG8_BAR; PG8_MMA(1, 0, At, B0); PG8_MMA(1, 1, At, B1); PG8_BAR; PG8_SCHED;
;     ...
;         if constexpr (ALIGN_EPI) { if (wr == 0) PG8_BAR; }
	s_add_i32 s12, s28, s34
	v_lshl_add_u64 v[156:157], v[156:157], 0, s[0:1]
	s_mov_b32 m0, s12
	ds_read_b128 v[182:185], v160 offset:49152
	ds_read_b128 v[186:189], v160 offset:50176
	ds_read_b128 v[200:203], v160 offset:51200
	ds_read_b128 v[204:207], v160 offset:52224
	ds_read_b128 v[208:211], v160 offset:53248
	ds_read_b128 v[212:215], v160 offset:54272
	ds_read_b128 v[216:219], v160 offset:55296
	ds_read_b128 v[226:229], v160 offset:56320
	global_load_lds_dwordx4 v[156:157], off
	s_add_i32 m0, s12, 0x2000
	s_add_u32 s10, s10, 0x40080
	v_lshl_add_u64 v[156:157], v[230:231], 0, s[0:1]
	s_addc_u32 s11, s11, 0
	s_add_i32 s12, s29, s34
	global_load_lds_dwordx4 v[156:157], off
	s_mov_b32 m0, s12
	s_nop 0
	global_load_lds_dwordx4 v132, s[10:11]
	s_add_i32 m0, s12, 0x2000
	s_nop 0
	global_load_lds_dwordx4 v128, s[10:11]
	v_lshl_add_u64 v[156:157], v[232:233], 0, s[0:1]
	s_mov_b32 m0, s83
	s_nop 0
	global_load_lds_dwordx4 v[156:157], off
	v_lshl_add_u64 v[156:157], v[234:235], 0, s[0:1]
	s_mov_b32 m0, s84
	s_nop 0
	global_load_lds_dwordx4 v[156:157], off
	s_waitcnt vmcnt(8)
	s_waitcnt lgkmcnt(0)
	s_barrier
	s_setprio 1
	s_waitcnt lgkmcnt(0)
	v_mfma_f32_16x16x32_bf16 v[60:63], v[144:147], v[182:185], v[60:63]
	v_mfma_f32_16x16x32_bf16 v[56:59], v[152:155], v[182:185], v[56:59]
	v_mfma_f32_16x16x32_bf16 v[44:47], v[144:147], v[200:203], v[44:47]
	v_mfma_f32_16x16x32_bf16 v[40:43], v[152:155], v[200:203], v[40:43]
	v_mfma_f32_16x16x32_bf16 v[28:31], v[144:147], v[208:211], v[28:31]
	v_mfma_f32_16x16x32_bf16 v[24:27], v[152:155], v[208:211], v[24:27]
	v_mfma_f32_16x16x32_bf16 v[12:15], v[144:147], v[216:219], v[12:15]
	v_mfma_f32_16x16x32_bf16 v[8:11], v[152:155], v[216:219], v[8:11]
	v_mfma_f32_16x16x32_bf16 v[60:63], v[148:151], v[186:189], v[60:63]
	v_mfma_f32_16x16x32_bf16 v[56:59], v[162:165], v[186:189], v[56:59]
	v_mfma_f32_16x16x32_bf16 v[44:47], v[148:151], v[204:207], v[44:47]
	v_mfma_f32_16x16x32_bf16 v[40:43], v[162:165], v[204:207], v[40:43]
	v_mfma_f32_16x16x32_bf16 v[28:31], v[148:151], v[212:215], v[28:31]
	v_mfma_f32_16x16x32_bf16 v[24:27], v[162:165], v[212:215], v[24:27]
	v_mfma_f32_16x16x32_bf16 v[12:15], v[148:151], v[226:229], v[12:15]
	v_mfma_f32_16x16x32_bf16 v[8:11], v[162:165], v[226:229], v[8:11]
	s_setprio 0
	s_setprio 1
	v_mfma_f32_16x16x32_bf16 v[52:55], v[166:169], v[182:185], v[52:55]
	v_mfma_f32_16x16x32_bf16 v[48:51], v[174:177], v[182:185], v[48:51]
	v_mfma_f32_16x16x32_bf16 v[36:39], v[166:169], v[200:203], v[36:39]
	v_mfma_f32_16x16x32_bf16 v[32:35], v[174:177], v[200:203], v[32:35]
	v_mfma_f32_16x16x32_bf16 v[20:23], v[166:169], v[208:211], v[20:23]
	v_mfma_f32_16x16x32_bf16 v[16:19], v[174:177], v[208:211], v[16:19]
	v_mfma_f32_16x16x32_bf16 v[4:7], v[166:169], v[216:219], v[4:7]
	v_mfma_f32_16x16x32_bf16 v[0:3], v[174:177], v[216:219], v[0:3]
	v_mfma_f32_16x16x32_bf16 v[52:55], v[170:173], v[186:189], v[52:55]
	v_mfma_f32_16x16x32_bf16 v[48:51], v[178:181], v[186:189], v[48:51]
	v_mfma_f32_16x16x32_bf16 v[36:39], v[170:173], v[204:207], v[36:39]
	v_mfma_f32_16x16x32_bf16 v[32:35], v[178:181], v[204:207], v[32:35]
	v_mfma_f32_16x16x32_bf16 v[20:23], v[170:173], v[212:215], v[20:23]
	v_mfma_f32_16x16x32_bf16 v[16:19], v[178:181], v[212:215], v[16:19]
	v_mfma_f32_16x16x32_bf16 v[4:7], v[170:173], v[226:229], v[4:7]
	v_mfma_f32_16x16x32_bf16 v[0:3], v[178:181], v[226:229], v[0:3]
	s_setprio 0
	s_barrier
	s_add_i32 s27, s27, 2
	s_add_u32 s25, s25, 0x100
	s_addc_u32 s26, s26, 0
	s_add_u32 s2, s2, 0x100
	s_addc_u32 s3, s3, 0
	s_cmp_gt_u32 s27, 13
	s_cbranch_scc0 .LBB0_204
	s_and_b64 vcc, exec, s[62:63]
	s_cbranch_vccz .LBB0_207
	s_barrier

; #define PG8_STAGE(bufoff, gbase, voff) do { _Pragma("unroll") for (int _i = 0; _i < 2; ++_i) \
;         __builtin_amdgcn_global_load_lds((const unsigned*)((const char*)(gbase) + (voff)[_i]), (PG8_LAS unsigned*)(lds + (bufoff) + ldsw + _i * 8192), 16, 0, 0); } while (0)
; #define PG8_LDA(dst, b, h) do { _Pragma("unroll") for (int m = 0; m < 4; ++m) _Pragma("unroll") for (int k = 0; k < 2; ++k) dst[m][k] = *(const PG8_LAS bf16x8*)(lds + PG8_SA(b, h) + aoff + m * 2048 + k * 1024); } while (0)
; #define PG8_LDB(dst, b, h) do { _Pragma("unroll") for (int n = 0; n < 2; ++n) _Pragma("unroll") for (int k = 0; k < 2; ++k) dst[n][k] = *(const PG8_LAS bf16x8*)(lds + PG8_SB(b, h) + boff + n * 2048 + k * 1024); } while (0)
; #define PG8_MMA(ai, bj, At, Bt) do { __builtin_amdgcn_s_setprio(1); _Pragma("unroll") for (int m = 0; m < 4; ++m) _Pragma("unroll") for (int n = 0; n < 2; ++n) _Pragma("unroll") for (int k = 0; k < 2; ++k) \
;         acc[ai][bj][m][n] = __builtin_amdgcn_mfma_f32_16x16x32_bf16(Bt[n][k], At[m][k], acc[ai][bj][m][n], 0, 0, 0); __builtin_amdgcn_s_setprio(0); } while (0)
; #define PG8_WAIT_V(n) asm volatile("s_waitcnt vmcnt(" #n ")" ::: "memory")
; #define PG8_WAIT_L(n) asm volatile("s_waitcnt lgkmcnt(" #n ")" ::: "memory")
; template <class Epi, class Sched, bool ALIGN_EPI = false, bool SP2 = false>
; __device__ __forceinline__ void gemm_phase(PG8_LAS unsigned char* lds, const Gemm g, const Sched& S, const Epi& E, int tid_in) {
;     ...
;             const bool last = (t == nt - 2);
;             const char* a1 = cA + (size_t)(t + 1) * kstep;
;             const char* a2 = last ? nA : cA + (size_t)(t + 2) * kstep; const char* b2 = last ? nB : cB + (size_t)(t + 2) * kstep;
;             const char* a3 = a2 + kstep; const char* b3 = b2 + kstep;
;             if (last && has_next) S.a_ready(nxt);
;             if constexpr (SP2) {
;             PG8_LDB(B0, 0, 0); PG8_LDB(B1, 0, 1); PG8_SCHED; PG8_LDA(At, 0, 0); PG8_STAGE(PG8_SA(1, 1), a1 + hstepA, voffA);
;             PG8_WAIT_V(8); PG8_WAIT_L(0); PG8_BAR; PG8_MMA(0, 0, At, B0); PG8_MMA(0, 1, At, B1); PG8_BAR; PG8_SCHED;
;             PG8_LDA(At, 0, 1); PG8_STAGE(PG8_SB(0, 0), b2, voffB); PG8_STAGE(PG8_SB(0, 1), b2 + hstep, voffB); PG8_STAGE(PG8_SA(0, 0), a2, voffA);
;             PG8_WAIT_V(8); PG8_WAIT_L(0); PG8_BAR; PG8_MMA(1, 0, At, B0); PG8_MMA(1, 1, At, B1); PG8_BAR; PG8_SCHED;
.LBB0_526:
	s_add_u32 s12, s2, 0xfffc0080
	s_addc_u32 s13, s3, -1
	s_add_i32 s66, 0, 0x10000
	s_cmp_eq_u32 s65, 12
	s_cselect_b32 s15, s45, s13
	s_cselect_b32 s14, s46, s12
	v_add_u32_e32 v148, s66, v151
	s_cselect_b32 s13, s29, s64
	s_cselect_b32 s12, s47, s51
	s_add_i32 s68, 0, 0x14000
	ds_read_b128 v[140:143], v148
	ds_read_b128 v[144:147], v148 offset:1024
	ds_read_b128 v[160:163], v148 offset:2048
	ds_read_b128 v[164:167], v148 offset:3072
	v_add_u32_e32 v148, s68, v151
	ds_read_b128 v[168:171], v148
	ds_read_b128 v[172:175], v148 offset:1024
	ds_read_b128 v[176:179], v148 offset:2048
	ds_read_b128 v[180:183], v148 offset:3072
	s_add_i32 m0, s56, 0xc000
	ds_read_b128 v[184:187], v156
	ds_read_b128 v[200:203], v156 offset:1024
	ds_read_b128 v[204:207], v156 offset:2048
	ds_read_b128 v[208:211], v156 offset:3072
	ds_read_b128 v[212:215], v156 offset:4096
	ds_read_b128 v[216:219], v156 offset:5120
	ds_read_b128 v[226:229], v156 offset:6144
	ds_read_b128 v[230:233], v156 offset:7168
	global_load_lds_dwordx4 v138, s[2:3]
	s_add_i32 m0, s56, 0xe000
	s_nop 0
	global_load_lds_dwordx4 v136, s[2:3]
	s_waitcnt vmcnt(8)
	s_waitcnt lgkmcnt(0)
	s_barrier
	s_setprio 1
	s_waitcnt lgkmcnt(0)
	v_mfma_f32_16x16x32_bf16 v[124:127], v[140:143], v[184:187], v[124:127]
	v_mfma_f32_16x16x32_bf16 v[120:123], v[160:163], v[184:187], v[120:123]
	v_mfma_f32_16x16x32_bf16 v[108:111], v[140:143], v[204:207], v[108:111]
	v_mfma_f32_16x16x32_bf16 v[104:107], v[160:163], v[204:207], v[104:107]
	v_mfma_f32_16x16x32_bf16 v[92:95], v[140:143], v[212:215], v[92:95]
	v_mfma_f32_16x16x32_bf16 v[88:91], v[160:163], v[212:215], v[88:91]
	v_mfma_f32_16x16x32_bf16 v[76:79], v[140:143], v[226:229], v[76:79]
	v_mfma_f32_16x16x32_bf16 v[72:75], v[160:163], v[226:229], v[72:75]
	v_mfma_f32_16x16x32_bf16 v[124:127], v[144:147], v[200:203], v[124:127]
	v_mfma_f32_16x16x32_bf16 v[120:123], v[164:167], v[200:203], v[120:123]
	v_mfma_f32_16x16x32_bf16 v[108:111], v[144:147], v[208:211], v[108:111]
	v_mfma_f32_16x16x32_bf16 v[104:107], v[164:167], v[208:211], v[104:107]
	v_mfma_f32_16x16x32_bf16 v[92:95], v[144:147], v[216:219], v[92:95]
	v_mfma_f32_16x16x32_bf16 v[88:91], v[164:167], v[216:219], v[88:91]
	v_mfma_f32_16x16x32_bf16 v[76:79], v[144:147], v[230:233], v[76:79]
	v_mfma_f32_16x16x32_bf16 v[72:75], v[164:167], v[230:233], v[72:75]
	s_setprio 0
	s_setprio 1
	v_mfma_f32_16x16x32_bf16 v[116:119], v[168:171], v[184:187], v[116:119]
	v_mfma_f32_16x16x32_bf16 v[112:115], v[176:179], v[184:187], v[112:115]
	v_mfma_f32_16x16x32_bf16 v[100:103], v[168:171], v[204:207], v[100:103]
	v_mfma_f32_16x16x32_bf16 v[96:99], v[176:179], v[204:207], v[96:99]
	v_mfma_f32_16x16x32_bf16 v[84:87], v[168:171], v[212:215], v[84:87]
	v_mfma_f32_16x16x32_bf16 v[80:83], v[176:179], v[212:215], v[80:83]
	v_mfma_f32_16x16x32_bf16 v[68:71], v[168:171], v[226:229], v[68:71]
	v_mfma_f32_16x16x32_bf16 v[64:67], v[176:179], v[226:229], v[64:67]
	v_mfma_f32_16x16x32_bf16 v[116:119], v[172:175], v[200:203], v[116:119]
	v_mfma_f32_16x16x32_bf16 v[112:115], v[180:183], v[200:203], v[112:115]
	v_mfma_f32_16x16x32_bf16 v[100:103], v[172:175], v[208:211], v[100:103]
	v_mfma_f32_16x16x32_bf16 v[96:99], v[180:183], v[208:211], v[96:99]
	v_mfma_f32_16x16x32_bf16 v[84:87], v[172:175], v[216:219], v[84:87]
	v_mfma_f32_16x16x32_bf16 v[80:83], v[180:183], v[216:219], v[80:83]
	v_mfma_f32_16x16x32_bf16 v[68:71], v[172:175], v[230:233], v[68:71]
	v_mfma_f32_16x16x32_bf16 v[64:67], v[180:183], v[230:233], v[64:67]
	s_setprio 0
	s_barrier
	s_add_i32 s66, s66, s49
	v_lshl_add_u64 v[148:149], s[12:13], 0, v[132:133]
	s_mov_b32 m0, s66
	ds_read_b128 v[184:187], v156 offset:16384
	ds_read_b128 v[200:203], v156 offset:17408
	ds_read_b128 v[204:207], v156 offset:18432
	ds_read_b128 v[208:211], v156 offset:19456
	ds_read_b128 v[212:215], v156 offset:20480
	ds_read_b128 v[216:219], v156 offset:21504
	ds_read_b128 v[226:229], v156 offset:22528
	ds_read_b128 v[230:233], v156 offset:23552
	global_load_lds_dwordx4 v[148:149], off
	s_add_i32 m0, s66, 0x2000
	s_add_u32 s66, s12, 0x40000
	v_lshl_add_u64 v[188:189], s[12:13], 0, v[128:129]
	s_addc_u32 s67, s13, 0
	s_add_i32 s68, s68, s49
	global_load_lds_dwordx4 v[188:189], off
	s_mov_b32 m0, s68
	v_lshl_add_u64 v[236:237], s[14:15], 0, v[130:131]
	global_load_lds_dwordx4 v132, s[66:67]
	s_add_i32 m0, s68, 0x2000
	s_nop 0
	global_load_lds_dwordx4 v128, s[66:67]
	v_lshl_add_u64 v[234:235], s[14:15], 0, v[134:135]
	s_mov_b32 m0, s56
	s_nop 0
	global_load_lds_dwordx4 v[234:235], off
	s_mov_b32 m0, s57
	s_nop 0
	global_load_lds_dwordx4 v[236:237], off
	s_waitcnt vmcnt(8)
	s_waitcnt lgkmcnt(0)
	s_barrier
; #define PG8_STAGE(bufoff, gbase, voff) do { _Pragma("unroll") for (int _i = 0; _i < 2; ++_i) \
;         __builtin_amdgcn_global_load_lds((const unsigned*)((const char*)(gbase) + (voff)[_i]), (PG8_LAS unsigned*)(lds + (bufoff) + ldsw + _i * 8192), 16, 0, 0); } while (0)
; #define PG8_LDA(dst, b, h) do { _Pragma("unroll") for (int m = 0; m < 4; ++m) _Pragma("unroll") for (int k = 0; k < 2; ++k) dst[m][k] = *(const PG8_LAS bf16x8*)(lds + PG8_SA(b, h) + aoff + m * 2048 + k * 1024); } while (0)
; #define PG8_LDB(dst, b, h) do { _Pragma("unroll") for (int n = 0; n < 2; ++n) _Pragma("unroll") for (int k = 0; k < 2; ++k) dst[n][k] = *(const PG8_LAS bf16x8*)(lds + PG8_SB(b, h) + boff + n * 2048 + k * 1024); } while (0)
; #define PG8_MMA(ai, bj, At, Bt) do { __builtin_amdgcn_s_setprio(1); _Pragma("unroll") for (int m = 0; m < 4; ++m) _Pragma("unroll") for (int n = 0; n < 2; ++n) _Pragma("unroll") for (int k = 0; k < 2; ++k) \
;         acc[ai][bj][m][n] = __builtin_amdgcn_mfma_f32_16x16x32_bf16(Bt[n][k], At[m][k], acc[ai][bj][m][n], 0, 0, 0); __builtin_amdgcn_s_setprio(0); } while (0)
; #define PG8_WAIT_V(n) asm volatile("s_waitcnt vmcnt(" #n ")" ::: "memory")
; #define PG8_WAIT_L(n) asm volatile("s_waitcnt lgkmcnt(" #n ")" ::: "memory")
; #define PG8_BAR __builtin_amdgcn_s_barrier()
; #define PG8_SCHED __builtin_amdgcn_sched_barrier(0)
; template <class Epi, class Sched, bool ALIGN_EPI = false, bool SP2 = false>
; __device__ __forceinline__ void gemm_phase(PG8_LAS unsigned char* lds, const Gemm g, const Sched& S, const Epi& E, int tid_in) {
;     ...
;             PG8_WAIT_V(8); PG8_WAIT_L(0); PG8_BAR; PG8_MMA(1, 0, At, B0); PG8_MMA(1, 1, At, B1); PG8_BAR; PG8_SCHED;
;             PG8_LDB(B0, 1, 0); PG8_LDB(B1, 1, 1); PG8_SCHED; PG8_LDA(At, 1, 0); PG8_STAGE(PG8_SA(0, 1), a2 + hstepA, voffA);
;             PG8_WAIT_V(8); PG8_WAIT_L(0); PG8_BAR; PG8_MMA(0, 0, At, B0); PG8_MMA(0, 1, At, B1); PG8_BAR; PG8_SCHED;
	s_setprio 1
	s_waitcnt lgkmcnt(0)
	v_mfma_f32_16x16x32_bf16 v[60:63], v[140:143], v[184:187], v[60:63]
	v_mfma_f32_16x16x32_bf16 v[56:59], v[160:163], v[184:187], v[56:59]
	v_mfma_f32_16x16x32_bf16 v[44:47], v[140:143], v[204:207], v[44:47]
	v_mfma_f32_16x16x32_bf16 v[40:43], v[160:163], v[204:207], v[40:43]
	v_mfma_f32_16x16x32_bf16 v[28:31], v[140:143], v[212:215], v[28:31]
	v_mfma_f32_16x16x32_bf16 v[24:27], v[160:163], v[212:215], v[24:27]
	v_mfma_f32_16x16x32_bf16 v[12:15], v[140:143], v[226:229], v[12:15]
	v_mfma_f32_16x16x32_bf16 v[8:11], v[160:163], v[226:229], v[8:11]
	v_mfma_f32_16x16x32_bf16 v[60:63], v[144:147], v[200:203], v[60:63]
	v_mfma_f32_16x16x32_bf16 v[56:59], v[164:167], v[200:203], v[56:59]
	v_mfma_f32_16x16x32_bf16 v[44:47], v[144:147], v[208:211], v[44:47]
	v_mfma_f32_16x16x32_bf16 v[40:43], v[164:167], v[208:211], v[40:43]
	v_mfma_f32_16x16x32_bf16 v[28:31], v[144:147], v[216:219], v[28:31]
	v_mfma_f32_16x16x32_bf16 v[24:27], v[164:167], v[216:219], v[24:27]
	v_mfma_f32_16x16x32_bf16 v[12:15], v[144:147], v[230:233], v[12:15]
	v_mfma_f32_16x16x32_bf16 v[8:11], v[164:167], v[230:233], v[8:11]
	s_setprio 0
	s_setprio 1
	v_mfma_f32_16x16x32_bf16 v[52:55], v[168:171], v[184:187], v[52:55]
	v_mfma_f32_16x16x32_bf16 v[48:51], v[176:179], v[184:187], v[48:51]
	v_mfma_f32_16x16x32_bf16 v[36:39], v[168:171], v[204:207], v[36:39]
	v_mfma_f32_16x16x32_bf16 v[32:35], v[176:179], v[204:207], v[32:35]
	v_mfma_f32_16x16x32_bf16 v[20:23], v[168:171], v[212:215], v[20:23]
	v_mfma_f32_16x16x32_bf16 v[16:19], v[176:179], v[212:215], v[16:19]
	v_mfma_f32_16x16x32_bf16 v[4:7], v[168:171], v[226:229], v[4:7]
	v_mfma_f32_16x16x32_bf16 v[0:3], v[176:179], v[226:229], v[0:3]
	v_mfma_f32_16x16x32_bf16 v[52:55], v[172:175], v[200:203], v[52:55]
	v_mfma_f32_16x16x32_bf16 v[48:51], v[180:183], v[200:203], v[48:51]
	v_mfma_f32_16x16x32_bf16 v[36:39], v[172:175], v[208:211], v[36:39]
	v_mfma_f32_16x16x32_bf16 v[32:35], v[180:183], v[208:211], v[32:35]
	v_mfma_f32_16x16x32_bf16 v[20:23], v[172:175], v[216:219], v[20:23]
	v_mfma_f32_16x16x32_bf16 v[16:19], v[180:183], v[216:219], v[16:19]
	v_mfma_f32_16x16x32_bf16 v[4:7], v[172:175], v[230:233], v[4:7]
	v_mfma_f32_16x16x32_bf16 v[0:3], v[180:183], v[230:233], v[0:3]
	s_setprio 0
	s_barrier
	s_add_i32 s66, 0, 0x18000
	v_add_u32_e32 v157, s66, v151
	s_add_i32 s67, 0, 0x1c000
	ds_read_b128 v[140:143], v157
	ds_read_b128 v[144:147], v157 offset:1024
	ds_read_b128 v[160:163], v157 offset:2048
	ds_read_b128 v[164:167], v157 offset:3072
	v_add_u32_e32 v157, s67, v151
	ds_read_b128 v[168:171], v157
	ds_read_b128 v[172:175], v157 offset:1024
	ds_read_b128 v[176:179], v157 offset:2048
	ds_read_b128 v[180:183], v157 offset:3072
	s_add_u32 s14, s14, 0x40000
	s_addc_u32 s15, s15, 0
	s_mov_b32 m0, s58
	ds_read_b128 v[184:187], v156 offset:32768
	ds_read_b128 v[200:203], v156 offset:33792
	ds_read_b128 v[204:207], v156 offset:34816
	ds_read_b128 v[208:211], v156 offset:35840
	ds_read_b128 v[212:215], v156 offset:36864
	ds_read_b128 v[216:219], v156 offset:37888
	ds_read_b128 v[226:229], v156 offset:38912
	ds_read_b128 v[230:233], v156 offset:39936
	global_load_lds_dwordx4 v134, s[14:15]
	s_mov_b32 m0, s59
	s_nop 0
	global_load_lds_dwordx4 v130, s[14:15]
	s_waitcnt vmcnt(8)
	s_waitcnt lgkmcnt(0)
	s_barrier
	s_setprio 1
	s_waitcnt lgkmcnt(0)
	v_mfma_f32_16x16x32_bf16 v[124:127], v[140:143], v[184:187], v[124:127]
	v_mfma_f32_16x16x32_bf16 v[120:123], v[160:163], v[184:187], v[120:123]
	v_mfma_f32_16x16x32_bf16 v[108:111], v[140:143], v[204:207], v[108:111]
	v_mfma_f32_16x16x32_bf16 v[104:107], v[160:163], v[204:207], v[104:107]
	v_mfma_f32_16x16x32_bf16 v[92:95], v[140:143], v[212:215], v[92:95]
	v_mfma_f32_16x16x32_bf16 v[88:91], v[160:163], v[212:215], v[88:91]
	v_mfma_f32_16x16x32_bf16 v[76:79], v[140:143], v[226:229], v[76:79]
	v_mfma_f32_16x16x32_bf16 v[72:75], v[160:163], v[226:229], v[72:75]
	v_mfma_f32_16x16x32_bf16 v[124:127], v[144:147], v[200:203], v[124:127]
	v_mfma_f32_16x16x32_bf16 v[120:123], v[164:167], v[200:203], v[120:123]
	v_mfma_f32_16x16x32_bf16 v[108:111], v[144:147], v[208:211], v[108:111]
	v_mfma_f32_16x16x32_bf16 v[104:107], v[164:167], v[208:211], v[104:107]
	v_mfma_f32_16x16x32_bf16 v[92:95], v[144:147], v[216:219], v[92:95]
	v_mfma_f32_16x16x32_bf16 v[88:91], v[164:167], v[216:219], v[88:91]
	v_mfma_f32_16x16x32_bf16 v[76:79], v[144:147], v[230:233], v[76:79]
	v_mfma_f32_16x16x32_bf16 v[72:75], v[164:167], v[230:233], v[72:75]
	s_setprio 0
	s_setprio 1
	v_mfma_f32_16x16x32_bf16 v[116:119], v[168:171], v[184:187], v[116:119]
	v_mfma_f32_16x16x32_bf16 v[112:115], v[176:179], v[184:187], v[112:115]
	v_mfma_f32_16x16x32_bf16 v[100:103], v[168:171], v[204:207], v[100:103]
	v_mfma_f32_16x16x32_bf16 v[96:99], v[176:179], v[204:207], v[96:99]
	v_mfma_f32_16x16x32_bf16 v[84:87], v[168:171], v[212:215], v[84:87]
	v_mfma_f32_16x16x32_bf16 v[80:83], v[176:179], v[212:215], v[80:83]
	v_mfma_f32_16x16x32_bf16 v[68:71], v[168:171], v[226:229], v[68:71]
	v_mfma_f32_16x16x32_bf16 v[64:67], v[176:179], v[226:229], v[64:67]
	v_mfma_f32_16x16x32_bf16 v[116:119], v[172:175], v[200:203], v[116:119]
	v_mfma_f32_16x16x32_bf16 v[112:115], v[180:183], v[200:203], v[112:115]
	v_mfma_f32_16x16x32_bf16 v[100:103], v[172:175], v[208:211], v[100:103]
	v_mfma_f32_16x16x32_bf16 v[96:99], v[180:183], v[208:211], v[96:99]
	v_mfma_f32_16x16x32_bf16 v[84:87], v[172:175], v[216:219], v[84:87]
	v_mfma_f32_16x16x32_bf16 v[80:83], v[180:183], v[216:219], v[80:83]
	v_mfma_f32_16x16x32_bf16 v[68:71], v[172:175], v[230:233], v[68:71]
	v_mfma_f32_16x16x32_bf16 v[64:67], v[180:183], v[230:233], v[64:67]
	s_setprio 0
	s_barrier
; #define PG8_STAGE(bufoff, gbase, voff) do { _Pragma("unroll") for (int _i = 0; _i < 2; ++_i) \
;         __builtin_amdgcn_global_load_lds((const unsigned*)((const char*)(gbase) + (voff)[_i]), (PG8_LAS unsigned*)(lds + (bufoff) + ldsw + _i * 8192), 16, 0, 0); } while (0)
; #define PG8_LDA(dst, b, h) do { _Pragma("unroll") for (int m = 0; m < 4; ++m) _Pragma("unroll") for (int k = 0; k < 2; ++k) dst[m][k] = *(const PG8_LAS bf16x8*)(lds + PG8_SA(b, h) + aoff + m * 2048 + k * 1024); } while (0)
; #define PG8_MMA(ai, bj, At, Bt) do { __builtin_amdgcn_s_setprio(1); _Pragma("unroll") for (int m = 0; m < 4; ++m) _Pragma("unroll") for (int n = 0; n < 2; ++n) _Pragma("unroll") for (int k = 0; k < 2; ++k) \
;         acc[ai][bj][m][n] = __builtin_amdgcn_mfma_f32_16x16x32_bf16(Bt[n][k], At[m][k], acc[ai][bj][m][n], 0, 0, 0); __builtin_amdgcn_s_setprio(0); } while (0)
; #define PG8_WAIT_V(n) asm volatile("s_waitcnt vmcnt(" #n ")" ::: "memory")
; #define PG8_WAIT_L(n) asm volatile("s_waitcnt lgkmcnt(" #n ")" ::: "memory")
; #define PG8_BAR __builtin_amdgcn_s_barrier()
; #define PG8_SCHED __builtin_amdgcn_sched_barrier(0)
; template <class Epi, class Sched, bool ALIGN_EPI = false, bool SP2 = false>
; __device__ __forceinline__ void gemm_phase(PG8_LAS unsigned char* lds, const Gemm g, const Sched& S, const Epi& E, int tid_in) {
;     ...
;             PG8_LDA(At, 1, 1); PG8_STAGE(PG8_SB(1, 0), b3, voffB); PG8_STAGE(PG8_SB(1, 1), b3 + hstep, voffB); PG8_STAGE(PG8_SA(1, 0), a3, voffA);
;             PG8_WAIT_V(8); PG8_WAIT_L(0); PG8_BAR; PG8_MMA(1, 0, At, B0); PG8_MMA(1, 1, At, B1); PG8_BAR; PG8_SCHED;
;     ...
;         if constexpr (ALIGN_EPI) { if (wr == 0) PG8_BAR; }
	s_add_i32 s14, s66, s49
	v_lshl_add_u64 v[148:149], v[148:149], 0, s[0:1]
	s_mov_b32 m0, s14
	ds_read_b128 v[184:187], v156 offset:49152
	ds_read_b128 v[200:203], v156 offset:50176
	ds_read_b128 v[204:207], v156 offset:51200
	ds_read_b128 v[208:211], v156 offset:52224
	ds_read_b128 v[212:215], v156 offset:53248
	ds_read_b128 v[216:219], v156 offset:54272
	ds_read_b128 v[226:229], v156 offset:55296
	ds_read_b128 v[230:233], v156 offset:56320
	global_load_lds_dwordx4 v[148:149], off
	s_add_i32 m0, s14, 0x2000
	s_add_u32 s12, s12, 0x40080
	v_lshl_add_u64 v[148:149], v[188:189], 0, s[0:1]
	s_addc_u32 s13, s13, 0
	s_add_i32 s14, s67, s49
	global_load_lds_dwordx4 v[148:149], off
	s_mov_b32 m0, s14
	s_nop 0
	global_load_lds_dwordx4 v132, s[12:13]
	s_add_i32 m0, s14, 0x2000
	s_nop 0
	global_load_lds_dwordx4 v128, s[12:13]
	v_lshl_add_u64 v[148:149], v[234:235], 0, s[0:1]
	s_mov_b32 m0, s61
	s_nop 0
	global_load_lds_dwordx4 v[148:149], off
	v_lshl_add_u64 v[148:149], v[236:237], 0, s[0:1]
	s_mov_b32 m0, s62
	s_nop 0
	global_load_lds_dwordx4 v[148:149], off
	s_waitcnt vmcnt(8)
	s_waitcnt lgkmcnt(0)
	s_barrier
	s_setprio 1
	s_waitcnt lgkmcnt(0)
	v_mfma_f32_16x16x32_bf16 v[60:63], v[140:143], v[184:187], v[60:63]
	v_mfma_f32_16x16x32_bf16 v[56:59], v[160:163], v[184:187], v[56:59]
	v_mfma_f32_16x16x32_bf16 v[44:47], v[140:143], v[204:207], v[44:47]
	v_mfma_f32_16x16x32_bf16 v[40:43], v[160:163], v[204:207], v[40:43]
	v_mfma_f32_16x16x32_bf16 v[28:31], v[140:143], v[212:215], v[28:31]
	v_mfma_f32_16x16x32_bf16 v[24:27], v[160:163], v[212:215], v[24:27]
	v_mfma_f32_16x16x32_bf16 v[12:15], v[140:143], v[226:229], v[12:15]
	v_mfma_f32_16x16x32_bf16 v[8:11], v[160:163], v[226:229], v[8:11]
	v_mfma_f32_16x16x32_bf16 v[60:63], v[144:147], v[200:203], v[60:63]
	v_mfma_f32_16x16x32_bf16 v[56:59], v[164:167], v[200:203], v[56:59]
	v_mfma_f32_16x16x32_bf16 v[44:47], v[144:147], v[208:211], v[44:47]
	v_mfma_f32_16x16x32_bf16 v[40:43], v[164:167], v[208:211], v[40:43]
	v_mfma_f32_16x16x32_bf16 v[28:31], v[144:147], v[216:219], v[28:31]
	v_mfma_f32_16x16x32_bf16 v[24:27], v[164:167], v[216:219], v[24:27]
	v_mfma_f32_16x16x32_bf16 v[12:15], v[144:147], v[230:233], v[12:15]
	v_mfma_f32_16x16x32_bf16 v[8:11], v[164:167], v[230:233], v[8:11]
	s_setprio 0
	s_setprio 1
	v_mfma_f32_16x16x32_bf16 v[52:55], v[168:171], v[184:187], v[52:55]
	v_mfma_f32_16x16x32_bf16 v[48:51], v[176:179], v[184:187], v[48:51]
	v_mfma_f32_16x16x32_bf16 v[36:39], v[168:171], v[204:207], v[36:39]
	v_mfma_f32_16x16x32_bf16 v[32:35], v[176:179], v[204:207], v[32:35]
	v_mfma_f32_16x16x32_bf16 v[20:23], v[168:171], v[212:215], v[20:23]
	v_mfma_f32_16x16x32_bf16 v[16:19], v[176:179], v[212:215], v[16:19]
	v_mfma_f32_16x16x32_bf16 v[4:7], v[168:171], v[226:229], v[4:7]
	v_mfma_f32_16x16x32_bf16 v[0:3], v[176:179], v[226:229], v[0:3]
	v_mfma_f32_16x16x32_bf16 v[52:55], v[172:175], v[200:203], v[52:55]
	v_mfma_f32_16x16x32_bf16 v[48:51], v[180:183], v[200:203], v[48:51]
	v_mfma_f32_16x16x32_bf16 v[36:39], v[172:175], v[208:211], v[36:39]
	v_mfma_f32_16x16x32_bf16 v[32:35], v[180:183], v[208:211], v[32:35]
	v_mfma_f32_16x16x32_bf16 v[20:23], v[172:175], v[216:219], v[20:23]
	v_mfma_f32_16x16x32_bf16 v[16:19], v[180:183], v[216:219], v[16:19]
	v_mfma_f32_16x16x32_bf16 v[4:7], v[172:175], v[230:233], v[4:7]
	v_mfma_f32_16x16x32_bf16 v[0:3], v[180:183], v[230:233], v[0:3]
	s_setprio 0
	s_barrier
	s_add_i32 s65, s65, 2
	s_add_u32 s51, s51, 0x100
	s_addc_u32 s64, s64, 0
	s_add_u32 s2, s2, 0x100
	s_addc_u32 s3, s3, 0
	s_cmp_gt_u32 s65, 13
	s_cbranch_scc0 .LBB0_526
	s_and_b64 vcc, exec, s[34:35]
	s_cbranch_vccz .LBB0_529
	s_barrier

; #define PG8_STAGE(bufoff, gbase, voff) do { _Pragma("unroll") for (int _i = 0; _i < 2; ++_i) \
;         __builtin_amdgcn_global_load_lds((const unsigned*)((const char*)(gbase) + (voff)[_i]), (PG8_LAS unsigned*)(lds + (bufoff) + ldsw + _i * 8192), 16, 0, 0); } while (0)
; #define PG8_LDA(dst, b, h) do { _Pragma("unroll") for (int m = 0; m < 4; ++m) _Pragma("unroll") for (int k = 0; k < 2; ++k) dst[m][k] = *(const PG8_LAS bf16x8*)(lds + PG8_SA(b, h) + aoff + m * 2048 + k * 1024); } while (0)
; #define PG8_LDB(dst, b, h) do { _Pragma("unroll") for (int n = 0; n < 2; ++n) _Pragma("unroll") for (int k = 0; k < 2; ++k) dst[n][k] = *(const PG8_LAS bf16x8*)(lds + PG8_SB(b, h) + boff + n * 2048 + k * 1024); } while (0)
; #define PG8_MMA(ai, bj, At, Bt) do { __builtin_amdgcn_s_setprio(1); _Pragma("unroll") for (int m = 0; m < 4; ++m) _Pragma("unroll") for (int n = 0; n < 2; ++n) _Pragma("unroll") for (int k = 0; k < 2; ++k) \
;         acc[ai][bj][m][n] = __builtin_amdgcn_mfma_f32_16x16x32_bf16(Bt[n][k], At[m][k], acc[ai][bj][m][n], 0, 0, 0); __builtin_amdgcn_s_setprio(0); } while (0)
; #define PG8_WAIT_V(n) asm volatile("s_waitcnt vmcnt(" #n ")" ::: "memory")
; #define PG8_WAIT_L(n) asm volatile("s_waitcnt lgkmcnt(" #n ")" ::: "memory")
; template <class Epi, class Sched, bool ALIGN_EPI = false, bool SP2 = false>
; __device__ __forceinline__ void gemm_phase(PG8_LAS unsigned char* lds, const Gemm g, const Sched& S, const Epi& E, int tid_in) {
;     ...
;             const bool last = (t == nt - 2);
;             const char* a1 = cA + (size_t)(t + 1) * kstep;
;             const char* a2 = last ? nA : cA + (size_t)(t + 2) * kstep; const char* b2 = last ? nB : cB + (size_t)(t + 2) * kstep;
;             const char* a3 = a2 + kstep; const char* b3 = b2 + kstep;
;             if (last && has_next) S.a_ready(nxt);
;             if constexpr (SP2) {
;             PG8_LDB(B0, 0, 0); PG8_LDB(B1, 0, 1); PG8_SCHED; PG8_LDA(At, 0, 0); PG8_STAGE(PG8_SA(1, 1), a1 + hstepA, voffA);
;             PG8_WAIT_V(8); PG8_WAIT_L(0); PG8_BAR; PG8_MMA(0, 0, At, B0); PG8_MMA(0, 1, At, B1); PG8_BAR; PG8_SCHED;
;             PG8_LDA(At, 0, 1); PG8_STAGE(PG8_SB(0, 0), b2, voffB); PG8_STAGE(PG8_SB(0, 1), b2 + hstep, voffB); PG8_STAGE(PG8_SA(0, 0), a2, voffA);
;             PG8_WAIT_V(8); PG8_WAIT_L(0); PG8_BAR; PG8_MMA(1, 0, At, B0); PG8_MMA(1, 1, At, B1); PG8_BAR; PG8_SCHED;
.LBB0_691:
	s_add_u32 s28, s26, 0xfffc0080
	s_addc_u32 s29, s27, -1
	s_add_i32 s57, 0, 0x10000
	s_cmp_eq_u32 s56, 12
	s_cselect_b32 s31, s15, s29
	s_cselect_b32 s30, s52, s28
	v_add_u32_e32 v147, s57, v145
	s_cselect_b32 s29, s13, s55
	s_cselect_b32 s28, s53, s54
	s_add_i32 s60, 0, 0x14000
	ds_read_b128 v[140:143], v147
	ds_read_b128 v[148:151], v147 offset:1024
	ds_read_b128 v[152:155], v147 offset:2048
	ds_read_b128 v[156:159], v147 offset:3072
	v_add_u32_e32 v147, s60, v145
	ds_read_b128 v[160:163], v147
	ds_read_b128 v[164:167], v147 offset:1024
	ds_read_b128 v[168:171], v147 offset:2048
	ds_read_b128 v[172:175], v147 offset:3072
	s_add_i32 m0, s42, 0xc000
	ds_read_b128 v[176:179], v146
	ds_read_b128 v[180:183], v146 offset:1024
	ds_read_b128 v[184:187], v146 offset:2048
	ds_read_b128 v[200:203], v146 offset:3072
	ds_read_b128 v[204:207], v146 offset:4096
	ds_read_b128 v[208:211], v146 offset:5120
	ds_read_b128 v[212:215], v146 offset:6144
	ds_read_b128 v[216:219], v146 offset:7168
	global_load_lds_dwordx4 v138, s[26:27]
	s_add_i32 m0, s42, 0xe000
	s_nop 0
	global_load_lds_dwordx4 v136, s[26:27]
	s_waitcnt vmcnt(8)
	s_waitcnt lgkmcnt(0)
	s_barrier
	s_setprio 1
	s_waitcnt lgkmcnt(0)
	v_mfma_f32_16x16x32_bf16 v[124:127], v[140:143], v[176:179], v[124:127]
	v_mfma_f32_16x16x32_bf16 v[120:123], v[152:155], v[176:179], v[120:123]
	v_mfma_f32_16x16x32_bf16 v[108:111], v[140:143], v[184:187], v[108:111]
	v_mfma_f32_16x16x32_bf16 v[104:107], v[152:155], v[184:187], v[104:107]
	v_mfma_f32_16x16x32_bf16 v[92:95], v[140:143], v[204:207], v[92:95]
	v_mfma_f32_16x16x32_bf16 v[88:91], v[152:155], v[204:207], v[88:91]
	v_mfma_f32_16x16x32_bf16 v[76:79], v[140:143], v[212:215], v[76:79]
	v_mfma_f32_16x16x32_bf16 v[72:75], v[152:155], v[212:215], v[72:75]
	v_mfma_f32_16x16x32_bf16 v[124:127], v[148:151], v[180:183], v[124:127]
	v_mfma_f32_16x16x32_bf16 v[120:123], v[156:159], v[180:183], v[120:123]
	v_mfma_f32_16x16x32_bf16 v[108:111], v[148:151], v[200:203], v[108:111]
	v_mfma_f32_16x16x32_bf16 v[104:107], v[156:159], v[200:203], v[104:107]
	v_mfma_f32_16x16x32_bf16 v[92:95], v[148:151], v[208:211], v[92:95]
	v_mfma_f32_16x16x32_bf16 v[88:91], v[156:159], v[208:211], v[88:91]
	v_mfma_f32_16x16x32_bf16 v[76:79], v[148:151], v[216:219], v[76:79]
	v_mfma_f32_16x16x32_bf16 v[72:75], v[156:159], v[216:219], v[72:75]
	s_setprio 0
	s_setprio 1
	v_mfma_f32_16x16x32_bf16 v[116:119], v[160:163], v[176:179], v[116:119]
	v_mfma_f32_16x16x32_bf16 v[112:115], v[168:171], v[176:179], v[112:115]
	v_mfma_f32_16x16x32_bf16 v[100:103], v[160:163], v[184:187], v[100:103]
	v_mfma_f32_16x16x32_bf16 v[96:99], v[168:171], v[184:187], v[96:99]
	v_mfma_f32_16x16x32_bf16 v[84:87], v[160:163], v[204:207], v[84:87]
	v_mfma_f32_16x16x32_bf16 v[80:83], v[168:171], v[204:207], v[80:83]
	v_mfma_f32_16x16x32_bf16 v[68:71], v[160:163], v[212:215], v[68:71]
	v_mfma_f32_16x16x32_bf16 v[64:67], v[168:171], v[212:215], v[64:67]
	v_mfma_f32_16x16x32_bf16 v[116:119], v[164:167], v[180:183], v[116:119]
	v_mfma_f32_16x16x32_bf16 v[112:115], v[172:175], v[180:183], v[112:115]
	v_mfma_f32_16x16x32_bf16 v[100:103], v[164:167], v[200:203], v[100:103]
	v_mfma_f32_16x16x32_bf16 v[96:99], v[172:175], v[200:203], v[96:99]
	v_mfma_f32_16x16x32_bf16 v[84:87], v[164:167], v[208:211], v[84:87]
	v_mfma_f32_16x16x32_bf16 v[80:83], v[172:175], v[208:211], v[80:83]
	v_mfma_f32_16x16x32_bf16 v[68:71], v[164:167], v[216:219], v[68:71]
	v_mfma_f32_16x16x32_bf16 v[64:67], v[172:175], v[216:219], v[64:67]
	s_setprio 0
	s_barrier
	s_add_i32 s57, s57, s41
	v_lshl_add_u64 v[188:189], s[28:29], 0, v[132:133]
	s_mov_b32 m0, s57
	ds_read_b128 v[176:179], v146 offset:16384
	ds_read_b128 v[180:183], v146 offset:17408
	ds_read_b128 v[184:187], v146 offset:18432
	ds_read_b128 v[200:203], v146 offset:19456
	ds_read_b128 v[204:207], v146 offset:20480
	ds_read_b128 v[208:211], v146 offset:21504
	ds_read_b128 v[212:215], v146 offset:22528
	ds_read_b128 v[216:219], v146 offset:23552
	global_load_lds_dwordx4 v[188:189], off
	s_add_i32 m0, s57, 0x2000
	s_add_u32 s58, s28, 0x40000
	v_lshl_add_u64 v[226:227], s[28:29], 0, v[128:129]
	s_addc_u32 s59, s29, 0
	s_add_i32 s57, s60, s41
	global_load_lds_dwordx4 v[226:227], off
	s_mov_b32 m0, s57
	v_lshl_add_u64 v[230:231], s[30:31], 0, v[130:131]
	global_load_lds_dwordx4 v132, s[58:59]
	s_add_i32 m0, s57, 0x2000
	s_nop 0
	global_load_lds_dwordx4 v128, s[58:59]
	v_lshl_add_u64 v[228:229], s[30:31], 0, v[134:135]
	s_mov_b32 m0, s42
	s_nop 0
	global_load_lds_dwordx4 v[228:229], off
	s_mov_b32 m0, s43
	s_nop 0
	global_load_lds_dwordx4 v[230:231], off
	s_waitcnt vmcnt(8)
	s_waitcnt lgkmcnt(0)
	s_barrier
; #define PG8_STAGE(bufoff, gbase, voff) do { _Pragma("unroll") for (int _i = 0; _i < 2; ++_i) \
;         __builtin_amdgcn_global_load_lds((const unsigned*)((const char*)(gbase) + (voff)[_i]), (PG8_LAS unsigned*)(lds + (bufoff) + ldsw + _i * 8192), 16, 0, 0); } while (0)
; #define PG8_LDA(dst, b, h) do { _Pragma("unroll") for (int m = 0; m < 4; ++m) _Pragma("unroll") for (int k = 0; k < 2; ++k) dst[m][k] = *(const PG8_LAS bf16x8*)(lds + PG8_SA(b, h) + aoff + m * 2048 + k * 1024); } while (0)
; #define PG8_LDB(dst, b, h) do { _Pragma("unroll") for (int n = 0; n < 2; ++n) _Pragma("unroll") for (int k = 0; k < 2; ++k) dst[n][k] = *(const PG8_LAS bf16x8*)(lds + PG8_SB(b, h) + boff + n * 2048 + k * 1024); } while (0)
; #define PG8_MMA(ai, bj, At, Bt) do { __builtin_amdgcn_s_setprio(1); _Pragma("unroll") for (int m = 0; m < 4; ++m) _Pragma("unroll") for (int n = 0; n < 2; ++n) _Pragma("unroll") for (int k = 0; k < 2; ++k) \
;         acc[ai][bj][m][n] = __builtin_amdgcn_mfma_f32_16x16x32_bf16(Bt[n][k], At[m][k], acc[ai][bj][m][n], 0, 0, 0); __builtin_amdgcn_s_setprio(0); } while (0)
; #define PG8_WAIT_V(n) asm volatile("s_waitcnt vmcnt(" #n ")" ::: "memory")
; #define PG8_WAIT_L(n) asm volatile("s_waitcnt lgkmcnt(" #n ")" ::: "memory")
; #define PG8_BAR __builtin_amdgcn_s_barrier()
; #define PG8_SCHED __builtin_amdgcn_sched_barrier(0)
; template <class Epi, class Sched, bool ALIGN_EPI = false, bool SP2 = false>
; __device__ __forceinline__ void gemm_phase(PG8_LAS unsigned char* lds, const Gemm g, const Sched& S, const Epi& E, int tid_in) {
;     ...
;             PG8_WAIT_V(8); PG8_WAIT_L(0); PG8_BAR; PG8_MMA(1, 0, At, B0); PG8_MMA(1, 1, At, B1); PG8_BAR; PG8_SCHED;
;             PG8_LDB(B0, 1, 0); PG8_LDB(B1, 1, 1); PG8_SCHED; PG8_LDA(At, 1, 0); PG8_STAGE(PG8_SA(0, 1), a2 + hstepA, voffA);
;             PG8_WAIT_V(8); PG8_WAIT_L(0); PG8_BAR; PG8_MMA(0, 0, At, B0); PG8_MMA(0, 1, At, B1); PG8_BAR; PG8_SCHED;
	s_setprio 1
	s_waitcnt lgkmcnt(0)
	v_mfma_f32_16x16x32_bf16 v[60:63], v[140:143], v[176:179], v[60:63]
	v_mfma_f32_16x16x32_bf16 v[56:59], v[152:155], v[176:179], v[56:59]
	v_mfma_f32_16x16x32_bf16 v[44:47], v[140:143], v[184:187], v[44:47]
	v_mfma_f32_16x16x32_bf16 v[40:43], v[152:155], v[184:187], v[40:43]
	v_mfma_f32_16x16x32_bf16 v[28:31], v[140:143], v[204:207], v[28:31]
	v_mfma_f32_16x16x32_bf16 v[24:27], v[152:155], v[204:207], v[24:27]
	v_mfma_f32_16x16x32_bf16 v[12:15], v[140:143], v[212:215], v[12:15]
	v_mfma_f32_16x16x32_bf16 v[8:11], v[152:155], v[212:215], v[8:11]
	v_mfma_f32_16x16x32_bf16 v[60:63], v[148:151], v[180:183], v[60:63]
	v_mfma_f32_16x16x32_bf16 v[56:59], v[156:159], v[180:183], v[56:59]
	v_mfma_f32_16x16x32_bf16 v[44:47], v[148:151], v[200:203], v[44:47]
	v_mfma_f32_16x16x32_bf16 v[40:43], v[156:159], v[200:203], v[40:43]
	v_mfma_f32_16x16x32_bf16 v[28:31], v[148:151], v[208:211], v[28:31]
	v_mfma_f32_16x16x32_bf16 v[24:27], v[156:159], v[208:211], v[24:27]
	v_mfma_f32_16x16x32_bf16 v[12:15], v[148:151], v[216:219], v[12:15]
	v_mfma_f32_16x16x32_bf16 v[8:11], v[156:159], v[216:219], v[8:11]
	s_setprio 0
	s_setprio 1
	v_mfma_f32_16x16x32_bf16 v[52:55], v[160:163], v[176:179], v[52:55]
	v_mfma_f32_16x16x32_bf16 v[48:51], v[168:171], v[176:179], v[48:51]
	v_mfma_f32_16x16x32_bf16 v[36:39], v[160:163], v[184:187], v[36:39]
	v_mfma_f32_16x16x32_bf16 v[32:35], v[168:171], v[184:187], v[32:35]
	v_mfma_f32_16x16x32_bf16 v[20:23], v[160:163], v[204:207], v[20:23]
	v_mfma_f32_16x16x32_bf16 v[16:19], v[168:171], v[204:207], v[16:19]
	v_mfma_f32_16x16x32_bf16 v[4:7], v[160:163], v[212:215], v[4:7]
	v_mfma_f32_16x16x32_bf16 v[0:3], v[168:171], v[212:215], v[0:3]
	v_mfma_f32_16x16x32_bf16 v[52:55], v[164:167], v[180:183], v[52:55]
	v_mfma_f32_16x16x32_bf16 v[48:51], v[172:175], v[180:183], v[48:51]
	v_mfma_f32_16x16x32_bf16 v[36:39], v[164:167], v[200:203], v[36:39]
	v_mfma_f32_16x16x32_bf16 v[32:35], v[172:175], v[200:203], v[32:35]
	v_mfma_f32_16x16x32_bf16 v[20:23], v[164:167], v[208:211], v[20:23]
	v_mfma_f32_16x16x32_bf16 v[16:19], v[172:175], v[208:211], v[16:19]
	v_mfma_f32_16x16x32_bf16 v[4:7], v[164:167], v[216:219], v[4:7]
	v_mfma_f32_16x16x32_bf16 v[0:3], v[172:175], v[216:219], v[0:3]
	s_setprio 0
	s_barrier
	s_add_i32 s57, 0, 0x18000
	v_add_u32_e32 v147, s57, v145
	s_add_i32 s58, 0, 0x1c000
	ds_read_b128 v[140:143], v147
	ds_read_b128 v[148:151], v147 offset:1024
	ds_read_b128 v[152:155], v147 offset:2048
	ds_read_b128 v[156:159], v147 offset:3072
	v_add_u32_e32 v147, s58, v145
	ds_read_b128 v[160:163], v147
	ds_read_b128 v[164:167], v147 offset:1024
	ds_read_b128 v[168:171], v147 offset:2048
	ds_read_b128 v[172:175], v147 offset:3072
	s_add_u32 s30, s30, 0x40000
	s_addc_u32 s31, s31, 0
	s_mov_b32 m0, s44
	ds_read_b128 v[176:179], v146 offset:32768
	ds_read_b128 v[180:183], v146 offset:33792
	ds_read_b128 v[184:187], v146 offset:34816
	ds_read_b128 v[200:203], v146 offset:35840
	ds_read_b128 v[204:207], v146 offset:36864
	ds_read_b128 v[208:211], v146 offset:37888
	ds_read_b128 v[212:215], v146 offset:38912
	ds_read_b128 v[216:219], v146 offset:39936
	global_load_lds_dwordx4 v134, s[30:31]
	s_mov_b32 m0, s45
	s_nop 0
	global_load_lds_dwordx4 v130, s[30:31]
	s_waitcnt vmcnt(8)
	s_waitcnt lgkmcnt(0)
	s_barrier
	s_setprio 1
	s_waitcnt lgkmcnt(0)
	v_mfma_f32_16x16x32_bf16 v[124:127], v[140:143], v[176:179], v[124:127]
	v_mfma_f32_16x16x32_bf16 v[120:123], v[152:155], v[176:179], v[120:123]
	v_mfma_f32_16x16x32_bf16 v[108:111], v[140:143], v[184:187], v[108:111]
	v_mfma_f32_16x16x32_bf16 v[104:107], v[152:155], v[184:187], v[104:107]
	v_mfma_f32_16x16x32_bf16 v[92:95], v[140:143], v[204:207], v[92:95]
	v_mfma_f32_16x16x32_bf16 v[88:91], v[152:155], v[204:207], v[88:91]
	v_mfma_f32_16x16x32_bf16 v[76:79], v[140:143], v[212:215], v[76:79]
	v_mfma_f32_16x16x32_bf16 v[72:75], v[152:155], v[212:215], v[72:75]
	v_mfma_f32_16x16x32_bf16 v[124:127], v[148:151], v[180:183], v[124:127]
	v_mfma_f32_16x16x32_bf16 v[120:123], v[156:159], v[180:183], v[120:123]
	v_mfma_f32_16x16x32_bf16 v[108:111], v[148:151], v[200:203], v[108:111]
	v_mfma_f32_16x16x32_bf16 v[104:107], v[156:159], v[200:203], v[104:107]
	v_mfma_f32_16x16x32_bf16 v[92:95], v[148:151], v[208:211], v[92:95]
	v_mfma_f32_16x16x32_bf16 v[88:91], v[156:159], v[208:211], v[88:91]
	v_mfma_f32_16x16x32_bf16 v[76:79], v[148:151], v[216:219], v[76:79]
	v_mfma_f32_16x16x32_bf16 v[72:75], v[156:159], v[216:219], v[72:75]
	s_setprio 0
	s_setprio 1
	v_mfma_f32_16x16x32_bf16 v[116:119], v[160:163], v[176:179], v[116:119]
	v_mfma_f32_16x16x32_bf16 v[112:115], v[168:171], v[176:179], v[112:115]
	v_mfma_f32_16x16x32_bf16 v[100:103], v[160:163], v[184:187], v[100:103]
	v_mfma_f32_16x16x32_bf16 v[96:99], v[168:171], v[184:187], v[96:99]
	v_mfma_f32_16x16x32_bf16 v[84:87], v[160:163], v[204:207], v[84:87]
	v_mfma_f32_16x16x32_bf16 v[80:83], v[168:171], v[204:207], v[80:83]
	v_mfma_f32_16x16x32_bf16 v[68:71], v[160:163], v[212:215], v[68:71]
	v_mfma_f32_16x16x32_bf16 v[64:67], v[168:171], v[212:215], v[64:67]
	v_mfma_f32_16x16x32_bf16 v[116:119], v[164:167], v[180:183], v[116:119]
	v_mfma_f32_16x16x32_bf16 v[112:115], v[172:175], v[180:183], v[112:115]
	v_mfma_f32_16x16x32_bf16 v[100:103], v[164:167], v[200:203], v[100:103]
	v_mfma_f32_16x16x32_bf16 v[96:99], v[172:175], v[200:203], v[96:99]
	v_mfma_f32_16x16x32_bf16 v[84:87], v[164:167], v[208:211], v[84:87]
	v_mfma_f32_16x16x32_bf16 v[80:83], v[172:175], v[208:211], v[80:83]
	v_mfma_f32_16x16x32_bf16 v[68:71], v[164:167], v[216:219], v[68:71]
	v_mfma_f32_16x16x32_bf16 v[64:67], v[172:175], v[216:219], v[64:67]
	s_setprio 0
	s_barrier
; #define PG8_STAGE(bufoff, gbase, voff) do { _Pragma("unroll") for (int _i = 0; _i < 2; ++_i) \
;         __builtin_amdgcn_global_load_lds((const unsigned*)((const char*)(gbase) + (voff)[_i]), (PG8_LAS unsigned*)(lds + (bufoff) + ldsw + _i * 8192), 16, 0, 0); } while (0)
; #define PG8_LDA(dst, b, h) do { _Pragma("unroll") for (int m = 0; m < 4; ++m) _Pragma("unroll") for (int k = 0; k < 2; ++k) dst[m][k] = *(const PG8_LAS bf16x8*)(lds + PG8_SA(b, h) + aoff + m * 2048 + k * 1024); } while (0)
; #define PG8_MMA(ai, bj, At, Bt) do { __builtin_amdgcn_s_setprio(1); _Pragma("unroll") for (int m = 0; m < 4; ++m) _Pragma("unroll") for (int n = 0; n < 2; ++n) _Pragma("unroll") for (int k = 0; k < 2; ++k) \
;         acc[ai][bj][m][n] = __builtin_amdgcn_mfma_f32_16x16x32_bf16(Bt[n][k], At[m][k], acc[ai][bj][m][n], 0, 0, 0); __builtin_amdgcn_s_setprio(0); } while (0)
; #define PG8_WAIT_V(n) asm volatile("s_waitcnt vmcnt(" #n ")" ::: "memory")
; #define PG8_WAIT_L(n) asm volatile("s_waitcnt lgkmcnt(" #n ")" ::: "memory")
; #define PG8_BAR __builtin_amdgcn_s_barrier()
; #define PG8_SCHED __builtin_amdgcn_sched_barrier(0)
; template <class Epi, class Sched, bool ALIGN_EPI = false, bool SP2 = false>
; __device__ __forceinline__ void gemm_phase(PG8_LAS unsigned char* lds, const Gemm g, const Sched& S, const Epi& E, int tid_in) {
;     ...
;             PG8_LDA(At, 1, 1); PG8_STAGE(PG8_SB(1, 0), b3, voffB); PG8_STAGE(PG8_SB(1, 1), b3 + hstep, voffB); PG8_STAGE(PG8_SA(1, 0), a3, voffA);
;             PG8_WAIT_V(8); PG8_WAIT_L(0); PG8_BAR; PG8_MMA(1, 0, At, B0); PG8_MMA(1, 1, At, B1); PG8_BAR; PG8_SCHED;
;     ...
;         if constexpr (ALIGN_EPI) { if (wr == 0) PG8_BAR; }
	s_add_i32 s30, s57, s41
	v_lshl_add_u64 v[188:189], v[188:189], 0, s[0:1]
	s_mov_b32 m0, s30
	ds_read_b128 v[176:179], v146 offset:49152
	ds_read_b128 v[180:183], v146 offset:50176
	ds_read_b128 v[184:187], v146 offset:51200
	ds_read_b128 v[200:203], v146 offset:52224
	ds_read_b128 v[204:207], v146 offset:53248
	ds_read_b128 v[208:211], v146 offset:54272
	ds_read_b128 v[212:215], v146 offset:55296
	ds_read_b128 v[216:219], v146 offset:56320
	global_load_lds_dwordx4 v[188:189], off
	s_add_i32 m0, s30, 0x2000
	s_add_u32 s28, s28, 0x40080
	v_lshl_add_u64 v[188:189], v[226:227], 0, s[0:1]
	s_addc_u32 s29, s29, 0
	s_add_i32 s30, s58, s41
	global_load_lds_dwordx4 v[188:189], off
	s_mov_b32 m0, s30
	s_nop 0
	global_load_lds_dwordx4 v132, s[28:29]
	s_add_i32 m0, s30, 0x2000
	s_nop 0
	global_load_lds_dwordx4 v128, s[28:29]
	v_lshl_add_u64 v[188:189], v[228:229], 0, s[0:1]
	s_mov_b32 m0, s46
	s_nop 0
	global_load_lds_dwordx4 v[188:189], off
	v_lshl_add_u64 v[188:189], v[230:231], 0, s[0:1]
	s_mov_b32 m0, s47
	s_nop 0
	global_load_lds_dwordx4 v[188:189], off
	s_waitcnt vmcnt(8)
	s_waitcnt lgkmcnt(0)
	s_barrier
	s_setprio 1
	s_waitcnt lgkmcnt(0)
	v_mfma_f32_16x16x32_bf16 v[60:63], v[140:143], v[176:179], v[60:63]
	v_mfma_f32_16x16x32_bf16 v[56:59], v[152:155], v[176:179], v[56:59]
	v_mfma_f32_16x16x32_bf16 v[44:47], v[140:143], v[184:187], v[44:47]
	v_mfma_f32_16x16x32_bf16 v[40:43], v[152:155], v[184:187], v[40:43]
	v_mfma_f32_16x16x32_bf16 v[28:31], v[140:143], v[204:207], v[28:31]
	v_mfma_f32_16x16x32_bf16 v[24:27], v[152:155], v[204:207], v[24:27]
	v_mfma_f32_16x16x32_bf16 v[12:15], v[140:143], v[212:215], v[12:15]
	v_mfma_f32_16x16x32_bf16 v[8:11], v[152:155], v[212:215], v[8:11]
	v_mfma_f32_16x16x32_bf16 v[60:63], v[148:151], v[180:183], v[60:63]
	v_mfma_f32_16x16x32_bf16 v[56:59], v[156:159], v[180:183], v[56:59]
	v_mfma_f32_16x16x32_bf16 v[44:47], v[148:151], v[200:203], v[44:47]
	v_mfma_f32_16x16x32_bf16 v[40:43], v[156:159], v[200:203], v[40:43]
	v_mfma_f32_16x16x32_bf16 v[28:31], v[148:151], v[208:211], v[28:31]
	v_mfma_f32_16x16x32_bf16 v[24:27], v[156:159], v[208:211], v[24:27]
	v_mfma_f32_16x16x32_bf16 v[12:15], v[148:151], v[216:219], v[12:15]
	v_mfma_f32_16x16x32_bf16 v[8:11], v[156:159], v[216:219], v[8:11]
	s_setprio 0
	s_setprio 1
	v_mfma_f32_16x16x32_bf16 v[52:55], v[160:163], v[176:179], v[52:55]
	v_mfma_f32_16x16x32_bf16 v[48:51], v[168:171], v[176:179], v[48:51]
	v_mfma_f32_16x16x32_bf16 v[36:39], v[160:163], v[184:187], v[36:39]
	v_mfma_f32_16x16x32_bf16 v[32:35], v[168:171], v[184:187], v[32:35]
	v_mfma_f32_16x16x32_bf16 v[20:23], v[160:163], v[204:207], v[20:23]
	v_mfma_f32_16x16x32_bf16 v[16:19], v[168:171], v[204:207], v[16:19]
	v_mfma_f32_16x16x32_bf16 v[4:7], v[160:163], v[212:215], v[4:7]
	v_mfma_f32_16x16x32_bf16 v[0:3], v[168:171], v[212:215], v[0:3]
	v_mfma_f32_16x16x32_bf16 v[52:55], v[164:167], v[180:183], v[52:55]
	v_mfma_f32_16x16x32_bf16 v[48:51], v[172:175], v[180:183], v[48:51]
	v_mfma_f32_16x16x32_bf16 v[36:39], v[164:167], v[200:203], v[36:39]
	v_mfma_f32_16x16x32_bf16 v[32:35], v[172:175], v[200:203], v[32:35]
	v_mfma_f32_16x16x32_bf16 v[20:23], v[164:167], v[208:211], v[20:23]
	v_mfma_f32_16x16x32_bf16 v[16:19], v[172:175], v[208:211], v[16:19]
	v_mfma_f32_16x16x32_bf16 v[4:7], v[164:167], v[216:219], v[4:7]
	v_mfma_f32_16x16x32_bf16 v[0:3], v[172:175], v[216:219], v[0:3]
	s_setprio 0
	s_barrier
	s_add_i32 s56, s56, 2
	s_add_u32 s54, s54, 0x100
	s_addc_u32 s55, s55, 0
	s_add_u32 s26, s26, 0x100
	s_addc_u32 s27, s27, 0
	s_cmp_gt_u32 s56, 13
	s_cbranch_scc0 .LBB0_691
	v_readlane_b32 s56, v255, 17
	s_and_b64 vcc, exec, s[10:11]
	s_mov_b64 s[30:31], 0x10000600
	v_readlane_b32 s57, v255, 18
	v_readlane_b32 s58, v255, 19
	v_readlane_b32 s59, v255, 20
	s_cbranch_vccz .LBB0_694
	s_barrier

; #define PG8_STAGE(bufoff, gbase, voff) do { _Pragma("unroll") for (int _i = 0; _i < 2; ++_i) \
;         __builtin_amdgcn_global_load_lds((const unsigned*)((const char*)(gbase) + (voff)[_i]), (PG8_LAS unsigned*)(lds + (bufoff) + ldsw + _i * 8192), 16, 0, 0); } while (0)
; #define PG8_LDA(dst, b, h) do { _Pragma("unroll") for (int m = 0; m < 4; ++m) _Pragma("unroll") for (int k = 0; k < 2; ++k) dst[m][k] = *(const PG8_LAS bf16x8*)(lds + PG8_SA(b, h) + aoff + m * 2048 + k * 1024); } while (0)
; #define PG8_LDB(dst, b, h) do { _Pragma("unroll") for (int n = 0; n < 2; ++n) _Pragma("unroll") for (int k = 0; k < 2; ++k) dst[n][k] = *(const PG8_LAS bf16x8*)(lds + PG8_SB(b, h) + boff + n * 2048 + k * 1024); } while (0)
; #define PG8_MMA(ai, bj, At, Bt) do { __builtin_amdgcn_s_setprio(1); _Pragma("unroll") for (int m = 0; m < 4; ++m) _Pragma("unroll") for (int n = 0; n < 2; ++n) _Pragma("unroll") for (int k = 0; k < 2; ++k) \
;         acc[ai][bj][m][n] = __builtin_amdgcn_mfma_f32_16x16x32_bf16(Bt[n][k], At[m][k], acc[ai][bj][m][n], 0, 0, 0); __builtin_amdgcn_s_setprio(0); } while (0)
; #define PG8_WAIT_V(n) asm volatile("s_waitcnt vmcnt(" #n ")" ::: "memory")
; #define PG8_WAIT_L(n) asm volatile("s_waitcnt lgkmcnt(" #n ")" ::: "memory")
; template <class Epi, class Sched, bool ALIGN_EPI = false, bool SP2 = false>
; __device__ __forceinline__ void gemm_phase(PG8_LAS unsigned char* lds, const Gemm g, const Sched& S, const Epi& E, int tid_in) {
;     ...
;             const bool last = (t == nt - 2);
;             const char* a1 = cA + (size_t)(t + 1) * kstep;
;             const char* a2 = last ? nA : cA + (size_t)(t + 2) * kstep; const char* b2 = last ? nB : cB + (size_t)(t + 2) * kstep;
;             const char* a3 = a2 + kstep; const char* b3 = b2 + kstep;
;             if (last && has_next) S.a_ready(nxt);
;             if constexpr (SP2) {
;             PG8_LDB(B0, 0, 0); PG8_LDB(B1, 0, 1); PG8_SCHED; PG8_LDA(At, 0, 0); PG8_STAGE(PG8_SA(1, 1), a1 + hstepA, voffA);
;             PG8_WAIT_V(8); PG8_WAIT_L(0); PG8_BAR; PG8_MMA(0, 0, At, B0); PG8_MMA(0, 1, At, B1); PG8_BAR; PG8_SCHED;
;             PG8_LDA(At, 0, 1); PG8_STAGE(PG8_SB(0, 0), b2, voffB); PG8_STAGE(PG8_SB(0, 1), b2 + hstep, voffB); PG8_STAGE(PG8_SA(0, 0), a2, voffA);
;             PG8_WAIT_V(8); PG8_WAIT_L(0); PG8_BAR; PG8_MMA(1, 0, At, B0); PG8_MMA(1, 1, At, B1); PG8_BAR; PG8_SCHED;
.LBB0_782:
	s_add_u32 s26, s24, 0xfffc0080
	s_addc_u32 s27, s25, -1
	s_add_i32 s54, 0, 0x10000
	s_cmp_eq_u32 s53, 28
	s_cselect_b32 s29, s15, s27
	s_cselect_b32 s28, s49, s26
	s_cselect_b32 s27, s13, s52
	s_cselect_b32 s26, s50, s51
	s_add_i32 s56, 0, 0x14000
	v_add_u32_e32 v158, s54, v156
	v_add_u32_e32 v174, s56, v156
	ds_read_b128 v[96:99], v158
	ds_read_b128 v[100:103], v158 offset:1024
	ds_read_b128 v[150:153], v158 offset:2048
	ds_read_b128 v[158:161], v158 offset:3072
	ds_read_b128 v[162:165], v174
	ds_read_b128 v[166:169], v174 offset:1024
	ds_read_b128 v[170:173], v174 offset:2048
	ds_read_b128 v[174:177], v174 offset:3072
	s_add_i32 m0, s38, 0xc000
	ds_read_b128 v[178:181], v157
	ds_read_b128 v[182:185], v157 offset:1024
	ds_read_b128 v[186:189], v157 offset:2048
	ds_read_b128 v[200:203], v157 offset:3072
	ds_read_b128 v[204:207], v157 offset:4096
	ds_read_b128 v[208:211], v157 offset:5120
	ds_read_b128 v[212:215], v157 offset:6144
	ds_read_b128 v[216:219], v157 offset:7168
	global_load_lds_dwordx4 v148, s[24:25]
	s_add_i32 m0, s38, 0xe000
	s_nop 0
	global_load_lds_dwordx4 v146, s[24:25]
	s_waitcnt vmcnt(8)
	s_waitcnt lgkmcnt(0)
	s_barrier
	s_setprio 1
	s_waitcnt lgkmcnt(0)
	v_mfma_f32_16x16x32_bf16 v[132:135], v[96:99], v[178:181], v[132:135]
	v_mfma_f32_16x16x32_bf16 v[128:131], v[150:153], v[178:181], v[128:131]
	v_mfma_f32_16x16x32_bf16 v[124:127], v[96:99], v[186:189], v[124:127]
	v_mfma_f32_16x16x32_bf16 v[120:123], v[150:153], v[186:189], v[120:123]
	v_mfma_f32_16x16x32_bf16 v[116:119], v[96:99], v[204:207], v[116:119]
	v_mfma_f32_16x16x32_bf16 v[112:115], v[150:153], v[204:207], v[112:115]
	v_mfma_f32_16x16x32_bf16 v[108:111], v[96:99], v[212:215], v[108:111]
	v_mfma_f32_16x16x32_bf16 v[104:107], v[150:153], v[212:215], v[104:107]
	v_mfma_f32_16x16x32_bf16 v[132:135], v[100:103], v[182:185], v[132:135]
	v_mfma_f32_16x16x32_bf16 v[128:131], v[158:161], v[182:185], v[128:131]
	v_mfma_f32_16x16x32_bf16 v[124:127], v[100:103], v[200:203], v[124:127]
	v_mfma_f32_16x16x32_bf16 v[120:123], v[158:161], v[200:203], v[120:123]
	v_mfma_f32_16x16x32_bf16 v[116:119], v[100:103], v[208:211], v[116:119]
	v_mfma_f32_16x16x32_bf16 v[112:115], v[158:161], v[208:211], v[112:115]
	v_mfma_f32_16x16x32_bf16 v[108:111], v[100:103], v[216:219], v[108:111]
	v_mfma_f32_16x16x32_bf16 v[104:107], v[158:161], v[216:219], v[104:107]
	s_setprio 0
	s_setprio 1
	v_mfma_f32_16x16x32_bf16 v[60:63], v[162:165], v[178:181], v[60:63]
	v_mfma_f32_16x16x32_bf16 v[56:59], v[170:173], v[178:181], v[56:59]
	v_mfma_f32_16x16x32_bf16 v[52:55], v[162:165], v[186:189], v[52:55]
	v_mfma_f32_16x16x32_bf16 v[48:51], v[170:173], v[186:189], v[48:51]
	v_mfma_f32_16x16x32_bf16 v[44:47], v[162:165], v[204:207], v[44:47]
	v_mfma_f32_16x16x32_bf16 v[40:43], v[170:173], v[204:207], v[40:43]
	v_mfma_f32_16x16x32_bf16 v[36:39], v[162:165], v[212:215], v[36:39]
	v_mfma_f32_16x16x32_bf16 v[32:35], v[170:173], v[212:215], v[32:35]
	v_mfma_f32_16x16x32_bf16 v[60:63], v[166:169], v[182:185], v[60:63]
	v_mfma_f32_16x16x32_bf16 v[56:59], v[174:177], v[182:185], v[56:59]
	v_mfma_f32_16x16x32_bf16 v[52:55], v[166:169], v[200:203], v[52:55]
	v_mfma_f32_16x16x32_bf16 v[48:51], v[174:177], v[200:203], v[48:51]
	v_mfma_f32_16x16x32_bf16 v[44:47], v[166:169], v[208:211], v[44:47]
	v_mfma_f32_16x16x32_bf16 v[40:43], v[174:177], v[208:211], v[40:43]
	v_mfma_f32_16x16x32_bf16 v[36:39], v[166:169], v[216:219], v[36:39]
	v_mfma_f32_16x16x32_bf16 v[32:35], v[174:177], v[216:219], v[32:35]
	s_setprio 0
	s_barrier
	s_add_i32 s54, s54, s35
	v_lshl_add_u64 v[226:227], s[26:27], 0, v[190:191]
	s_mov_b32 m0, s54
	ds_read_b128 v[178:181], v157 offset:16384
	ds_read_b128 v[182:185], v157 offset:17408
	ds_read_b128 v[186:189], v157 offset:18432
	ds_read_b128 v[200:203], v157 offset:19456
	ds_read_b128 v[204:207], v157 offset:20480
	ds_read_b128 v[208:211], v157 offset:21504
	ds_read_b128 v[212:215], v157 offset:22528
	ds_read_b128 v[216:219], v157 offset:23552
	global_load_lds_dwordx4 v[226:227], off
	s_add_i32 m0, s54, 0x2000
	s_add_u32 s54, s26, 0x80000
	v_lshl_add_u64 v[228:229], s[26:27], 0, v[136:137]
	s_addc_u32 s55, s27, 0
	s_add_i32 s56, s56, s35
	global_load_lds_dwordx4 v[228:229], off
	s_mov_b32 m0, s56
	v_lshl_add_u64 v[232:233], s[28:29], 0, v[138:139]
	global_load_lds_dwordx4 v190, s[54:55]
	s_add_i32 m0, s56, 0x2000
	s_nop 0
	global_load_lds_dwordx4 v136, s[54:55]
	v_lshl_add_u64 v[230:231], s[28:29], 0, v[140:141]
	s_mov_b32 m0, s38
	s_nop 0
	global_load_lds_dwordx4 v[230:231], off
	s_mov_b32 m0, s40
	s_nop 0
	global_load_lds_dwordx4 v[232:233], off
	s_waitcnt vmcnt(8)
	s_waitcnt lgkmcnt(0)
	s_barrier
; #define PG8_STAGE(bufoff, gbase, voff) do { _Pragma("unroll") for (int _i = 0; _i < 2; ++_i) \
;         __builtin_amdgcn_global_load_lds((const unsigned*)((const char*)(gbase) + (voff)[_i]), (PG8_LAS unsigned*)(lds + (bufoff) + ldsw + _i * 8192), 16, 0, 0); } while (0)
; #define PG8_LDA(dst, b, h) do { _Pragma("unroll") for (int m = 0; m < 4; ++m) _Pragma("unroll") for (int k = 0; k < 2; ++k) dst[m][k] = *(const PG8_LAS bf16x8*)(lds + PG8_SA(b, h) + aoff + m * 2048 + k * 1024); } while (0)
; #define PG8_LDB(dst, b, h) do { _Pragma("unroll") for (int n = 0; n < 2; ++n) _Pragma("unroll") for (int k = 0; k < 2; ++k) dst[n][k] = *(const PG8_LAS bf16x8*)(lds + PG8_SB(b, h) + boff + n * 2048 + k * 1024); } while (0)
; #define PG8_MMA(ai, bj, At, Bt) do { __builtin_amdgcn_s_setprio(1); _Pragma("unroll") for (int m = 0; m < 4; ++m) _Pragma("unroll") for (int n = 0; n < 2; ++n) _Pragma("unroll") for (int k = 0; k < 2; ++k) \
;         acc[ai][bj][m][n] = __builtin_amdgcn_mfma_f32_16x16x32_bf16(Bt[n][k], At[m][k], acc[ai][bj][m][n], 0, 0, 0); __builtin_amdgcn_s_setprio(0); } while (0)
; #define PG8_WAIT_V(n) asm volatile("s_waitcnt vmcnt(" #n ")" ::: "memory")
; #define PG8_WAIT_L(n) asm volatile("s_waitcnt lgkmcnt(" #n ")" ::: "memory")
; #define PG8_BAR __builtin_amdgcn_s_barrier()
; #define PG8_SCHED __builtin_amdgcn_sched_barrier(0)
; template <class Epi, class Sched, bool ALIGN_EPI = false, bool SP2 = false>
; __device__ __forceinline__ void gemm_phase(PG8_LAS unsigned char* lds, const Gemm g, const Sched& S, const Epi& E, int tid_in) {
;     ...
;             PG8_WAIT_V(8); PG8_WAIT_L(0); PG8_BAR; PG8_MMA(1, 0, At, B0); PG8_MMA(1, 1, At, B1); PG8_BAR; PG8_SCHED;
;             PG8_LDB(B0, 1, 0); PG8_LDB(B1, 1, 1); PG8_SCHED; PG8_LDA(At, 1, 0); PG8_STAGE(PG8_SA(0, 1), a2 + hstepA, voffA);
;             PG8_WAIT_V(8); PG8_WAIT_L(0); PG8_BAR; PG8_MMA(0, 0, At, B0); PG8_MMA(0, 1, At, B1); PG8_BAR; PG8_SCHED;
	s_setprio 1
	s_waitcnt lgkmcnt(0)
	v_mfma_f32_16x16x32_bf16 v[92:95], v[96:99], v[178:181], v[92:95]
	v_mfma_f32_16x16x32_bf16 v[88:91], v[150:153], v[178:181], v[88:91]
	v_mfma_f32_16x16x32_bf16 v[84:87], v[96:99], v[186:189], v[84:87]
	v_mfma_f32_16x16x32_bf16 v[80:83], v[150:153], v[186:189], v[80:83]
	v_mfma_f32_16x16x32_bf16 v[76:79], v[96:99], v[204:207], v[76:79]
	v_mfma_f32_16x16x32_bf16 v[72:75], v[150:153], v[204:207], v[72:75]
	v_mfma_f32_16x16x32_bf16 v[68:71], v[96:99], v[212:215], v[68:71]
	v_mfma_f32_16x16x32_bf16 v[64:67], v[150:153], v[212:215], v[64:67]
	v_mfma_f32_16x16x32_bf16 v[92:95], v[100:103], v[182:185], v[92:95]
	v_mfma_f32_16x16x32_bf16 v[88:91], v[158:161], v[182:185], v[88:91]
	v_mfma_f32_16x16x32_bf16 v[84:87], v[100:103], v[200:203], v[84:87]
	v_mfma_f32_16x16x32_bf16 v[80:83], v[158:161], v[200:203], v[80:83]
	v_mfma_f32_16x16x32_bf16 v[76:79], v[100:103], v[208:211], v[76:79]
	v_mfma_f32_16x16x32_bf16 v[72:75], v[158:161], v[208:211], v[72:75]
	v_mfma_f32_16x16x32_bf16 v[68:71], v[100:103], v[216:219], v[68:71]
	v_mfma_f32_16x16x32_bf16 v[64:67], v[158:161], v[216:219], v[64:67]
	s_setprio 0
	s_setprio 1
	v_mfma_f32_16x16x32_bf16 v[28:31], v[162:165], v[178:181], v[28:31]
	v_mfma_f32_16x16x32_bf16 v[24:27], v[170:173], v[178:181], v[24:27]
	v_mfma_f32_16x16x32_bf16 v[20:23], v[162:165], v[186:189], v[20:23]
	v_mfma_f32_16x16x32_bf16 v[16:19], v[170:173], v[186:189], v[16:19]
	v_mfma_f32_16x16x32_bf16 v[12:15], v[162:165], v[204:207], v[12:15]
	v_mfma_f32_16x16x32_bf16 v[8:11], v[170:173], v[204:207], v[8:11]
	v_mfma_f32_16x16x32_bf16 v[4:7], v[162:165], v[212:215], v[4:7]
	v_mfma_f32_16x16x32_bf16 v[0:3], v[170:173], v[212:215], v[0:3]
	v_mfma_f32_16x16x32_bf16 v[28:31], v[166:169], v[182:185], v[28:31]
	v_mfma_f32_16x16x32_bf16 v[24:27], v[174:177], v[182:185], v[24:27]
	v_mfma_f32_16x16x32_bf16 v[20:23], v[166:169], v[200:203], v[20:23]
	v_mfma_f32_16x16x32_bf16 v[16:19], v[174:177], v[200:203], v[16:19]
	v_mfma_f32_16x16x32_bf16 v[12:15], v[166:169], v[208:211], v[12:15]
	v_mfma_f32_16x16x32_bf16 v[8:11], v[174:177], v[208:211], v[8:11]
	v_mfma_f32_16x16x32_bf16 v[4:7], v[166:169], v[216:219], v[4:7]
	v_mfma_f32_16x16x32_bf16 v[0:3], v[174:177], v[216:219], v[0:3]
	s_setprio 0
	s_barrier
	s_add_i32 s54, 0, 0x18000
	s_add_i32 s55, 0, 0x1c000
	v_add_u32_e32 v158, s54, v156
	v_add_u32_e32 v174, s55, v156
	ds_read_b128 v[96:99], v158
	ds_read_b128 v[100:103], v158 offset:1024
	ds_read_b128 v[150:153], v158 offset:2048
	ds_read_b128 v[158:161], v158 offset:3072
	ds_read_b128 v[162:165], v174
	ds_read_b128 v[166:169], v174 offset:1024
	ds_read_b128 v[170:173], v174 offset:2048
	ds_read_b128 v[174:177], v174 offset:3072
	s_add_u32 s28, s28, 0x40000
	s_addc_u32 s29, s29, 0
	s_mov_b32 m0, s41
	ds_read_b128 v[178:181], v157 offset:32768
	ds_read_b128 v[182:185], v157 offset:33792
	ds_read_b128 v[186:189], v157 offset:34816
	ds_read_b128 v[200:203], v157 offset:35840
	ds_read_b128 v[204:207], v157 offset:36864
	ds_read_b128 v[208:211], v157 offset:37888
	ds_read_b128 v[212:215], v157 offset:38912
	ds_read_b128 v[216:219], v157 offset:39936
	global_load_lds_dwordx4 v140, s[28:29]
	s_mov_b32 m0, s42
	s_nop 0
	global_load_lds_dwordx4 v138, s[28:29]
	s_waitcnt vmcnt(8)
	s_waitcnt lgkmcnt(0)
	s_barrier
	s_setprio 1
	s_waitcnt lgkmcnt(0)
	v_mfma_f32_16x16x32_bf16 v[132:135], v[96:99], v[178:181], v[132:135]
	v_mfma_f32_16x16x32_bf16 v[128:131], v[150:153], v[178:181], v[128:131]
	v_mfma_f32_16x16x32_bf16 v[124:127], v[96:99], v[186:189], v[124:127]
	v_mfma_f32_16x16x32_bf16 v[120:123], v[150:153], v[186:189], v[120:123]
	v_mfma_f32_16x16x32_bf16 v[116:119], v[96:99], v[204:207], v[116:119]
	v_mfma_f32_16x16x32_bf16 v[112:115], v[150:153], v[204:207], v[112:115]
	v_mfma_f32_16x16x32_bf16 v[108:111], v[96:99], v[212:215], v[108:111]
	v_mfma_f32_16x16x32_bf16 v[104:107], v[150:153], v[212:215], v[104:107]
	v_mfma_f32_16x16x32_bf16 v[132:135], v[100:103], v[182:185], v[132:135]
	v_mfma_f32_16x16x32_bf16 v[128:131], v[158:161], v[182:185], v[128:131]
	v_mfma_f32_16x16x32_bf16 v[124:127], v[100:103], v[200:203], v[124:127]
	v_mfma_f32_16x16x32_bf16 v[120:123], v[158:161], v[200:203], v[120:123]
	v_mfma_f32_16x16x32_bf16 v[116:119], v[100:103], v[208:211], v[116:119]
	v_mfma_f32_16x16x32_bf16 v[112:115], v[158:161], v[208:211], v[112:115]
	v_mfma_f32_16x16x32_bf16 v[108:111], v[100:103], v[216:219], v[108:111]
	v_mfma_f32_16x16x32_bf16 v[104:107], v[158:161], v[216:219], v[104:107]
	s_setprio 0
	s_setprio 1
	v_mfma_f32_16x16x32_bf16 v[60:63], v[162:165], v[178:181], v[60:63]
	v_mfma_f32_16x16x32_bf16 v[56:59], v[170:173], v[178:181], v[56:59]
	v_mfma_f32_16x16x32_bf16 v[52:55], v[162:165], v[186:189], v[52:55]
	v_mfma_f32_16x16x32_bf16 v[48:51], v[170:173], v[186:189], v[48:51]
	v_mfma_f32_16x16x32_bf16 v[44:47], v[162:165], v[204:207], v[44:47]
	v_mfma_f32_16x16x32_bf16 v[40:43], v[170:173], v[204:207], v[40:43]
	v_mfma_f32_16x16x32_bf16 v[36:39], v[162:165], v[212:215], v[36:39]
	v_mfma_f32_16x16x32_bf16 v[32:35], v[170:173], v[212:215], v[32:35]
	v_mfma_f32_16x16x32_bf16 v[60:63], v[166:169], v[182:185], v[60:63]
	v_mfma_f32_16x16x32_bf16 v[56:59], v[174:177], v[182:185], v[56:59]
	v_mfma_f32_16x16x32_bf16 v[52:55], v[166:169], v[200:203], v[52:55]
	v_mfma_f32_16x16x32_bf16 v[48:51], v[174:177], v[200:203], v[48:51]
	v_mfma_f32_16x16x32_bf16 v[44:47], v[166:169], v[208:211], v[44:47]
	v_mfma_f32_16x16x32_bf16 v[40:43], v[174:177], v[208:211], v[40:43]
	v_mfma_f32_16x16x32_bf16 v[36:39], v[166:169], v[216:219], v[36:39]
	v_mfma_f32_16x16x32_bf16 v[32:35], v[174:177], v[216:219], v[32:35]
	s_setprio 0
	s_barrier
; #define PG8_STAGE(bufoff, gbase, voff) do { _Pragma("unroll") for (int _i = 0; _i < 2; ++_i) \
;         __builtin_amdgcn_global_load_lds((const unsigned*)((const char*)(gbase) + (voff)[_i]), (PG8_LAS unsigned*)(lds + (bufoff) + ldsw + _i * 8192), 16, 0, 0); } while (0)
; #define PG8_LDA(dst, b, h) do { _Pragma("unroll") for (int m = 0; m < 4; ++m) _Pragma("unroll") for (int k = 0; k < 2; ++k) dst[m][k] = *(const PG8_LAS bf16x8*)(lds + PG8_SA(b, h) + aoff + m * 2048 + k * 1024); } while (0)
; #define PG8_MMA(ai, bj, At, Bt) do { __builtin_amdgcn_s_setprio(1); _Pragma("unroll") for (int m = 0; m < 4; ++m) _Pragma("unroll") for (int n = 0; n < 2; ++n) _Pragma("unroll") for (int k = 0; k < 2; ++k) \
;         acc[ai][bj][m][n] = __builtin_amdgcn_mfma_f32_16x16x32_bf16(Bt[n][k], At[m][k], acc[ai][bj][m][n], 0, 0, 0); __builtin_amdgcn_s_setprio(0); } while (0)
; #define PG8_WAIT_V(n) asm volatile("s_waitcnt vmcnt(" #n ")" ::: "memory")
; #define PG8_WAIT_L(n) asm volatile("s_waitcnt lgkmcnt(" #n ")" ::: "memory")
; #define PG8_BAR __builtin_amdgcn_s_barrier()
; #define PG8_SCHED __builtin_amdgcn_sched_barrier(0)
; template <class Epi, class Sched, bool ALIGN_EPI = false, bool SP2 = false>
; __device__ __forceinline__ void gemm_phase(PG8_LAS unsigned char* lds, const Gemm g, const Sched& S, const Epi& E, int tid_in) {
;     ...
;             PG8_LDA(At, 1, 1); PG8_STAGE(PG8_SB(1, 0), b3, voffB); PG8_STAGE(PG8_SB(1, 1), b3 + hstep, voffB); PG8_STAGE(PG8_SA(1, 0), a3, voffA);
;             PG8_WAIT_V(8); PG8_WAIT_L(0); PG8_BAR; PG8_MMA(1, 0, At, B0); PG8_MMA(1, 1, At, B1); PG8_BAR; PG8_SCHED;
;     ...
;         if constexpr (ALIGN_EPI) { if (wr == 0) PG8_BAR; }
	s_add_i32 s28, s54, s35
	v_lshl_add_u64 v[226:227], v[226:227], 0, s[0:1]
	s_mov_b32 m0, s28
	ds_read_b128 v[178:181], v157 offset:49152
	ds_read_b128 v[182:185], v157 offset:50176
	ds_read_b128 v[186:189], v157 offset:51200
	ds_read_b128 v[200:203], v157 offset:52224
	ds_read_b128 v[204:207], v157 offset:53248
	ds_read_b128 v[208:211], v157 offset:54272
	ds_read_b128 v[212:215], v157 offset:55296
	ds_read_b128 v[216:219], v157 offset:56320
	global_load_lds_dwordx4 v[226:227], off
	s_add_i32 m0, s28, 0x2000
	s_add_u32 s26, s26, 0x80080
	v_lshl_add_u64 v[226:227], v[228:229], 0, s[0:1]
	s_addc_u32 s27, s27, 0
	s_add_i32 s28, s55, s35
	global_load_lds_dwordx4 v[226:227], off
	s_mov_b32 m0, s28
	s_nop 0
	global_load_lds_dwordx4 v190, s[26:27]
	s_add_i32 m0, s28, 0x2000
	s_nop 0
	global_load_lds_dwordx4 v136, s[26:27]
	v_lshl_add_u64 v[226:227], v[230:231], 0, s[0:1]
	s_mov_b32 m0, s45
	s_nop 0
	global_load_lds_dwordx4 v[226:227], off
	v_lshl_add_u64 v[226:227], v[232:233], 0, s[0:1]
	s_mov_b32 m0, s46
	s_nop 0
	global_load_lds_dwordx4 v[226:227], off
	s_waitcnt vmcnt(8)
	s_waitcnt lgkmcnt(0)
	s_barrier
	s_setprio 1
	s_waitcnt lgkmcnt(0)
	v_mfma_f32_16x16x32_bf16 v[92:95], v[96:99], v[178:181], v[92:95]
	v_mfma_f32_16x16x32_bf16 v[88:91], v[150:153], v[178:181], v[88:91]
	v_mfma_f32_16x16x32_bf16 v[84:87], v[96:99], v[186:189], v[84:87]
	v_mfma_f32_16x16x32_bf16 v[80:83], v[150:153], v[186:189], v[80:83]
	v_mfma_f32_16x16x32_bf16 v[76:79], v[96:99], v[204:207], v[76:79]
	v_mfma_f32_16x16x32_bf16 v[72:75], v[150:153], v[204:207], v[72:75]
	v_mfma_f32_16x16x32_bf16 v[68:71], v[96:99], v[212:215], v[68:71]
	v_mfma_f32_16x16x32_bf16 v[64:67], v[150:153], v[212:215], v[64:67]
	v_mfma_f32_16x16x32_bf16 v[92:95], v[100:103], v[182:185], v[92:95]
	v_mfma_f32_16x16x32_bf16 v[88:91], v[158:161], v[182:185], v[88:91]
	v_mfma_f32_16x16x32_bf16 v[84:87], v[100:103], v[200:203], v[84:87]
	v_mfma_f32_16x16x32_bf16 v[80:83], v[158:161], v[200:203], v[80:83]
	v_mfma_f32_16x16x32_bf16 v[76:79], v[100:103], v[208:211], v[76:79]
	v_mfma_f32_16x16x32_bf16 v[72:75], v[158:161], v[208:211], v[72:75]
	v_mfma_f32_16x16x32_bf16 v[68:71], v[100:103], v[216:219], v[68:71]
	v_mfma_f32_16x16x32_bf16 v[64:67], v[158:161], v[216:219], v[64:67]
	s_setprio 0
	s_setprio 1
	v_mfma_f32_16x16x32_bf16 v[28:31], v[162:165], v[178:181], v[28:31]
	v_mfma_f32_16x16x32_bf16 v[24:27], v[170:173], v[178:181], v[24:27]
	v_mfma_f32_16x16x32_bf16 v[20:23], v[162:165], v[186:189], v[20:23]
	v_mfma_f32_16x16x32_bf16 v[16:19], v[170:173], v[186:189], v[16:19]
	v_mfma_f32_16x16x32_bf16 v[12:15], v[162:165], v[204:207], v[12:15]
	v_mfma_f32_16x16x32_bf16 v[8:11], v[170:173], v[204:207], v[8:11]
	v_mfma_f32_16x16x32_bf16 v[4:7], v[162:165], v[212:215], v[4:7]
	v_mfma_f32_16x16x32_bf16 v[0:3], v[170:173], v[212:215], v[0:3]
	v_mfma_f32_16x16x32_bf16 v[28:31], v[166:169], v[182:185], v[28:31]
	v_mfma_f32_16x16x32_bf16 v[24:27], v[174:177], v[182:185], v[24:27]
	v_mfma_f32_16x16x32_bf16 v[20:23], v[166:169], v[200:203], v[20:23]
	v_mfma_f32_16x16x32_bf16 v[16:19], v[174:177], v[200:203], v[16:19]
	v_mfma_f32_16x16x32_bf16 v[12:15], v[166:169], v[208:211], v[12:15]
	v_mfma_f32_16x16x32_bf16 v[8:11], v[174:177], v[208:211], v[8:11]
	v_mfma_f32_16x16x32_bf16 v[4:7], v[166:169], v[216:219], v[4:7]
	v_mfma_f32_16x16x32_bf16 v[0:3], v[174:177], v[216:219], v[0:3]
	s_setprio 0
	s_barrier
	s_add_i32 s53, s53, 2
	s_add_u32 s51, s51, 0x100
	s_addc_u32 s52, s52, 0
	s_add_u32 s24, s24, 0x100
	s_addc_u32 s25, s25, 0
	s_cmp_gt_u32 s53, 29
	s_cbranch_scc0 .LBB0_782
	s_and_b64 vcc, exec, s[8:9]
	s_cbranch_vccz .LBB0_785
	s_barrier

; #define PG8_STAGE(bufoff, gbase, voff) do { _Pragma("unroll") for (int _i = 0; _i < 2; ++_i) \
;         __builtin_amdgcn_global_load_lds((const unsigned*)((const char*)(gbase) + (voff)[_i]), (PG8_LAS unsigned*)(lds + (bufoff) + ldsw + _i * 8192), 16, 0, 0); } while (0)
; #define PG8_LDA(dst, b, h) do { _Pragma("unroll") for (int m = 0; m < 4; ++m) _Pragma("unroll") for (int k = 0; k < 2; ++k) dst[m][k] = *(const PG8_LAS bf16x8*)(lds + PG8_SA(b, h) + aoff + m * 2048 + k * 1024); } while (0)
; #define PG8_LDB(dst, b, h) do { _Pragma("unroll") for (int n = 0; n < 2; ++n) _Pragma("unroll") for (int k = 0; k < 2; ++k) dst[n][k] = *(const PG8_LAS bf16x8*)(lds + PG8_SB(b, h) + boff + n * 2048 + k * 1024); } while (0)
; #define PG8_MMA(ai, bj, At, Bt) do { __builtin_amdgcn_s_setprio(1); _Pragma("unroll") for (int m = 0; m < 4; ++m) _Pragma("unroll") for (int n = 0; n < 2; ++n) _Pragma("unroll") for (int k = 0; k < 2; ++k) \
;         acc[ai][bj][m][n] = __builtin_amdgcn_mfma_f32_16x16x32_bf16(Bt[n][k], At[m][k], acc[ai][bj][m][n], 0, 0, 0); __builtin_amdgcn_s_setprio(0); } while (0)
; #define PG8_WAIT_V(n) asm volatile("s_waitcnt vmcnt(" #n ")" ::: "memory")
; #define PG8_WAIT_L(n) asm volatile("s_waitcnt lgkmcnt(" #n ")" ::: "memory")
; template <class Epi, class Sched, bool ALIGN_EPI = false, bool SP2 = false>
; __device__ __forceinline__ void gemm_phase(PG8_LAS unsigned char* lds, const Gemm g, const Sched& S, const Epi& E, int tid_in) {
;     ...
;             const bool last = (t == nt - 2);
;             const char* a1 = cA + (size_t)(t + 1) * kstep;
;             const char* a2 = last ? nA : cA + (size_t)(t + 2) * kstep; const char* b2 = last ? nB : cB + (size_t)(t + 2) * kstep;
;             const char* a3 = a2 + kstep; const char* b3 = b2 + kstep;
;             if (last && has_next) S.a_ready(nxt);
;             if constexpr (SP2) {
;             PG8_LDB(B0, 0, 0); PG8_LDB(B1, 0, 1); PG8_SCHED; PG8_LDA(At, 0, 0); PG8_STAGE(PG8_SA(1, 1), a1 + hstepA, voffA);
;             PG8_WAIT_V(8); PG8_WAIT_L(0); PG8_BAR; PG8_MMA(0, 0, At, B0); PG8_MMA(0, 1, At, B1); PG8_BAR; PG8_SCHED;
;             PG8_LDA(At, 0, 1); PG8_STAGE(PG8_SB(0, 0), b2, voffB); PG8_STAGE(PG8_SB(0, 1), b2 + hstep, voffB); PG8_STAGE(PG8_SA(0, 0), a2, voffA);
;             PG8_WAIT_V(8); PG8_WAIT_L(0); PG8_BAR; PG8_MMA(1, 0, At, B0); PG8_MMA(1, 1, At, B1); PG8_BAR; PG8_SCHED;
.LBB0_1283:
	s_add_u32 s14, s12, 0xfffc0080
	s_addc_u32 s15, s13, -1
	s_add_i32 s60, 0, 0x10000
	s_cmp_eq_u32 s59, 12
	s_cselect_b32 s27, s19, s15
	s_cselect_b32 s26, s55, s14
	s_cselect_b32 s15, s11, s58
	s_cselect_b32 s14, s56, s57
	s_add_i32 s62, 0, 0x14000
	v_add_u32_e32 v124, s60, v226
	v_add_u32_e32 v140, s62, v226
	ds_read_b128 v[112:115], v124
	ds_read_b128 v[116:119], v124 offset:1024
	ds_read_b128 v[120:123], v124 offset:2048
	ds_read_b128 v[124:127], v124 offset:3072
	ds_read_b128 v[128:131], v140
	ds_read_b128 v[132:135], v140 offset:1024
	ds_read_b128 v[136:139], v140 offset:2048
	ds_read_b128 v[140:143], v140 offset:3072
	s_add_i32 m0, s35, 0xc000
	ds_read_b128 v[144:147], v227
	ds_read_b128 v[148:151], v227 offset:1024
	ds_read_b128 v[152:155], v227 offset:2048
	ds_read_b128 v[156:159], v227 offset:3072
	ds_read_b128 v[176:179], v227 offset:4096
	ds_read_b128 v[180:183], v227 offset:5120
	ds_read_b128 v[208:211], v227 offset:6144
	ds_read_b128 v[212:215], v227 offset:7168
	global_load_lds_dwordx4 v206, s[12:13]
	s_add_i32 m0, s35, 0xe000
	s_nop 0
	global_load_lds_dwordx4 v204, s[12:13]
	s_waitcnt vmcnt(8)
	s_waitcnt lgkmcnt(0)
	s_barrier
	s_setprio 1
	s_waitcnt lgkmcnt(0)
	v_mfma_f32_16x16x32_bf16 v[172:175], v[112:115], v[144:147], v[172:175]
	v_mfma_f32_16x16x32_bf16 v[168:171], v[120:123], v[144:147], v[168:171]
	v_mfma_f32_16x16x32_bf16 v[108:111], v[112:115], v[152:155], v[108:111]
	v_mfma_f32_16x16x32_bf16 v[104:107], v[120:123], v[152:155], v[104:107]
	v_mfma_f32_16x16x32_bf16 v[92:95], v[112:115], v[176:179], v[92:95]
	v_mfma_f32_16x16x32_bf16 v[88:91], v[120:123], v[176:179], v[88:91]
	v_mfma_f32_16x16x32_bf16 v[76:79], v[112:115], v[208:211], v[76:79]
	v_mfma_f32_16x16x32_bf16 v[72:75], v[120:123], v[208:211], v[72:75]
	v_mfma_f32_16x16x32_bf16 v[172:175], v[116:119], v[148:151], v[172:175]
	v_mfma_f32_16x16x32_bf16 v[168:171], v[124:127], v[148:151], v[168:171]
	v_mfma_f32_16x16x32_bf16 v[108:111], v[116:119], v[156:159], v[108:111]
	v_mfma_f32_16x16x32_bf16 v[104:107], v[124:127], v[156:159], v[104:107]
	v_mfma_f32_16x16x32_bf16 v[92:95], v[116:119], v[180:183], v[92:95]
	v_mfma_f32_16x16x32_bf16 v[88:91], v[124:127], v[180:183], v[88:91]
	v_mfma_f32_16x16x32_bf16 v[76:79], v[116:119], v[212:215], v[76:79]
	v_mfma_f32_16x16x32_bf16 v[72:75], v[124:127], v[212:215], v[72:75]
	s_setprio 0
	s_setprio 1
	v_mfma_f32_16x16x32_bf16 v[164:167], v[128:131], v[144:147], v[164:167]
	v_mfma_f32_16x16x32_bf16 v[100:103], v[128:131], v[152:155], v[100:103]
	v_mfma_f32_16x16x32_bf16 v[96:99], v[136:139], v[152:155], v[96:99]
	v_mfma_f32_16x16x32_bf16 v[84:87], v[128:131], v[176:179], v[84:87]
	v_mfma_f32_16x16x32_bf16 v[80:83], v[136:139], v[176:179], v[80:83]
	v_mfma_f32_16x16x32_bf16 v[68:71], v[128:131], v[208:211], v[68:71]
	v_mfma_f32_16x16x32_bf16 v[64:67], v[136:139], v[208:211], v[64:67]
	v_mfma_f32_16x16x32_bf16 v[164:167], v[132:135], v[148:151], v[164:167]
	v_mfma_f32_16x16x32_bf16 v[144:147], v[136:139], v[144:147], v[160:163]
	v_mfma_f32_16x16x32_bf16 v[100:103], v[132:135], v[156:159], v[100:103]
	v_mfma_f32_16x16x32_bf16 v[96:99], v[140:143], v[156:159], v[96:99]
	v_mfma_f32_16x16x32_bf16 v[84:87], v[132:135], v[180:183], v[84:87]
	v_mfma_f32_16x16x32_bf16 v[80:83], v[140:143], v[180:183], v[80:83]
	v_mfma_f32_16x16x32_bf16 v[68:71], v[132:135], v[212:215], v[68:71]
	v_mfma_f32_16x16x32_bf16 v[64:67], v[140:143], v[212:215], v[64:67]
	v_mfma_f32_16x16x32_bf16 v[144:147], v[140:143], v[148:151], v[144:147]
	s_setprio 0
	s_barrier
	s_add_i32 s60, s60, s34
	v_lshl_add_u64 v[228:229], s[14:15], 0, v[190:191]
	s_mov_b32 m0, s60
	ds_read_b128 v[148:151], v227 offset:16384
	ds_read_b128 v[152:155], v227 offset:17408
	ds_read_b128 v[156:159], v227 offset:18432
	ds_read_b128 v[160:163], v227 offset:19456
	ds_read_b128 v[176:179], v227 offset:20480
	ds_read_b128 v[180:183], v227 offset:21504
	ds_read_b128 v[208:211], v227 offset:22528
	ds_read_b128 v[212:215], v227 offset:23552
	global_load_lds_dwordx4 v[228:229], off
	s_add_i32 m0, s60, 0x2000
	s_add_u32 s60, s14, 0x40000
	v_lshl_add_u64 v[230:231], s[14:15], 0, v[184:185]
	s_addc_u32 s61, s15, 0
	s_add_i32 s62, s62, s34
	global_load_lds_dwordx4 v[230:231], off
	s_mov_b32 m0, s62
	v_lshl_add_u64 v[232:233], s[26:27], 0, v[188:189]
	global_load_lds_dwordx4 v190, s[60:61]
	s_add_i32 m0, s62, 0x2000
	v_lshl_add_u64 v[234:235], s[26:27], 0, v[186:187]
	global_load_lds_dwordx4 v184, s[60:61]
	s_mov_b32 m0, s35
	s_nop 0
	global_load_lds_dwordx4 v[232:233], off
	s_mov_b32 m0, s46
	s_nop 0
	global_load_lds_dwordx4 v[234:235], off
	s_waitcnt vmcnt(8)
	s_waitcnt lgkmcnt(0)
	s_barrier
; #define PG8_STAGE(bufoff, gbase, voff) do { _Pragma("unroll") for (int _i = 0; _i < 2; ++_i) \
;         __builtin_amdgcn_global_load_lds((const unsigned*)((const char*)(gbase) + (voff)[_i]), (PG8_LAS unsigned*)(lds + (bufoff) + ldsw + _i * 8192), 16, 0, 0); } while (0)
; #define PG8_LDA(dst, b, h) do { _Pragma("unroll") for (int m = 0; m < 4; ++m) _Pragma("unroll") for (int k = 0; k < 2; ++k) dst[m][k] = *(const PG8_LAS bf16x8*)(lds + PG8_SA(b, h) + aoff + m * 2048 + k * 1024); } while (0)
; #define PG8_LDB(dst, b, h) do { _Pragma("unroll") for (int n = 0; n < 2; ++n) _Pragma("unroll") for (int k = 0; k < 2; ++k) dst[n][k] = *(const PG8_LAS bf16x8*)(lds + PG8_SB(b, h) + boff + n * 2048 + k * 1024); } while (0)
; #define PG8_MMA(ai, bj, At, Bt) do { __builtin_amdgcn_s_setprio(1); _Pragma("unroll") for (int m = 0; m < 4; ++m) _Pragma("unroll") for (int n = 0; n < 2; ++n) _Pragma("unroll") for (int k = 0; k < 2; ++k) \
;         acc[ai][bj][m][n] = __builtin_amdgcn_mfma_f32_16x16x32_bf16(Bt[n][k], At[m][k], acc[ai][bj][m][n], 0, 0, 0); __builtin_amdgcn_s_setprio(0); } while (0)
; #define PG8_WAIT_V(n) asm volatile("s_waitcnt vmcnt(" #n ")" ::: "memory")
; #define PG8_WAIT_L(n) asm volatile("s_waitcnt lgkmcnt(" #n ")" ::: "memory")
; #define PG8_BAR __builtin_amdgcn_s_barrier()
; #define PG8_SCHED __builtin_amdgcn_sched_barrier(0)
; template <class Epi, class Sched, bool ALIGN_EPI = false, bool SP2 = false>
; __device__ __forceinline__ void gemm_phase(PG8_LAS unsigned char* lds, const Gemm g, const Sched& S, const Epi& E, int tid_in) {
;     ...
;             PG8_WAIT_V(8); PG8_WAIT_L(0); PG8_BAR; PG8_MMA(1, 0, At, B0); PG8_MMA(1, 1, At, B1); PG8_BAR; PG8_SCHED;
;             PG8_LDB(B0, 1, 0); PG8_LDB(B1, 1, 1); PG8_SCHED; PG8_LDA(At, 1, 0); PG8_STAGE(PG8_SA(0, 1), a2 + hstepA, voffA);
;             PG8_WAIT_V(8); PG8_WAIT_L(0); PG8_BAR; PG8_MMA(0, 0, At, B0); PG8_MMA(0, 1, At, B1); PG8_BAR; PG8_SCHED;
	s_setprio 1
	s_waitcnt lgkmcnt(0)
	v_mfma_f32_16x16x32_bf16 v[60:63], v[112:115], v[148:151], v[60:63]
	v_mfma_f32_16x16x32_bf16 v[56:59], v[120:123], v[148:151], v[56:59]
	v_mfma_f32_16x16x32_bf16 v[44:47], v[112:115], v[156:159], v[44:47]
	v_mfma_f32_16x16x32_bf16 v[40:43], v[120:123], v[156:159], v[40:43]
	v_mfma_f32_16x16x32_bf16 v[28:31], v[112:115], v[176:179], v[28:31]
	v_mfma_f32_16x16x32_bf16 v[24:27], v[120:123], v[176:179], v[24:27]
	v_mfma_f32_16x16x32_bf16 v[12:15], v[112:115], v[208:211], v[12:15]
	v_mfma_f32_16x16x32_bf16 v[8:11], v[120:123], v[208:211], v[8:11]
	v_mfma_f32_16x16x32_bf16 v[60:63], v[116:119], v[152:155], v[60:63]
	v_mfma_f32_16x16x32_bf16 v[56:59], v[124:127], v[152:155], v[56:59]
	v_mfma_f32_16x16x32_bf16 v[44:47], v[116:119], v[160:163], v[44:47]
	v_mfma_f32_16x16x32_bf16 v[40:43], v[124:127], v[160:163], v[40:43]
	v_mfma_f32_16x16x32_bf16 v[28:31], v[116:119], v[180:183], v[28:31]
	v_mfma_f32_16x16x32_bf16 v[24:27], v[124:127], v[180:183], v[24:27]
	v_mfma_f32_16x16x32_bf16 v[12:15], v[116:119], v[212:215], v[12:15]
	v_mfma_f32_16x16x32_bf16 v[8:11], v[124:127], v[212:215], v[8:11]
	s_setprio 0
	s_setprio 1
	v_mfma_f32_16x16x32_bf16 v[52:55], v[128:131], v[148:151], v[52:55]
	v_mfma_f32_16x16x32_bf16 v[48:51], v[136:139], v[148:151], v[48:51]
	v_mfma_f32_16x16x32_bf16 v[36:39], v[128:131], v[156:159], v[36:39]
	v_mfma_f32_16x16x32_bf16 v[32:35], v[136:139], v[156:159], v[32:35]
	v_mfma_f32_16x16x32_bf16 v[20:23], v[128:131], v[176:179], v[20:23]
	v_mfma_f32_16x16x32_bf16 v[16:19], v[136:139], v[176:179], v[16:19]
	v_mfma_f32_16x16x32_bf16 v[4:7], v[128:131], v[208:211], v[4:7]
	v_mfma_f32_16x16x32_bf16 v[0:3], v[136:139], v[208:211], v[0:3]
	v_mfma_f32_16x16x32_bf16 v[52:55], v[132:135], v[152:155], v[52:55]
	v_mfma_f32_16x16x32_bf16 v[48:51], v[140:143], v[152:155], v[48:51]
	v_mfma_f32_16x16x32_bf16 v[36:39], v[132:135], v[160:163], v[36:39]
	v_mfma_f32_16x16x32_bf16 v[32:35], v[140:143], v[160:163], v[32:35]
	v_mfma_f32_16x16x32_bf16 v[20:23], v[132:135], v[180:183], v[20:23]
	v_mfma_f32_16x16x32_bf16 v[16:19], v[140:143], v[180:183], v[16:19]
	v_mfma_f32_16x16x32_bf16 v[4:7], v[132:135], v[212:215], v[4:7]
	v_mfma_f32_16x16x32_bf16 v[0:3], v[140:143], v[212:215], v[0:3]
	s_setprio 0
	s_barrier
	s_add_i32 s60, 0, 0x18000
	s_add_i32 s61, 0, 0x1c000
	v_add_u32_e32 v124, s60, v226
	v_add_u32_e32 v140, s61, v226
	ds_read_b128 v[112:115], v124
	ds_read_b128 v[116:119], v124 offset:1024
	ds_read_b128 v[120:123], v124 offset:2048
	ds_read_b128 v[124:127], v124 offset:3072
	ds_read_b128 v[128:131], v140
	ds_read_b128 v[132:135], v140 offset:1024
	ds_read_b128 v[136:139], v140 offset:2048
	ds_read_b128 v[140:143], v140 offset:3072
	s_add_u32 s26, s26, 0x40000
	s_addc_u32 s27, s27, 0
	s_mov_b32 m0, s47
	ds_read_b128 v[148:151], v227 offset:32768
	ds_read_b128 v[152:155], v227 offset:33792
	ds_read_b128 v[156:159], v227 offset:34816
	ds_read_b128 v[176:179], v227 offset:35840
	ds_read_b128 v[180:183], v227 offset:36864
	ds_read_b128 v[208:211], v227 offset:37888
	ds_read_b128 v[212:215], v227 offset:38912
	ds_read_b128 v[216:219], v227 offset:39936
	global_load_lds_dwordx4 v188, s[26:27]
	s_mov_b32 m0, s49
	s_nop 0
	global_load_lds_dwordx4 v186, s[26:27]
	s_waitcnt vmcnt(8)
	s_waitcnt lgkmcnt(0)
	s_barrier
	s_setprio 1
	s_waitcnt lgkmcnt(0)
	v_mfma_f32_16x16x32_bf16 v[160:163], v[112:115], v[148:151], v[172:175]
	v_mfma_f32_16x16x32_bf16 v[172:175], v[116:119], v[152:155], v[160:163]
	v_mfma_f32_16x16x32_bf16 v[160:163], v[120:123], v[148:151], v[168:171]
	v_mfma_f32_16x16x32_bf16 v[108:111], v[112:115], v[156:159], v[108:111]
	v_mfma_f32_16x16x32_bf16 v[104:107], v[120:123], v[156:159], v[104:107]
	v_mfma_f32_16x16x32_bf16 v[92:95], v[112:115], v[180:183], v[92:95]
	v_mfma_f32_16x16x32_bf16 v[88:91], v[120:123], v[180:183], v[88:91]
	v_mfma_f32_16x16x32_bf16 v[76:79], v[112:115], v[212:215], v[76:79]
	v_mfma_f32_16x16x32_bf16 v[72:75], v[120:123], v[212:215], v[72:75]
	v_mfma_f32_16x16x32_bf16 v[168:171], v[124:127], v[152:155], v[160:163]
	v_mfma_f32_16x16x32_bf16 v[108:111], v[116:119], v[176:179], v[108:111]
	v_mfma_f32_16x16x32_bf16 v[104:107], v[124:127], v[176:179], v[104:107]
	v_mfma_f32_16x16x32_bf16 v[92:95], v[116:119], v[208:211], v[92:95]
	v_mfma_f32_16x16x32_bf16 v[88:91], v[124:127], v[208:211], v[88:91]
	v_mfma_f32_16x16x32_bf16 v[76:79], v[116:119], v[216:219], v[76:79]
	v_mfma_f32_16x16x32_bf16 v[72:75], v[124:127], v[216:219], v[72:75]
	s_setprio 0
	s_setprio 1
	v_mfma_f32_16x16x32_bf16 v[160:163], v[128:131], v[148:151], v[164:167]
	v_mfma_f32_16x16x32_bf16 v[144:147], v[136:139], v[148:151], v[144:147]
	v_mfma_f32_16x16x32_bf16 v[100:103], v[128:131], v[156:159], v[100:103]
	v_mfma_f32_16x16x32_bf16 v[96:99], v[136:139], v[156:159], v[96:99]
	v_mfma_f32_16x16x32_bf16 v[84:87], v[128:131], v[180:183], v[84:87]
	v_mfma_f32_16x16x32_bf16 v[80:83], v[136:139], v[180:183], v[80:83]
	v_mfma_f32_16x16x32_bf16 v[68:71], v[128:131], v[212:215], v[68:71]
	v_mfma_f32_16x16x32_bf16 v[64:67], v[136:139], v[212:215], v[64:67]
	v_mfma_f32_16x16x32_bf16 v[164:167], v[132:135], v[152:155], v[160:163]
	v_mfma_f32_16x16x32_bf16 v[160:163], v[140:143], v[152:155], v[144:147]
	v_mfma_f32_16x16x32_bf16 v[100:103], v[132:135], v[176:179], v[100:103]
	v_mfma_f32_16x16x32_bf16 v[96:99], v[140:143], v[176:179], v[96:99]
	v_mfma_f32_16x16x32_bf16 v[84:87], v[132:135], v[208:211], v[84:87]
	v_mfma_f32_16x16x32_bf16 v[80:83], v[140:143], v[208:211], v[80:83]
	v_mfma_f32_16x16x32_bf16 v[68:71], v[132:135], v[216:219], v[68:71]
	v_mfma_f32_16x16x32_bf16 v[64:67], v[140:143], v[216:219], v[64:67]
	s_setprio 0
	s_barrier
; #define PG8_STAGE(bufoff, gbase, voff) do { _Pragma("unroll") for (int _i = 0; _i < 2; ++_i) \
;         __builtin_amdgcn_global_load_lds((const unsigned*)((const char*)(gbase) + (voff)[_i]), (PG8_LAS unsigned*)(lds + (bufoff) + ldsw + _i * 8192), 16, 0, 0); } while (0)
; #define PG8_LDA(dst, b, h) do { _Pragma("unroll") for (int m = 0; m < 4; ++m) _Pragma("unroll") for (int k = 0; k < 2; ++k) dst[m][k] = *(const PG8_LAS bf16x8*)(lds + PG8_SA(b, h) + aoff + m * 2048 + k * 1024); } while (0)
; #define PG8_MMA(ai, bj, At, Bt) do { __builtin_amdgcn_s_setprio(1); _Pragma("unroll") for (int m = 0; m < 4; ++m) _Pragma("unroll") for (int n = 0; n < 2; ++n) _Pragma("unroll") for (int k = 0; k < 2; ++k) \
;         acc[ai][bj][m][n] = __builtin_amdgcn_mfma_f32_16x16x32_bf16(Bt[n][k], At[m][k], acc[ai][bj][m][n], 0, 0, 0); __builtin_amdgcn_s_setprio(0); } while (0)
; #define PG8_WAIT_V(n) asm volatile("s_waitcnt vmcnt(" #n ")" ::: "memory")
; #define PG8_WAIT_L(n) asm volatile("s_waitcnt lgkmcnt(" #n ")" ::: "memory")
; #define PG8_BAR __builtin_amdgcn_s_barrier()
; #define PG8_SCHED __builtin_amdgcn_sched_barrier(0)
; template <class Epi, class Sched, bool ALIGN_EPI = false, bool SP2 = false>
; __device__ __forceinline__ void gemm_phase(PG8_LAS unsigned char* lds, const Gemm g, const Sched& S, const Epi& E, int tid_in) {
;     ...
;             PG8_LDA(At, 1, 1); PG8_STAGE(PG8_SB(1, 0), b3, voffB); PG8_STAGE(PG8_SB(1, 1), b3 + hstep, voffB); PG8_STAGE(PG8_SA(1, 0), a3, voffA);
;             PG8_WAIT_V(8); PG8_WAIT_L(0); PG8_BAR; PG8_MMA(1, 0, At, B0); PG8_MMA(1, 1, At, B1); PG8_BAR; PG8_SCHED;
	s_add_i32 s26, s60, s34
	v_lshl_add_u64 v[216:217], v[228:229], 0, s[0:1]
	s_mov_b32 m0, s26
	ds_read_b128 v[144:147], v227 offset:49152
	ds_read_b128 v[148:151], v227 offset:50176
	ds_read_b128 v[152:155], v227 offset:51200
	ds_read_b128 v[156:159], v227 offset:52224
	ds_read_b128 v[176:179], v227 offset:53248
	ds_read_b128 v[180:183], v227 offset:54272
	ds_read_b128 v[208:211], v227 offset:55296
	ds_read_b128 v[212:215], v227 offset:56320
	global_load_lds_dwordx4 v[216:217], off
	s_add_i32 m0, s26, 0x2000
	s_add_u32 s14, s14, 0x40080
	v_lshl_add_u64 v[216:217], v[230:231], 0, s[0:1]
	s_addc_u32 s15, s15, 0
	s_add_i32 s26, s61, s34
	global_load_lds_dwordx4 v[216:217], off
	s_mov_b32 m0, s26
	s_nop 0
	global_load_lds_dwordx4 v190, s[14:15]
	s_add_i32 m0, s26, 0x2000
	s_nop 0
	global_load_lds_dwordx4 v184, s[14:15]
	v_lshl_add_u64 v[216:217], v[232:233], 0, s[0:1]
	s_mov_b32 m0, s52
	s_nop 0
	global_load_lds_dwordx4 v[216:217], off
	v_lshl_add_u64 v[216:217], v[234:235], 0, s[0:1]
	s_mov_b32 m0, s53
	s_nop 0
	global_load_lds_dwordx4 v[216:217], off
	s_waitcnt vmcnt(8)
	s_waitcnt lgkmcnt(0)
	s_barrier
	s_setprio 1
	s_waitcnt lgkmcnt(0)
	v_mfma_f32_16x16x32_bf16 v[60:63], v[112:115], v[144:147], v[60:63]
	v_mfma_f32_16x16x32_bf16 v[56:59], v[120:123], v[144:147], v[56:59]
	v_mfma_f32_16x16x32_bf16 v[44:47], v[112:115], v[152:155], v[44:47]
	v_mfma_f32_16x16x32_bf16 v[40:43], v[120:123], v[152:155], v[40:43]
	v_mfma_f32_16x16x32_bf16 v[28:31], v[112:115], v[176:179], v[28:31]
	v_mfma_f32_16x16x32_bf16 v[24:27], v[120:123], v[176:179], v[24:27]
	v_mfma_f32_16x16x32_bf16 v[12:15], v[112:115], v[208:211], v[12:15]
	v_mfma_f32_16x16x32_bf16 v[8:11], v[120:123], v[208:211], v[8:11]
	v_mfma_f32_16x16x32_bf16 v[60:63], v[116:119], v[148:151], v[60:63]
	v_mfma_f32_16x16x32_bf16 v[56:59], v[124:127], v[148:151], v[56:59]
	v_mfma_f32_16x16x32_bf16 v[44:47], v[116:119], v[156:159], v[44:47]
	v_mfma_f32_16x16x32_bf16 v[40:43], v[124:127], v[156:159], v[40:43]
	v_mfma_f32_16x16x32_bf16 v[28:31], v[116:119], v[180:183], v[28:31]
	v_mfma_f32_16x16x32_bf16 v[24:27], v[124:127], v[180:183], v[24:27]
	v_mfma_f32_16x16x32_bf16 v[12:15], v[116:119], v[212:215], v[12:15]
	v_mfma_f32_16x16x32_bf16 v[8:11], v[124:127], v[212:215], v[8:11]
	s_setprio 0
	s_setprio 1
	v_mfma_f32_16x16x32_bf16 v[52:55], v[128:131], v[144:147], v[52:55]
	v_mfma_f32_16x16x32_bf16 v[48:51], v[136:139], v[144:147], v[48:51]
	v_mfma_f32_16x16x32_bf16 v[36:39], v[128:131], v[152:155], v[36:39]
	v_mfma_f32_16x16x32_bf16 v[32:35], v[136:139], v[152:155], v[32:35]
	v_mfma_f32_16x16x32_bf16 v[20:23], v[128:131], v[176:179], v[20:23]
	v_mfma_f32_16x16x32_bf16 v[16:19], v[136:139], v[176:179], v[16:19]
	v_mfma_f32_16x16x32_bf16 v[4:7], v[128:131], v[208:211], v[4:7]
	v_mfma_f32_16x16x32_bf16 v[0:3], v[136:139], v[208:211], v[0:3]
	v_mfma_f32_16x16x32_bf16 v[52:55], v[132:135], v[148:151], v[52:55]
	v_mfma_f32_16x16x32_bf16 v[48:51], v[140:143], v[148:151], v[48:51]
	v_mfma_f32_16x16x32_bf16 v[36:39], v[132:135], v[156:159], v[36:39]
	v_mfma_f32_16x16x32_bf16 v[32:35], v[140:143], v[156:159], v[32:35]
	v_mfma_f32_16x16x32_bf16 v[20:23], v[132:135], v[180:183], v[20:23]
	v_mfma_f32_16x16x32_bf16 v[16:19], v[140:143], v[180:183], v[16:19]
	v_mfma_f32_16x16x32_bf16 v[4:7], v[132:135], v[212:215], v[4:7]
	v_mfma_f32_16x16x32_bf16 v[0:3], v[140:143], v[212:215], v[0:3]
	s_setprio 0
	s_barrier
	s_add_i32 s59, s59, 2
	s_add_u32 s57, s57, 0x100
	s_addc_u32 s58, s58, 0
	s_add_u32 s12, s12, 0x100
	s_addc_u32 s13, s13, 0
	s_cmp_gt_u32 s59, 13
	s_cbranch_scc0 .LBB0_1283
	s_and_b64 vcc, exec, s[8:9]
	s_cbranch_vccz .LBB0_1286
	s_barrier

; #define PG8_STAGE(bufoff, gbase, voff) do { _Pragma("unroll") for (int _i = 0; _i < 2; ++_i) \
;         __builtin_amdgcn_global_load_lds((const unsigned*)((const char*)(gbase) + (voff)[_i]), (PG8_LAS unsigned*)(lds + (bufoff) + ldsw + _i * 8192), 16, 0, 0); } while (0)
; #define PG8_LDA(dst, b, h) do { _Pragma("unroll") for (int m = 0; m < 4; ++m) _Pragma("unroll") for (int k = 0; k < 2; ++k) dst[m][k] = *(const PG8_LAS bf16x8*)(lds + PG8_SA(b, h) + aoff + m * 2048 + k * 1024); } while (0)
; #define PG8_LDB(dst, b, h) do { _Pragma("unroll") for (int n = 0; n < 2; ++n) _Pragma("unroll") for (int k = 0; k < 2; ++k) dst[n][k] = *(const PG8_LAS bf16x8*)(lds + PG8_SB(b, h) + boff + n * 2048 + k * 1024); } while (0)
; #define PG8_MMA(ai, bj, At, Bt) do { __builtin_amdgcn_s_setprio(1); _Pragma("unroll") for (int m = 0; m < 4; ++m) _Pragma("unroll") for (int n = 0; n < 2; ++n) _Pragma("unroll") for (int k = 0; k < 2; ++k) \
;         acc[ai][bj][m][n] = __builtin_amdgcn_mfma_f32_16x16x32_bf16(Bt[n][k], At[m][k], acc[ai][bj][m][n], 0, 0, 0); __builtin_amdgcn_s_setprio(0); } while (0)
; #define PG8_WAIT_V(n) asm volatile("s_waitcnt vmcnt(" #n ")" ::: "memory")
; #define PG8_WAIT_L(n) asm volatile("s_waitcnt lgkmcnt(" #n ")" ::: "memory")
; template <class Epi, class Sched, bool ALIGN_EPI = false, bool SP2 = false>
; __device__ __forceinline__ void gemm_phase(PG8_LAS unsigned char* lds, const Gemm g, const Sched& S, const Epi& E, int tid_in) {
;     ...
;             const bool last = (t == nt - 2);
;             const char* a1 = cA + (size_t)(t + 1) * kstep;
;             const char* a2 = last ? nA : cA + (size_t)(t + 2) * kstep; const char* b2 = last ? nB : cB + (size_t)(t + 2) * kstep;
;             const char* a3 = a2 + kstep; const char* b3 = b2 + kstep;
;             if (last && has_next) S.a_ready(nxt);
;             if constexpr (SP2) {
;             PG8_LDB(B0, 0, 0); PG8_LDB(B1, 0, 1); PG8_SCHED; PG8_LDA(At, 0, 0); PG8_STAGE(PG8_SA(1, 1), a1 + hstepA, voffA);
;             PG8_WAIT_V(8); PG8_WAIT_L(0); PG8_BAR; PG8_MMA(0, 0, At, B0); PG8_MMA(0, 1, At, B1); PG8_BAR; PG8_SCHED;
;             PG8_LDA(At, 0, 1); PG8_STAGE(PG8_SB(0, 0), b2, voffB); PG8_STAGE(PG8_SB(0, 1), b2 + hstep, voffB); PG8_STAGE(PG8_SA(0, 0), a2, voffA);
;             PG8_WAIT_V(8); PG8_WAIT_L(0); PG8_BAR; PG8_MMA(1, 0, At, B0); PG8_MMA(1, 1, At, B1); PG8_BAR; PG8_SCHED;
.LBB0_1385:
	s_add_u32 s12, s2, 0xfffc0080
	s_addc_u32 s13, s3, -1
	s_add_i32 s58, 0, 0x10000
	s_cmp_eq_u32 s57, 12
	s_cselect_b32 s15, s21, s13
	s_cselect_b32 s14, s53, s12
	v_add_u32_e32 v140, s58, v145
	s_cselect_b32 s13, s19, s56
	s_cselect_b32 s12, s54, s55
	s_add_i32 s60, 0, 0x14000
	ds_read_b128 v[148:151], v140
	ds_read_b128 v[152:155], v140 offset:1024
	ds_read_b128 v[156:159], v140 offset:2048
	ds_read_b128 v[160:163], v140 offset:3072
	v_add_u32_e32 v140, s60, v145
	ds_read_b128 v[164:167], v140
	ds_read_b128 v[168:171], v140 offset:1024
	ds_read_b128 v[172:175], v140 offset:2048
	ds_read_b128 v[176:179], v140 offset:3072
	s_add_i32 m0, s45, 0xc000
	ds_read_b128 v[180:183], v146
	ds_read_b128 v[184:187], v146 offset:1024
	ds_read_b128 v[200:203], v146 offset:2048
	ds_read_b128 v[204:207], v146 offset:3072
	ds_read_b128 v[208:211], v146 offset:4096
	ds_read_b128 v[212:215], v146 offset:5120
	ds_read_b128 v[216:219], v146 offset:6144
	ds_read_b128 v[226:229], v146 offset:7168
	global_load_lds_dwordx4 v138, s[2:3]
	s_add_i32 m0, s45, 0xe000
	s_nop 0
	global_load_lds_dwordx4 v136, s[2:3]
	s_waitcnt vmcnt(8)
	s_waitcnt lgkmcnt(0)
	s_barrier
	s_setprio 1
	s_waitcnt lgkmcnt(0)
	v_mfma_f32_16x16x32_bf16 v[124:127], v[148:151], v[180:183], v[124:127]
	v_mfma_f32_16x16x32_bf16 v[116:119], v[156:159], v[180:183], v[116:119]
	v_mfma_f32_16x16x32_bf16 v[108:111], v[148:151], v[200:203], v[108:111]
	v_mfma_f32_16x16x32_bf16 v[100:103], v[156:159], v[200:203], v[100:103]
	v_mfma_f32_16x16x32_bf16 v[92:95], v[148:151], v[208:211], v[92:95]
	v_mfma_f32_16x16x32_bf16 v[84:87], v[156:159], v[208:211], v[84:87]
	v_mfma_f32_16x16x32_bf16 v[76:79], v[148:151], v[216:219], v[76:79]
	v_mfma_f32_16x16x32_bf16 v[68:71], v[156:159], v[216:219], v[68:71]
	v_mfma_f32_16x16x32_bf16 v[124:127], v[152:155], v[184:187], v[124:127]
	v_mfma_f32_16x16x32_bf16 v[116:119], v[160:163], v[184:187], v[116:119]
	v_mfma_f32_16x16x32_bf16 v[108:111], v[152:155], v[204:207], v[108:111]
	v_mfma_f32_16x16x32_bf16 v[100:103], v[160:163], v[204:207], v[100:103]
	v_mfma_f32_16x16x32_bf16 v[92:95], v[152:155], v[212:215], v[92:95]
	v_mfma_f32_16x16x32_bf16 v[84:87], v[160:163], v[212:215], v[84:87]
	v_mfma_f32_16x16x32_bf16 v[76:79], v[152:155], v[226:229], v[76:79]
	v_mfma_f32_16x16x32_bf16 v[68:71], v[160:163], v[226:229], v[68:71]
	s_setprio 0
	s_setprio 1
	v_mfma_f32_16x16x32_bf16 v[120:123], v[164:167], v[180:183], v[120:123]
	v_mfma_f32_16x16x32_bf16 v[112:115], v[172:175], v[180:183], v[112:115]
	v_mfma_f32_16x16x32_bf16 v[104:107], v[164:167], v[200:203], v[104:107]
	v_mfma_f32_16x16x32_bf16 v[96:99], v[172:175], v[200:203], v[96:99]
	v_mfma_f32_16x16x32_bf16 v[88:91], v[164:167], v[208:211], v[88:91]
	v_mfma_f32_16x16x32_bf16 v[80:83], v[172:175], v[208:211], v[80:83]
	v_mfma_f32_16x16x32_bf16 v[72:75], v[164:167], v[216:219], v[72:75]
	v_mfma_f32_16x16x32_bf16 v[64:67], v[172:175], v[216:219], v[64:67]
	v_mfma_f32_16x16x32_bf16 v[120:123], v[168:171], v[184:187], v[120:123]
	v_mfma_f32_16x16x32_bf16 v[112:115], v[176:179], v[184:187], v[112:115]
	v_mfma_f32_16x16x32_bf16 v[104:107], v[168:171], v[204:207], v[104:107]
	v_mfma_f32_16x16x32_bf16 v[96:99], v[176:179], v[204:207], v[96:99]
	v_mfma_f32_16x16x32_bf16 v[88:91], v[168:171], v[212:215], v[88:91]
	v_mfma_f32_16x16x32_bf16 v[80:83], v[176:179], v[212:215], v[80:83]
	v_mfma_f32_16x16x32_bf16 v[72:75], v[168:171], v[226:229], v[72:75]
	v_mfma_f32_16x16x32_bf16 v[64:67], v[176:179], v[226:229], v[64:67]
	s_setprio 0
	s_barrier
	s_add_i32 s58, s58, s44
	v_lshl_add_u64 v[140:141], s[12:13], 0, v[132:133]
	s_mov_b32 m0, s58
	ds_read_b128 v[180:183], v146 offset:16384
	ds_read_b128 v[184:187], v146 offset:17408
	ds_read_b128 v[200:203], v146 offset:18432
	ds_read_b128 v[204:207], v146 offset:19456
	ds_read_b128 v[208:211], v146 offset:20480
	ds_read_b128 v[212:215], v146 offset:21504
	ds_read_b128 v[216:219], v146 offset:22528
	ds_read_b128 v[226:229], v146 offset:23552
	global_load_lds_dwordx4 v[140:141], off
	s_add_i32 m0, s58, 0x2000
	s_add_u32 s58, s12, 0x40000
	v_lshl_add_u64 v[188:189], s[12:13], 0, v[128:129]
	s_addc_u32 s59, s13, 0
	s_add_i32 s60, s60, s44
	global_load_lds_dwordx4 v[188:189], off
	s_mov_b32 m0, s60
	v_lshl_add_u64 v[232:233], s[14:15], 0, v[130:131]
	global_load_lds_dwordx4 v132, s[58:59]
	s_add_i32 m0, s60, 0x2000
	s_nop 0
	global_load_lds_dwordx4 v128, s[58:59]
	v_lshl_add_u64 v[230:231], s[14:15], 0, v[134:135]
	s_mov_b32 m0, s45
	s_nop 0
	global_load_lds_dwordx4 v[230:231], off
	s_mov_b32 m0, s46
	s_nop 0
	global_load_lds_dwordx4 v[232:233], off
	s_waitcnt vmcnt(8)
	s_waitcnt lgkmcnt(0)
	s_barrier
; #define PG8_STAGE(bufoff, gbase, voff) do { _Pragma("unroll") for (int _i = 0; _i < 2; ++_i) \
;         __builtin_amdgcn_global_load_lds((const unsigned*)((const char*)(gbase) + (voff)[_i]), (PG8_LAS unsigned*)(lds + (bufoff) + ldsw + _i * 8192), 16, 0, 0); } while (0)
; #define PG8_LDA(dst, b, h) do { _Pragma("unroll") for (int m = 0; m < 4; ++m) _Pragma("unroll") for (int k = 0; k < 2; ++k) dst[m][k] = *(const PG8_LAS bf16x8*)(lds + PG8_SA(b, h) + aoff + m * 2048 + k * 1024); } while (0)
; #define PG8_LDB(dst, b, h) do { _Pragma("unroll") for (int n = 0; n < 2; ++n) _Pragma("unroll") for (int k = 0; k < 2; ++k) dst[n][k] = *(const PG8_LAS bf16x8*)(lds + PG8_SB(b, h) + boff + n * 2048 + k * 1024); } while (0)
; #define PG8_MMA(ai, bj, At, Bt) do { __builtin_amdgcn_s_setprio(1); _Pragma("unroll") for (int m = 0; m < 4; ++m) _Pragma("unroll") for (int n = 0; n < 2; ++n) _Pragma("unroll") for (int k = 0; k < 2; ++k) \
;         acc[ai][bj][m][n] = __builtin_amdgcn_mfma_f32_16x16x32_bf16(Bt[n][k], At[m][k], acc[ai][bj][m][n], 0, 0, 0); __builtin_amdgcn_s_setprio(0); } while (0)
; #define PG8_WAIT_V(n) asm volatile("s_waitcnt vmcnt(" #n ")" ::: "memory")
; #define PG8_WAIT_L(n) asm volatile("s_waitcnt lgkmcnt(" #n ")" ::: "memory")
; #define PG8_BAR __builtin_amdgcn_s_barrier()
; #define PG8_SCHED __builtin_amdgcn_sched_barrier(0)
; template <class Epi, class Sched, bool ALIGN_EPI = false, bool SP2 = false>
; __device__ __forceinline__ void gemm_phase(PG8_LAS unsigned char* lds, const Gemm g, const Sched& S, const Epi& E, int tid_in) {
;     ...
;             PG8_WAIT_V(8); PG8_WAIT_L(0); PG8_BAR; PG8_MMA(1, 0, At, B0); PG8_MMA(1, 1, At, B1); PG8_BAR; PG8_SCHED;
;             PG8_LDB(B0, 1, 0); PG8_LDB(B1, 1, 1); PG8_SCHED; PG8_LDA(At, 1, 0); PG8_STAGE(PG8_SA(0, 1), a2 + hstepA, voffA);
;             PG8_WAIT_V(8); PG8_WAIT_L(0); PG8_BAR; PG8_MMA(0, 0, At, B0); PG8_MMA(0, 1, At, B1); PG8_BAR; PG8_SCHED;
	s_setprio 1
	s_waitcnt lgkmcnt(0)
	v_mfma_f32_16x16x32_bf16 v[60:63], v[148:151], v[180:183], v[60:63]
	v_mfma_f32_16x16x32_bf16 v[52:55], v[156:159], v[180:183], v[52:55]
	v_mfma_f32_16x16x32_bf16 v[44:47], v[148:151], v[200:203], v[44:47]
	v_mfma_f32_16x16x32_bf16 v[36:39], v[156:159], v[200:203], v[36:39]
	v_mfma_f32_16x16x32_bf16 v[28:31], v[148:151], v[208:211], v[28:31]
	v_mfma_f32_16x16x32_bf16 v[20:23], v[156:159], v[208:211], v[20:23]
	v_mfma_f32_16x16x32_bf16 v[12:15], v[148:151], v[216:219], v[12:15]
	v_mfma_f32_16x16x32_bf16 v[4:7], v[156:159], v[216:219], v[4:7]
	v_mfma_f32_16x16x32_bf16 v[60:63], v[152:155], v[184:187], v[60:63]
	v_mfma_f32_16x16x32_bf16 v[52:55], v[160:163], v[184:187], v[52:55]
	v_mfma_f32_16x16x32_bf16 v[44:47], v[152:155], v[204:207], v[44:47]
	v_mfma_f32_16x16x32_bf16 v[36:39], v[160:163], v[204:207], v[36:39]
	v_mfma_f32_16x16x32_bf16 v[28:31], v[152:155], v[212:215], v[28:31]
	v_mfma_f32_16x16x32_bf16 v[20:23], v[160:163], v[212:215], v[20:23]
	v_mfma_f32_16x16x32_bf16 v[12:15], v[152:155], v[226:229], v[12:15]
	v_mfma_f32_16x16x32_bf16 v[4:7], v[160:163], v[226:229], v[4:7]
	s_setprio 0
	s_setprio 1
	v_mfma_f32_16x16x32_bf16 v[56:59], v[164:167], v[180:183], v[56:59]
	v_mfma_f32_16x16x32_bf16 v[48:51], v[172:175], v[180:183], v[48:51]
	v_mfma_f32_16x16x32_bf16 v[40:43], v[164:167], v[200:203], v[40:43]
	v_mfma_f32_16x16x32_bf16 v[32:35], v[172:175], v[200:203], v[32:35]
	v_mfma_f32_16x16x32_bf16 v[24:27], v[164:167], v[208:211], v[24:27]
	v_mfma_f32_16x16x32_bf16 v[16:19], v[172:175], v[208:211], v[16:19]
	v_mfma_f32_16x16x32_bf16 v[8:11], v[164:167], v[216:219], v[8:11]
	v_mfma_f32_16x16x32_bf16 v[0:3], v[172:175], v[216:219], v[0:3]
	v_mfma_f32_16x16x32_bf16 v[56:59], v[168:171], v[184:187], v[56:59]
	v_mfma_f32_16x16x32_bf16 v[48:51], v[176:179], v[184:187], v[48:51]
	v_mfma_f32_16x16x32_bf16 v[40:43], v[168:171], v[204:207], v[40:43]
	v_mfma_f32_16x16x32_bf16 v[32:35], v[176:179], v[204:207], v[32:35]
	v_mfma_f32_16x16x32_bf16 v[24:27], v[168:171], v[212:215], v[24:27]
	v_mfma_f32_16x16x32_bf16 v[16:19], v[176:179], v[212:215], v[16:19]
	v_mfma_f32_16x16x32_bf16 v[8:11], v[168:171], v[226:229], v[8:11]
	v_mfma_f32_16x16x32_bf16 v[0:3], v[176:179], v[226:229], v[0:3]
	s_setprio 0
	s_barrier
	s_add_i32 s58, 0, 0x18000
	v_add_u32_e32 v142, s58, v145
	s_add_i32 s59, 0, 0x1c000
	ds_read_b128 v[148:151], v142
	ds_read_b128 v[152:155], v142 offset:1024
	ds_read_b128 v[156:159], v142 offset:2048
	ds_read_b128 v[160:163], v142 offset:3072
	v_add_u32_e32 v142, s59, v145
	ds_read_b128 v[164:167], v142
	ds_read_b128 v[168:171], v142 offset:1024
	ds_read_b128 v[172:175], v142 offset:2048
	ds_read_b128 v[176:179], v142 offset:3072
	s_add_u32 s14, s14, 0x40000
	s_addc_u32 s15, s15, 0
	s_mov_b32 m0, s47
	ds_read_b128 v[180:183], v146 offset:32768
	ds_read_b128 v[184:187], v146 offset:33792
	ds_read_b128 v[200:203], v146 offset:34816
	ds_read_b128 v[204:207], v146 offset:35840
	ds_read_b128 v[208:211], v146 offset:36864
	ds_read_b128 v[212:215], v146 offset:37888
	ds_read_b128 v[216:219], v146 offset:38912
	ds_read_b128 v[226:229], v146 offset:39936
	global_load_lds_dwordx4 v134, s[14:15]
	s_mov_b32 m0, s49
	s_nop 0
	global_load_lds_dwordx4 v130, s[14:15]
	s_waitcnt vmcnt(8)
	s_waitcnt lgkmcnt(0)
	s_barrier
	s_setprio 1
	s_waitcnt lgkmcnt(0)
	v_mfma_f32_16x16x32_bf16 v[124:127], v[148:151], v[180:183], v[124:127]
	v_mfma_f32_16x16x32_bf16 v[116:119], v[156:159], v[180:183], v[116:119]
	v_mfma_f32_16x16x32_bf16 v[108:111], v[148:151], v[200:203], v[108:111]
	v_mfma_f32_16x16x32_bf16 v[100:103], v[156:159], v[200:203], v[100:103]
	v_mfma_f32_16x16x32_bf16 v[92:95], v[148:151], v[208:211], v[92:95]
	v_mfma_f32_16x16x32_bf16 v[84:87], v[156:159], v[208:211], v[84:87]
	v_mfma_f32_16x16x32_bf16 v[76:79], v[148:151], v[216:219], v[76:79]
	v_mfma_f32_16x16x32_bf16 v[68:71], v[156:159], v[216:219], v[68:71]
	v_mfma_f32_16x16x32_bf16 v[124:127], v[152:155], v[184:187], v[124:127]
	v_mfma_f32_16x16x32_bf16 v[116:119], v[160:163], v[184:187], v[116:119]
	v_mfma_f32_16x16x32_bf16 v[108:111], v[152:155], v[204:207], v[108:111]
	v_mfma_f32_16x16x32_bf16 v[100:103], v[160:163], v[204:207], v[100:103]
	v_mfma_f32_16x16x32_bf16 v[92:95], v[152:155], v[212:215], v[92:95]
	v_mfma_f32_16x16x32_bf16 v[84:87], v[160:163], v[212:215], v[84:87]
	v_mfma_f32_16x16x32_bf16 v[76:79], v[152:155], v[226:229], v[76:79]
	v_mfma_f32_16x16x32_bf16 v[68:71], v[160:163], v[226:229], v[68:71]
	s_setprio 0
	s_setprio 1
	v_mfma_f32_16x16x32_bf16 v[120:123], v[164:167], v[180:183], v[120:123]
	v_mfma_f32_16x16x32_bf16 v[112:115], v[172:175], v[180:183], v[112:115]
	v_mfma_f32_16x16x32_bf16 v[104:107], v[164:167], v[200:203], v[104:107]
	v_mfma_f32_16x16x32_bf16 v[96:99], v[172:175], v[200:203], v[96:99]
	v_mfma_f32_16x16x32_bf16 v[88:91], v[164:167], v[208:211], v[88:91]
	v_mfma_f32_16x16x32_bf16 v[80:83], v[172:175], v[208:211], v[80:83]
	v_mfma_f32_16x16x32_bf16 v[72:75], v[164:167], v[216:219], v[72:75]
	v_mfma_f32_16x16x32_bf16 v[64:67], v[172:175], v[216:219], v[64:67]
	v_mfma_f32_16x16x32_bf16 v[120:123], v[168:171], v[184:187], v[120:123]
	v_mfma_f32_16x16x32_bf16 v[112:115], v[176:179], v[184:187], v[112:115]
	v_mfma_f32_16x16x32_bf16 v[104:107], v[168:171], v[204:207], v[104:107]
	v_mfma_f32_16x16x32_bf16 v[96:99], v[176:179], v[204:207], v[96:99]
	v_mfma_f32_16x16x32_bf16 v[88:91], v[168:171], v[212:215], v[88:91]
	v_mfma_f32_16x16x32_bf16 v[80:83], v[176:179], v[212:215], v[80:83]
	v_mfma_f32_16x16x32_bf16 v[72:75], v[168:171], v[226:229], v[72:75]
	v_mfma_f32_16x16x32_bf16 v[64:67], v[176:179], v[226:229], v[64:67]
	s_setprio 0
	s_barrier
; #define PG8_STAGE(bufoff, gbase, voff) do { _Pragma("unroll") for (int _i = 0; _i < 2; ++_i) \
;         __builtin_amdgcn_global_load_lds((const unsigned*)((const char*)(gbase) + (voff)[_i]), (PG8_LAS unsigned*)(lds + (bufoff) + ldsw + _i * 8192), 16, 0, 0); } while (0)
; #define PG8_LDA(dst, b, h) do { _Pragma("unroll") for (int m = 0; m < 4; ++m) _Pragma("unroll") for (int k = 0; k < 2; ++k) dst[m][k] = *(const PG8_LAS bf16x8*)(lds + PG8_SA(b, h) + aoff + m * 2048 + k * 1024); } while (0)
; #define PG8_MMA(ai, bj, At, Bt) do { __builtin_amdgcn_s_setprio(1); _Pragma("unroll") for (int m = 0; m < 4; ++m) _Pragma("unroll") for (int n = 0; n < 2; ++n) _Pragma("unroll") for (int k = 0; k < 2; ++k) \
;         acc[ai][bj][m][n] = __builtin_amdgcn_mfma_f32_16x16x32_bf16(Bt[n][k], At[m][k], acc[ai][bj][m][n], 0, 0, 0); __builtin_amdgcn_s_setprio(0); } while (0)
; #define PG8_WAIT_V(n) asm volatile("s_waitcnt vmcnt(" #n ")" ::: "memory")
; #define PG8_WAIT_L(n) asm volatile("s_waitcnt lgkmcnt(" #n ")" ::: "memory")
; #define PG8_BAR __builtin_amdgcn_s_barrier()
; #define PG8_SCHED __builtin_amdgcn_sched_barrier(0)
; template <class Epi, class Sched, bool ALIGN_EPI = false, bool SP2 = false>
; __device__ __forceinline__ void gemm_phase(PG8_LAS unsigned char* lds, const Gemm g, const Sched& S, const Epi& E, int tid_in) {
;     ...
;             PG8_LDA(At, 1, 1); PG8_STAGE(PG8_SB(1, 0), b3, voffB); PG8_STAGE(PG8_SB(1, 1), b3 + hstep, voffB); PG8_STAGE(PG8_SA(1, 0), a3, voffA);
;             PG8_WAIT_V(8); PG8_WAIT_L(0); PG8_BAR; PG8_MMA(1, 0, At, B0); PG8_MMA(1, 1, At, B1); PG8_BAR; PG8_SCHED;
	s_add_i32 s14, s58, s44
	v_lshl_add_u64 v[140:141], v[140:141], 0, s[0:1]
	s_mov_b32 m0, s14
	ds_read_b128 v[180:183], v146 offset:49152
	ds_read_b128 v[184:187], v146 offset:50176
	ds_read_b128 v[200:203], v146 offset:51200
	ds_read_b128 v[204:207], v146 offset:52224
	ds_read_b128 v[208:211], v146 offset:53248
	ds_read_b128 v[212:215], v146 offset:54272
	ds_read_b128 v[216:219], v146 offset:55296
	ds_read_b128 v[226:229], v146 offset:56320
	global_load_lds_dwordx4 v[140:141], off
	s_add_i32 m0, s14, 0x2000
	s_add_u32 s12, s12, 0x40080
	v_lshl_add_u64 v[140:141], v[188:189], 0, s[0:1]
	s_addc_u32 s13, s13, 0
	s_add_i32 s14, s59, s44
	global_load_lds_dwordx4 v[140:141], off
	s_mov_b32 m0, s14
	s_nop 0
	global_load_lds_dwordx4 v132, s[12:13]
	s_add_i32 m0, s14, 0x2000
	s_nop 0
	global_load_lds_dwordx4 v128, s[12:13]
	v_lshl_add_u64 v[140:141], v[230:231], 0, s[0:1]
	s_mov_b32 m0, s50
	s_nop 0
	global_load_lds_dwordx4 v[140:141], off
	v_lshl_add_u64 v[140:141], v[232:233], 0, s[0:1]
	s_mov_b32 m0, s51
	s_nop 0
	global_load_lds_dwordx4 v[140:141], off
	s_waitcnt vmcnt(8)
	s_waitcnt lgkmcnt(0)
	s_barrier
	s_setprio 1
	s_waitcnt lgkmcnt(0)
	v_mfma_f32_16x16x32_bf16 v[60:63], v[148:151], v[180:183], v[60:63]
	v_mfma_f32_16x16x32_bf16 v[52:55], v[156:159], v[180:183], v[52:55]
	v_mfma_f32_16x16x32_bf16 v[44:47], v[148:151], v[200:203], v[44:47]
	v_mfma_f32_16x16x32_bf16 v[36:39], v[156:159], v[200:203], v[36:39]
	v_mfma_f32_16x16x32_bf16 v[28:31], v[148:151], v[208:211], v[28:31]
	v_mfma_f32_16x16x32_bf16 v[20:23], v[156:159], v[208:211], v[20:23]
	v_mfma_f32_16x16x32_bf16 v[12:15], v[148:151], v[216:219], v[12:15]
	v_mfma_f32_16x16x32_bf16 v[4:7], v[156:159], v[216:219], v[4:7]
	v_mfma_f32_16x16x32_bf16 v[60:63], v[152:155], v[184:187], v[60:63]
	v_mfma_f32_16x16x32_bf16 v[52:55], v[160:163], v[184:187], v[52:55]
	v_mfma_f32_16x16x32_bf16 v[44:47], v[152:155], v[204:207], v[44:47]
	v_mfma_f32_16x16x32_bf16 v[36:39], v[160:163], v[204:207], v[36:39]
	v_mfma_f32_16x16x32_bf16 v[28:31], v[152:155], v[212:215], v[28:31]
	v_mfma_f32_16x16x32_bf16 v[20:23], v[160:163], v[212:215], v[20:23]
	v_mfma_f32_16x16x32_bf16 v[12:15], v[152:155], v[226:229], v[12:15]
	v_mfma_f32_16x16x32_bf16 v[4:7], v[160:163], v[226:229], v[4:7]
	s_setprio 0
	s_setprio 1
	v_mfma_f32_16x16x32_bf16 v[56:59], v[164:167], v[180:183], v[56:59]
	v_mfma_f32_16x16x32_bf16 v[48:51], v[172:175], v[180:183], v[48:51]
	v_mfma_f32_16x16x32_bf16 v[40:43], v[164:167], v[200:203], v[40:43]
	v_mfma_f32_16x16x32_bf16 v[32:35], v[172:175], v[200:203], v[32:35]
	v_mfma_f32_16x16x32_bf16 v[24:27], v[164:167], v[208:211], v[24:27]
	v_mfma_f32_16x16x32_bf16 v[16:19], v[172:175], v[208:211], v[16:19]
	v_mfma_f32_16x16x32_bf16 v[8:11], v[164:167], v[216:219], v[8:11]
	v_mfma_f32_16x16x32_bf16 v[0:3], v[172:175], v[216:219], v[0:3]
	v_mfma_f32_16x16x32_bf16 v[56:59], v[168:171], v[184:187], v[56:59]
	v_mfma_f32_16x16x32_bf16 v[48:51], v[176:179], v[184:187], v[48:51]
	v_mfma_f32_16x16x32_bf16 v[40:43], v[168:171], v[204:207], v[40:43]
	v_mfma_f32_16x16x32_bf16 v[32:35], v[176:179], v[204:207], v[32:35]
	v_mfma_f32_16x16x32_bf16 v[24:27], v[168:171], v[212:215], v[24:27]
	v_mfma_f32_16x16x32_bf16 v[16:19], v[176:179], v[212:215], v[16:19]
	v_mfma_f32_16x16x32_bf16 v[8:11], v[168:171], v[226:229], v[8:11]
	v_mfma_f32_16x16x32_bf16 v[0:3], v[176:179], v[226:229], v[0:3]
	s_setprio 0
	s_barrier
	s_add_i32 s57, s57, 2
	s_add_u32 s55, s55, 0x100
	s_addc_u32 s56, s56, 0
	s_add_u32 s2, s2, 0x100
	s_addc_u32 s3, s3, 0
	s_cmp_gt_u32 s57, 13
	s_cbranch_scc0 .LBB0_1385
	s_and_b64 vcc, exec, s[10:11]
	s_cbranch_vccz .LBB0_1388
	s_barrier

; #define PG8_STAGE(bufoff, gbase, voff) do { _Pragma("unroll") for (int _i = 0; _i < 2; ++_i) \
;         __builtin_amdgcn_global_load_lds((const unsigned*)((const char*)(gbase) + (voff)[_i]), (PG8_LAS unsigned*)(lds + (bufoff) + ldsw + _i * 8192), 16, 0, 0); } while (0)
; #define PG8_LDA(dst, b, h) do { _Pragma("unroll") for (int m = 0; m < 4; ++m) _Pragma("unroll") for (int k = 0; k < 2; ++k) dst[m][k] = *(const PG8_LAS bf16x8*)(lds + PG8_SA(b, h) + aoff + m * 2048 + k * 1024); } while (0)
; #define PG8_LDB(dst, b, h) do { _Pragma("unroll") for (int n = 0; n < 2; ++n) _Pragma("unroll") for (int k = 0; k < 2; ++k) dst[n][k] = *(const PG8_LAS bf16x8*)(lds + PG8_SB(b, h) + boff + n * 2048 + k * 1024); } while (0)
; #define PG8_MMA(ai, bj, At, Bt) do { __builtin_amdgcn_s_setprio(1); _Pragma("unroll") for (int m = 0; m < 4; ++m) _Pragma("unroll") for (int n = 0; n < 2; ++n) _Pragma("unroll") for (int k = 0; k < 2; ++k) \
;         acc[ai][bj][m][n] = __builtin_amdgcn_mfma_f32_16x16x32_bf16(Bt[n][k], At[m][k], acc[ai][bj][m][n], 0, 0, 0); __builtin_amdgcn_s_setprio(0); } while (0)
; #define PG8_WAIT_V(n) asm volatile("s_waitcnt vmcnt(" #n ")" ::: "memory")
; #define PG8_WAIT_L(n) asm volatile("s_waitcnt lgkmcnt(" #n ")" ::: "memory")
; template <class Epi, class Sched, bool ALIGN_EPI = false, bool SP2 = false>
; __device__ __forceinline__ void gemm_phase(PG8_LAS unsigned char* lds, const Gemm g, const Sched& S, const Epi& E, int tid_in) {
;     ...
;             const bool last = (t == nt - 2);
;             const char* a1 = cA + (size_t)(t + 1) * kstep;
;             const char* a2 = last ? nA : cA + (size_t)(t + 2) * kstep; const char* b2 = last ? nB : cB + (size_t)(t + 2) * kstep;
;             const char* a3 = a2 + kstep; const char* b3 = b2 + kstep;
;             if (last && has_next) S.a_ready(nxt);
;             if constexpr (SP2) {
;             PG8_LDB(B0, 0, 0); PG8_LDB(B1, 0, 1); PG8_SCHED; PG8_LDA(At, 0, 0); PG8_STAGE(PG8_SA(1, 1), a1 + hstepA, voffA);
;             PG8_WAIT_V(8); PG8_WAIT_L(0); PG8_BAR; PG8_MMA(0, 0, At, B0); PG8_MMA(0, 1, At, B1); PG8_BAR; PG8_SCHED;
;             PG8_LDA(At, 0, 1); PG8_STAGE(PG8_SB(0, 0), b2, voffB); PG8_STAGE(PG8_SB(0, 1), b2 + hstep, voffB); PG8_STAGE(PG8_SA(0, 0), a2, voffA);
;             PG8_WAIT_V(8); PG8_WAIT_L(0); PG8_BAR; PG8_MMA(1, 0, At, B0); PG8_MMA(1, 1, At, B1); PG8_BAR; PG8_SCHED;
.LBB0_1479:
	s_add_u32 s14, s12, 0x100
	s_addc_u32 s15, s13, 0
	s_add_i32 s56, 0, 0x10000
	s_cmp_eq_u32 s55, 40
	s_cselect_b32 s25, s11, s15
	s_cselect_b32 s24, s10, s14
	s_cselect_b32 s21, s19, s45
	s_cselect_b32 s20, s18, s44
	s_add_i32 s57, 0, 0x14000
	v_add_u32_e32 v124, s56, v226
	v_add_u32_e32 v140, s57, v226
	ds_read_b128 v[112:115], v124
	ds_read_b128 v[116:119], v124 offset:1024
	ds_read_b128 v[120:123], v124 offset:2048
	ds_read_b128 v[124:127], v124 offset:3072
	ds_read_b128 v[128:131], v140
	ds_read_b128 v[132:135], v140 offset:1024
	ds_read_b128 v[136:139], v140 offset:2048
	ds_read_b128 v[140:143], v140 offset:3072
	s_add_i32 m0, s31, 0xc000
	ds_read_b128 v[144:147], v227
	ds_read_b128 v[148:151], v227 offset:1024
	ds_read_b128 v[152:155], v227 offset:2048
	ds_read_b128 v[156:159], v227 offset:3072
	ds_read_b128 v[176:179], v227 offset:4096
	ds_read_b128 v[180:183], v227 offset:5120
	ds_read_b128 v[208:211], v227 offset:6144
	ds_read_b128 v[212:215], v227 offset:7168
	global_load_lds_dwordx4 v206, s[12:13]
	s_add_i32 m0, s31, 0xe000
	s_nop 0
	global_load_lds_dwordx4 v204, s[12:13]
	s_waitcnt vmcnt(8)
	s_waitcnt lgkmcnt(0)
	s_barrier
	s_setprio 1
	s_waitcnt lgkmcnt(0)
	v_mfma_f32_16x16x32_bf16 v[172:175], v[112:115], v[144:147], v[172:175]
	v_mfma_f32_16x16x32_bf16 v[168:171], v[120:123], v[144:147], v[168:171]
	v_mfma_f32_16x16x32_bf16 v[108:111], v[112:115], v[152:155], v[108:111]
	v_mfma_f32_16x16x32_bf16 v[104:107], v[120:123], v[152:155], v[104:107]
	v_mfma_f32_16x16x32_bf16 v[92:95], v[112:115], v[176:179], v[92:95]
	v_mfma_f32_16x16x32_bf16 v[88:91], v[120:123], v[176:179], v[88:91]
	v_mfma_f32_16x16x32_bf16 v[76:79], v[112:115], v[208:211], v[76:79]
	v_mfma_f32_16x16x32_bf16 v[72:75], v[120:123], v[208:211], v[72:75]
	v_mfma_f32_16x16x32_bf16 v[172:175], v[116:119], v[148:151], v[172:175]
	v_mfma_f32_16x16x32_bf16 v[168:171], v[124:127], v[148:151], v[168:171]
	v_mfma_f32_16x16x32_bf16 v[108:111], v[116:119], v[156:159], v[108:111]
	v_mfma_f32_16x16x32_bf16 v[104:107], v[124:127], v[156:159], v[104:107]
	v_mfma_f32_16x16x32_bf16 v[92:95], v[116:119], v[180:183], v[92:95]
	v_mfma_f32_16x16x32_bf16 v[88:91], v[124:127], v[180:183], v[88:91]
	v_mfma_f32_16x16x32_bf16 v[76:79], v[116:119], v[212:215], v[76:79]
	v_mfma_f32_16x16x32_bf16 v[72:75], v[124:127], v[212:215], v[72:75]
	s_setprio 0
	s_setprio 1
	v_mfma_f32_16x16x32_bf16 v[164:167], v[128:131], v[144:147], v[164:167]
	v_mfma_f32_16x16x32_bf16 v[100:103], v[128:131], v[152:155], v[100:103]
	v_mfma_f32_16x16x32_bf16 v[96:99], v[136:139], v[152:155], v[96:99]
	v_mfma_f32_16x16x32_bf16 v[84:87], v[128:131], v[176:179], v[84:87]
	v_mfma_f32_16x16x32_bf16 v[80:83], v[136:139], v[176:179], v[80:83]
	v_mfma_f32_16x16x32_bf16 v[68:71], v[128:131], v[208:211], v[68:71]
	v_mfma_f32_16x16x32_bf16 v[64:67], v[136:139], v[208:211], v[64:67]
	v_mfma_f32_16x16x32_bf16 v[164:167], v[132:135], v[148:151], v[164:167]
	v_mfma_f32_16x16x32_bf16 v[144:147], v[136:139], v[144:147], v[160:163]
	v_mfma_f32_16x16x32_bf16 v[100:103], v[132:135], v[156:159], v[100:103]
	v_mfma_f32_16x16x32_bf16 v[96:99], v[140:143], v[156:159], v[96:99]
	v_mfma_f32_16x16x32_bf16 v[84:87], v[132:135], v[180:183], v[84:87]
	v_mfma_f32_16x16x32_bf16 v[80:83], v[140:143], v[180:183], v[80:83]
	v_mfma_f32_16x16x32_bf16 v[68:71], v[132:135], v[212:215], v[68:71]
	v_mfma_f32_16x16x32_bf16 v[64:67], v[140:143], v[212:215], v[64:67]
	v_mfma_f32_16x16x32_bf16 v[144:147], v[140:143], v[148:151], v[144:147]
	s_setprio 0
	s_barrier
	s_add_i32 s12, s56, s30
	v_lshl_add_u64 v[228:229], s[20:21], 0, v[190:191]
	s_mov_b32 m0, s12
	ds_read_b128 v[148:151], v227 offset:16384
	ds_read_b128 v[152:155], v227 offset:17408
	ds_read_b128 v[156:159], v227 offset:18432
	ds_read_b128 v[160:163], v227 offset:19456
	ds_read_b128 v[176:179], v227 offset:20480
	ds_read_b128 v[180:183], v227 offset:21504
	ds_read_b128 v[208:211], v227 offset:22528
	ds_read_b128 v[212:215], v227 offset:23552
	global_load_lds_dwordx4 v[228:229], off
	s_add_i32 m0, s12, 0x2000
	s_add_u32 s12, s20, 0xb0000
	v_lshl_add_u64 v[230:231], s[20:21], 0, v[184:185]
	s_addc_u32 s13, s21, 0
	s_add_i32 s56, s57, s30
	global_load_lds_dwordx4 v[230:231], off
	s_mov_b32 m0, s56
	v_lshl_add_u64 v[232:233], s[24:25], 0, v[188:189]
	global_load_lds_dwordx4 v190, s[12:13]
	s_add_i32 m0, s56, 0x2000
	v_lshl_add_u64 v[234:235], s[24:25], 0, v[186:187]
	global_load_lds_dwordx4 v184, s[12:13]
	s_mov_b32 m0, s31
	s_nop 0
	global_load_lds_dwordx4 v[232:233], off
	s_mov_b32 m0, s34
	s_nop 0
	global_load_lds_dwordx4 v[234:235], off
	s_waitcnt vmcnt(8)
	s_waitcnt lgkmcnt(0)
	s_barrier
; #define PG8_STAGE(bufoff, gbase, voff) do { _Pragma("unroll") for (int _i = 0; _i < 2; ++_i) \
;         __builtin_amdgcn_global_load_lds((const unsigned*)((const char*)(gbase) + (voff)[_i]), (PG8_LAS unsigned*)(lds + (bufoff) + ldsw + _i * 8192), 16, 0, 0); } while (0)
; #define PG8_LDA(dst, b, h) do { _Pragma("unroll") for (int m = 0; m < 4; ++m) _Pragma("unroll") for (int k = 0; k < 2; ++k) dst[m][k] = *(const PG8_LAS bf16x8*)(lds + PG8_SA(b, h) + aoff + m * 2048 + k * 1024); } while (0)
; #define PG8_LDB(dst, b, h) do { _Pragma("unroll") for (int n = 0; n < 2; ++n) _Pragma("unroll") for (int k = 0; k < 2; ++k) dst[n][k] = *(const PG8_LAS bf16x8*)(lds + PG8_SB(b, h) + boff + n * 2048 + k * 1024); } while (0)
; #define PG8_MMA(ai, bj, At, Bt) do { __builtin_amdgcn_s_setprio(1); _Pragma("unroll") for (int m = 0; m < 4; ++m) _Pragma("unroll") for (int n = 0; n < 2; ++n) _Pragma("unroll") for (int k = 0; k < 2; ++k) \
;         acc[ai][bj][m][n] = __builtin_amdgcn_mfma_f32_16x16x32_bf16(Bt[n][k], At[m][k], acc[ai][bj][m][n], 0, 0, 0); __builtin_amdgcn_s_setprio(0); } while (0)
; #define PG8_WAIT_V(n) asm volatile("s_waitcnt vmcnt(" #n ")" ::: "memory")
; #define PG8_WAIT_L(n) asm volatile("s_waitcnt lgkmcnt(" #n ")" ::: "memory")
; #define PG8_BAR __builtin_amdgcn_s_barrier()
; #define PG8_SCHED __builtin_amdgcn_sched_barrier(0)
; template <class Epi, class Sched, bool ALIGN_EPI = false, bool SP2 = false>
; __device__ __forceinline__ void gemm_phase(PG8_LAS unsigned char* lds, const Gemm g, const Sched& S, const Epi& E, int tid_in) {
;     ...
;             PG8_WAIT_V(8); PG8_WAIT_L(0); PG8_BAR; PG8_MMA(1, 0, At, B0); PG8_MMA(1, 1, At, B1); PG8_BAR; PG8_SCHED;
;             PG8_LDB(B0, 1, 0); PG8_LDB(B1, 1, 1); PG8_SCHED; PG8_LDA(At, 1, 0); PG8_STAGE(PG8_SA(0, 1), a2 + hstepA, voffA);
;             PG8_WAIT_V(8); PG8_WAIT_L(0); PG8_BAR; PG8_MMA(0, 0, At, B0); PG8_MMA(0, 1, At, B1); PG8_BAR; PG8_SCHED;
	s_setprio 1
	s_waitcnt lgkmcnt(0)
	v_mfma_f32_16x16x32_bf16 v[60:63], v[112:115], v[148:151], v[60:63]
	v_mfma_f32_16x16x32_bf16 v[56:59], v[120:123], v[148:151], v[56:59]
	v_mfma_f32_16x16x32_bf16 v[44:47], v[112:115], v[156:159], v[44:47]
	v_mfma_f32_16x16x32_bf16 v[40:43], v[120:123], v[156:159], v[40:43]
	v_mfma_f32_16x16x32_bf16 v[28:31], v[112:115], v[176:179], v[28:31]
	v_mfma_f32_16x16x32_bf16 v[24:27], v[120:123], v[176:179], v[24:27]
	v_mfma_f32_16x16x32_bf16 v[12:15], v[112:115], v[208:211], v[12:15]
	v_mfma_f32_16x16x32_bf16 v[8:11], v[120:123], v[208:211], v[8:11]
	v_mfma_f32_16x16x32_bf16 v[60:63], v[116:119], v[152:155], v[60:63]
	v_mfma_f32_16x16x32_bf16 v[56:59], v[124:127], v[152:155], v[56:59]
	v_mfma_f32_16x16x32_bf16 v[44:47], v[116:119], v[160:163], v[44:47]
	v_mfma_f32_16x16x32_bf16 v[40:43], v[124:127], v[160:163], v[40:43]
	v_mfma_f32_16x16x32_bf16 v[28:31], v[116:119], v[180:183], v[28:31]
	v_mfma_f32_16x16x32_bf16 v[24:27], v[124:127], v[180:183], v[24:27]
	v_mfma_f32_16x16x32_bf16 v[12:15], v[116:119], v[212:215], v[12:15]
	v_mfma_f32_16x16x32_bf16 v[8:11], v[124:127], v[212:215], v[8:11]
	s_setprio 0
	s_setprio 1
	v_mfma_f32_16x16x32_bf16 v[52:55], v[128:131], v[148:151], v[52:55]
	v_mfma_f32_16x16x32_bf16 v[48:51], v[136:139], v[148:151], v[48:51]
	v_mfma_f32_16x16x32_bf16 v[36:39], v[128:131], v[156:159], v[36:39]
	v_mfma_f32_16x16x32_bf16 v[32:35], v[136:139], v[156:159], v[32:35]
	v_mfma_f32_16x16x32_bf16 v[20:23], v[128:131], v[176:179], v[20:23]
	v_mfma_f32_16x16x32_bf16 v[16:19], v[136:139], v[176:179], v[16:19]
	v_mfma_f32_16x16x32_bf16 v[4:7], v[128:131], v[208:211], v[4:7]
	v_mfma_f32_16x16x32_bf16 v[0:3], v[136:139], v[208:211], v[0:3]
	v_mfma_f32_16x16x32_bf16 v[52:55], v[132:135], v[152:155], v[52:55]
	v_mfma_f32_16x16x32_bf16 v[48:51], v[140:143], v[152:155], v[48:51]
	v_mfma_f32_16x16x32_bf16 v[36:39], v[132:135], v[160:163], v[36:39]
	v_mfma_f32_16x16x32_bf16 v[32:35], v[140:143], v[160:163], v[32:35]
	v_mfma_f32_16x16x32_bf16 v[20:23], v[132:135], v[180:183], v[20:23]
	v_mfma_f32_16x16x32_bf16 v[16:19], v[140:143], v[180:183], v[16:19]
	v_mfma_f32_16x16x32_bf16 v[4:7], v[132:135], v[212:215], v[4:7]
	v_mfma_f32_16x16x32_bf16 v[0:3], v[140:143], v[212:215], v[0:3]
	s_setprio 0
	s_barrier
	s_add_i32 s56, 0, 0x18000
	s_add_i32 s57, 0, 0x1c000
	v_add_u32_e32 v124, s56, v226
	v_add_u32_e32 v140, s57, v226
	ds_read_b128 v[112:115], v124
	ds_read_b128 v[116:119], v124 offset:1024
	ds_read_b128 v[120:123], v124 offset:2048
	ds_read_b128 v[124:127], v124 offset:3072
	ds_read_b128 v[128:131], v140
	ds_read_b128 v[132:135], v140 offset:1024
	ds_read_b128 v[136:139], v140 offset:2048
	ds_read_b128 v[140:143], v140 offset:3072
	s_add_u32 s12, s24, 0xb0000
	s_addc_u32 s13, s25, 0
	s_mov_b32 m0, s35
	ds_read_b128 v[148:151], v227 offset:32768
	ds_read_b128 v[152:155], v227 offset:33792
	ds_read_b128 v[156:159], v227 offset:34816
	ds_read_b128 v[176:179], v227 offset:35840
	ds_read_b128 v[180:183], v227 offset:36864
	ds_read_b128 v[208:211], v227 offset:37888
	ds_read_b128 v[212:215], v227 offset:38912
	ds_read_b128 v[216:219], v227 offset:39936
	global_load_lds_dwordx4 v188, s[12:13]
	s_mov_b32 m0, s46
	s_nop 0
	global_load_lds_dwordx4 v186, s[12:13]
	s_waitcnt vmcnt(8)
	s_waitcnt lgkmcnt(0)
	s_barrier
	s_setprio 1
	s_waitcnt lgkmcnt(0)
	v_mfma_f32_16x16x32_bf16 v[160:163], v[112:115], v[148:151], v[172:175]
	v_mfma_f32_16x16x32_bf16 v[172:175], v[116:119], v[152:155], v[160:163]
	v_mfma_f32_16x16x32_bf16 v[160:163], v[120:123], v[148:151], v[168:171]
	v_mfma_f32_16x16x32_bf16 v[108:111], v[112:115], v[156:159], v[108:111]
	v_mfma_f32_16x16x32_bf16 v[104:107], v[120:123], v[156:159], v[104:107]
	v_mfma_f32_16x16x32_bf16 v[92:95], v[112:115], v[180:183], v[92:95]
	v_mfma_f32_16x16x32_bf16 v[88:91], v[120:123], v[180:183], v[88:91]
	v_mfma_f32_16x16x32_bf16 v[76:79], v[112:115], v[212:215], v[76:79]
	v_mfma_f32_16x16x32_bf16 v[72:75], v[120:123], v[212:215], v[72:75]
	v_mfma_f32_16x16x32_bf16 v[168:171], v[124:127], v[152:155], v[160:163]
	v_mfma_f32_16x16x32_bf16 v[108:111], v[116:119], v[176:179], v[108:111]
	v_mfma_f32_16x16x32_bf16 v[104:107], v[124:127], v[176:179], v[104:107]
	v_mfma_f32_16x16x32_bf16 v[92:95], v[116:119], v[208:211], v[92:95]
	v_mfma_f32_16x16x32_bf16 v[88:91], v[124:127], v[208:211], v[88:91]
	v_mfma_f32_16x16x32_bf16 v[76:79], v[116:119], v[216:219], v[76:79]
	v_mfma_f32_16x16x32_bf16 v[72:75], v[124:127], v[216:219], v[72:75]
	s_setprio 0
	s_setprio 1
	v_mfma_f32_16x16x32_bf16 v[160:163], v[128:131], v[148:151], v[164:167]
	v_mfma_f32_16x16x32_bf16 v[144:147], v[136:139], v[148:151], v[144:147]
	v_mfma_f32_16x16x32_bf16 v[100:103], v[128:131], v[156:159], v[100:103]
	v_mfma_f32_16x16x32_bf16 v[96:99], v[136:139], v[156:159], v[96:99]
	v_mfma_f32_16x16x32_bf16 v[84:87], v[128:131], v[180:183], v[84:87]
	v_mfma_f32_16x16x32_bf16 v[80:83], v[136:139], v[180:183], v[80:83]
	v_mfma_f32_16x16x32_bf16 v[68:71], v[128:131], v[212:215], v[68:71]
	v_mfma_f32_16x16x32_bf16 v[64:67], v[136:139], v[212:215], v[64:67]
	v_mfma_f32_16x16x32_bf16 v[164:167], v[132:135], v[152:155], v[160:163]
	v_mfma_f32_16x16x32_bf16 v[160:163], v[140:143], v[152:155], v[144:147]
	v_mfma_f32_16x16x32_bf16 v[100:103], v[132:135], v[176:179], v[100:103]
	v_mfma_f32_16x16x32_bf16 v[96:99], v[140:143], v[176:179], v[96:99]
	v_mfma_f32_16x16x32_bf16 v[84:87], v[132:135], v[208:211], v[84:87]
	v_mfma_f32_16x16x32_bf16 v[80:83], v[140:143], v[208:211], v[80:83]
	v_mfma_f32_16x16x32_bf16 v[68:71], v[132:135], v[216:219], v[68:71]
	v_mfma_f32_16x16x32_bf16 v[64:67], v[140:143], v[216:219], v[64:67]
	s_setprio 0
	s_barrier
; #define PG8_STAGE(bufoff, gbase, voff) do { _Pragma("unroll") for (int _i = 0; _i < 2; ++_i) \
;         __builtin_amdgcn_global_load_lds((const unsigned*)((const char*)(gbase) + (voff)[_i]), (PG8_LAS unsigned*)(lds + (bufoff) + ldsw + _i * 8192), 16, 0, 0); } while (0)
; #define PG8_LDA(dst, b, h) do { _Pragma("unroll") for (int m = 0; m < 4; ++m) _Pragma("unroll") for (int k = 0; k < 2; ++k) dst[m][k] = *(const PG8_LAS bf16x8*)(lds + PG8_SA(b, h) + aoff + m * 2048 + k * 1024); } while (0)
; #define PG8_MMA(ai, bj, At, Bt) do { __builtin_amdgcn_s_setprio(1); _Pragma("unroll") for (int m = 0; m < 4; ++m) _Pragma("unroll") for (int n = 0; n < 2; ++n) _Pragma("unroll") for (int k = 0; k < 2; ++k) \
;         acc[ai][bj][m][n] = __builtin_amdgcn_mfma_f32_16x16x32_bf16(Bt[n][k], At[m][k], acc[ai][bj][m][n], 0, 0, 0); __builtin_amdgcn_s_setprio(0); } while (0)
; #define PG8_WAIT_V(n) asm volatile("s_waitcnt vmcnt(" #n ")" ::: "memory")
; #define PG8_WAIT_L(n) asm volatile("s_waitcnt lgkmcnt(" #n ")" ::: "memory")
; #define PG8_BAR __builtin_amdgcn_s_barrier()
; #define PG8_SCHED __builtin_amdgcn_sched_barrier(0)
; template <class Epi, class Sched, bool ALIGN_EPI = false, bool SP2 = false>
; __device__ __forceinline__ void gemm_phase(PG8_LAS unsigned char* lds, const Gemm g, const Sched& S, const Epi& E, int tid_in) {
;     ...
;             PG8_LDA(At, 1, 1); PG8_STAGE(PG8_SB(1, 0), b3, voffB); PG8_STAGE(PG8_SB(1, 1), b3 + hstep, voffB); PG8_STAGE(PG8_SA(1, 0), a3, voffA);
;             PG8_WAIT_V(8); PG8_WAIT_L(0); PG8_BAR; PG8_MMA(1, 0, At, B0); PG8_MMA(1, 1, At, B1); PG8_BAR; PG8_SCHED;
	s_add_i32 s12, s56, s30
	v_lshl_add_u64 v[216:217], v[228:229], 0, s[0:1]
	s_mov_b32 m0, s12
	ds_read_b128 v[144:147], v227 offset:49152
	ds_read_b128 v[148:151], v227 offset:50176
	ds_read_b128 v[152:155], v227 offset:51200
	ds_read_b128 v[156:159], v227 offset:52224
	ds_read_b128 v[176:179], v227 offset:53248
	ds_read_b128 v[180:183], v227 offset:54272
	ds_read_b128 v[208:211], v227 offset:55296
	ds_read_b128 v[212:215], v227 offset:56320
	global_load_lds_dwordx4 v[216:217], off
	s_add_i32 m0, s12, 0x2000
	s_add_u32 s12, s20, 0xb0080
	v_lshl_add_u64 v[216:217], v[230:231], 0, s[0:1]
	s_addc_u32 s13, s21, 0
	s_add_i32 s20, s57, s30
	global_load_lds_dwordx4 v[216:217], off
	s_mov_b32 m0, s20
	s_nop 0
	global_load_lds_dwordx4 v190, s[12:13]
	s_add_i32 m0, s20, 0x2000
	s_nop 0
	global_load_lds_dwordx4 v184, s[12:13]
	v_lshl_add_u64 v[216:217], v[232:233], 0, s[0:1]
	s_mov_b32 m0, s49
	s_nop 0
	global_load_lds_dwordx4 v[216:217], off
	v_lshl_add_u64 v[216:217], v[234:235], 0, s[0:1]
	s_mov_b32 m0, s50
	s_nop 0
	global_load_lds_dwordx4 v[216:217], off
	s_waitcnt vmcnt(8)
	s_waitcnt lgkmcnt(0)
	s_barrier
	s_setprio 1
	s_waitcnt lgkmcnt(0)
	v_mfma_f32_16x16x32_bf16 v[60:63], v[112:115], v[144:147], v[60:63]
	v_mfma_f32_16x16x32_bf16 v[56:59], v[120:123], v[144:147], v[56:59]
	v_mfma_f32_16x16x32_bf16 v[44:47], v[112:115], v[152:155], v[44:47]
	v_mfma_f32_16x16x32_bf16 v[40:43], v[120:123], v[152:155], v[40:43]
	v_mfma_f32_16x16x32_bf16 v[28:31], v[112:115], v[176:179], v[28:31]
	v_mfma_f32_16x16x32_bf16 v[24:27], v[120:123], v[176:179], v[24:27]
	v_mfma_f32_16x16x32_bf16 v[12:15], v[112:115], v[208:211], v[12:15]
	v_mfma_f32_16x16x32_bf16 v[8:11], v[120:123], v[208:211], v[8:11]
	v_mfma_f32_16x16x32_bf16 v[60:63], v[116:119], v[148:151], v[60:63]
	v_mfma_f32_16x16x32_bf16 v[56:59], v[124:127], v[148:151], v[56:59]
	v_mfma_f32_16x16x32_bf16 v[44:47], v[116:119], v[156:159], v[44:47]
	v_mfma_f32_16x16x32_bf16 v[40:43], v[124:127], v[156:159], v[40:43]
	v_mfma_f32_16x16x32_bf16 v[28:31], v[116:119], v[180:183], v[28:31]
	v_mfma_f32_16x16x32_bf16 v[24:27], v[124:127], v[180:183], v[24:27]
	v_mfma_f32_16x16x32_bf16 v[12:15], v[116:119], v[212:215], v[12:15]
	v_mfma_f32_16x16x32_bf16 v[8:11], v[124:127], v[212:215], v[8:11]
	s_setprio 0
	s_setprio 1
	v_mfma_f32_16x16x32_bf16 v[52:55], v[128:131], v[144:147], v[52:55]
	v_mfma_f32_16x16x32_bf16 v[48:51], v[136:139], v[144:147], v[48:51]
	v_mfma_f32_16x16x32_bf16 v[36:39], v[128:131], v[152:155], v[36:39]
	v_mfma_f32_16x16x32_bf16 v[32:35], v[136:139], v[152:155], v[32:35]
	v_mfma_f32_16x16x32_bf16 v[20:23], v[128:131], v[176:179], v[20:23]
	v_mfma_f32_16x16x32_bf16 v[16:19], v[136:139], v[176:179], v[16:19]
	v_mfma_f32_16x16x32_bf16 v[4:7], v[128:131], v[208:211], v[4:7]
	v_mfma_f32_16x16x32_bf16 v[0:3], v[136:139], v[208:211], v[0:3]
	v_mfma_f32_16x16x32_bf16 v[52:55], v[132:135], v[148:151], v[52:55]
	v_mfma_f32_16x16x32_bf16 v[48:51], v[140:143], v[148:151], v[48:51]
	v_mfma_f32_16x16x32_bf16 v[36:39], v[132:135], v[156:159], v[36:39]
	v_mfma_f32_16x16x32_bf16 v[32:35], v[140:143], v[156:159], v[32:35]
	v_mfma_f32_16x16x32_bf16 v[20:23], v[132:135], v[180:183], v[20:23]
	v_mfma_f32_16x16x32_bf16 v[16:19], v[140:143], v[180:183], v[16:19]
	v_mfma_f32_16x16x32_bf16 v[4:7], v[132:135], v[212:215], v[4:7]
	v_mfma_f32_16x16x32_bf16 v[0:3], v[140:143], v[212:215], v[0:3]
	s_setprio 0
	s_barrier
	s_add_i32 s55, s55, 2
	s_add_u32 s44, s44, 0x100
	s_addc_u32 s45, s45, 0
	s_cmp_gt_u32 s55, 41
	s_mov_b64 s[12:13], s[14:15]
	s_cbranch_scc0 .LBB0_1479
	s_and_b64 vcc, exec, s[8:9]
	s_cbranch_vccz .LBB0_1482
	s_barrier
